# K-loops: removed the redundant post-barrier lgkmcnt(0) and the back-to-back setprio 0/1 flip in the middle of each 32-MFMA segment (on top of saddr DMA, LDS immediate offsets, C=0 peel)
# speedup vs baseline: 1.0181x; 1.0003x over previous
; #define PG8_STAGE(bufoff, gbase, voff) do { _Pragma("unroll") for (int _i = 0; _i < 2; ++_i) \
;         __builtin_amdgcn_global_load_lds((const unsigned*)((const char*)(gbase) + (voff)[_i]), (PG8_LAS unsigned*)(lds + (bufoff) + ldsw + _i * 8192), 16, 0, 0); } while (0)
; #define PG8_LDA(dst, b, h) do { _Pragma("unroll") for (int m = 0; m < 4; ++m) _Pragma("unroll") for (int k = 0; k < 2; ++k) dst[m][k] = *(const PG8_LAS bf16x8*)(lds + PG8_SA(b, h) + aoff + m * 2048 + k * 1024); } while (0)
; #define PG8_LDB(dst, b, h) do { _Pragma("unroll") for (int n = 0; n < 2; ++n) _Pragma("unroll") for (int k = 0; k < 2; ++k) dst[n][k] = *(const PG8_LAS bf16x8*)(lds + PG8_SB(b, h) + boff + n * 2048 + k * 1024); } while (0)
; #define PG8_MMA(ai, bj, At, Bt) do { __builtin_amdgcn_s_setprio(1); _Pragma("unroll") for (int m = 0; m < 4; ++m) _Pragma("unroll") for (int n = 0; n < 2; ++n) _Pragma("unroll") for (int k = 0; k < 2; ++k) \
;         acc[ai][bj][m][n] = __builtin_amdgcn_mfma_f32_16x16x32_bf16(Bt[n][k], At[m][k], acc[ai][bj][m][n], 0, 0, 0); __builtin_amdgcn_s_setprio(0); } while (0)
; #define PG8_WAIT_V(n) asm volatile("s_waitcnt vmcnt(" #n ")" ::: "memory")
; #define PG8_WAIT_L(n) asm volatile("s_waitcnt lgkmcnt(" #n ")" ::: "memory")
; #define PG8_BAR __builtin_amdgcn_s_barrier()
; #define PG8_SCHED __builtin_amdgcn_sched_barrier(0)
; template <class Epi, class Sched, bool ALIGN_EPI = false, bool SP2 = false>
; __device__ __forceinline__ void gemm_phase(PG8_LAS unsigned char* lds, const Gemm g, const Sched& S, const Epi& E) {
;     ...
;             PG8_LDB(B0, 0, 0); PG8_LDB(B1, 0, 1); PG8_SCHED; PG8_LDA(At, 0, 0); PG8_STAGE(PG8_SA(1, 1), a1 + hstep, voffA);
;             PG8_WAIT_V(8); PG8_WAIT_L(0); PG8_BAR; PG8_MMA(0, 0, At, B0); PG8_MMA(0, 1, At, B1); PG8_BAR; PG8_SCHED;
;             PG8_LDA(At, 0, 1); PG8_STAGE(PG8_SB(0, 0), b2, voffB); PG8_STAGE(PG8_SB(0, 1), b2 + hstep, voffB); PG8_STAGE(PG8_SA(0, 0), a2, voffA);
;             PG8_WAIT_V(8); PG8_WAIT_L(0); PG8_BAR; PG8_MMA(1, 0, At, B0); PG8_MMA(1, 1, At, B1); PG8_BAR; PG8_SCHED;
.Labo_peel:
	ds_read_b128 v[68:71], v254
	ds_read_b128 v[72:75], v254 offset:1024
	ds_read_b128 v[76:79], v254 offset:2048
	ds_read_b128 v[80:83], v254 offset:3072
	ds_read_b128 v[174:177], v254 offset:16384
	ds_read_b128 v[182:185], v254 offset:17408
	ds_read_b128 v[186:189], v254 offset:18432
	ds_read_b128 v[210:213], v254 offset:19456
	s_add_u32 s2, s0, 0xfffc0080
	s_addc_u32 s3, s1, -1
	s_cmp_eq_u32 s56, 12
	s_cselect_b32 s5, s27, s3
	s_cselect_b32 s4, s52, s2
	s_cselect_b32 s3, s25, s55
	s_cselect_b32 s2, s53, s54
	s_add_i32 m0, s29, 0xc000
	ds_read_b128 v[214:217], v179
	ds_read_b128 v[218:221], v179 offset:1024
	ds_read_b128 v[222:225], v179 offset:2048
	ds_read_b128 v[226:229], v179 offset:3072
	ds_read_b128 v[230:233], v179 offset:4096
	ds_read_b128 v[234:237], v179 offset:5120
	ds_read_b128 v[238:241], v179 offset:6144
	ds_read_b128 v[242:245], v179 offset:7168
	global_load_lds_dwordx4 v170, s[0:1]
	s_add_i32 m0, s29, 0xe000
	s_nop 0
	global_load_lds_dwordx4 v172, s[0:1]
	s_waitcnt vmcnt(8)
	s_waitcnt lgkmcnt(0)
	s_barrier
	s_setprio 1
	v_mfma_f32_16x16x32_bf16 v[140:143], v[68:71], v[214:217], 0
	v_mfma_f32_16x16x32_bf16 v[136:139], v[76:79], v[214:217], 0
	v_mfma_f32_16x16x32_bf16 v[124:127], v[68:71], v[222:225], 0
	v_mfma_f32_16x16x32_bf16 v[120:123], v[76:79], v[222:225], 0
	v_mfma_f32_16x16x32_bf16 v[108:111], v[68:71], v[230:233], 0
	v_mfma_f32_16x16x32_bf16 v[104:107], v[76:79], v[230:233], 0
	v_mfma_f32_16x16x32_bf16 v[92:95], v[68:71], v[238:241], 0
	v_mfma_f32_16x16x32_bf16 v[88:91], v[76:79], v[238:241], 0
	v_mfma_f32_16x16x32_bf16 v[140:143], v[72:75], v[218:221], v[140:143]
	v_mfma_f32_16x16x32_bf16 v[136:139], v[80:83], v[218:221], v[136:139]
	v_mfma_f32_16x16x32_bf16 v[124:127], v[72:75], v[226:229], v[124:127]
	v_mfma_f32_16x16x32_bf16 v[120:123], v[80:83], v[226:229], v[120:123]
	v_mfma_f32_16x16x32_bf16 v[108:111], v[72:75], v[234:237], v[108:111]
	v_mfma_f32_16x16x32_bf16 v[104:107], v[80:83], v[234:237], v[104:107]
	v_mfma_f32_16x16x32_bf16 v[92:95], v[72:75], v[242:245], v[92:95]
	v_mfma_f32_16x16x32_bf16 v[88:91], v[80:83], v[242:245], v[88:91]
	v_mfma_f32_16x16x32_bf16 v[132:135], v[174:177], v[214:217], 0
	v_mfma_f32_16x16x32_bf16 v[128:131], v[186:189], v[214:217], 0
	v_mfma_f32_16x16x32_bf16 v[116:119], v[174:177], v[222:225], 0
	v_mfma_f32_16x16x32_bf16 v[112:115], v[186:189], v[222:225], 0
	v_mfma_f32_16x16x32_bf16 v[100:103], v[174:177], v[230:233], 0
	v_mfma_f32_16x16x32_bf16 v[96:99], v[186:189], v[230:233], 0
	v_mfma_f32_16x16x32_bf16 v[84:87], v[174:177], v[238:241], 0
	v_mfma_f32_16x16x32_bf16 v[64:67], v[186:189], v[238:241], 0
	v_mfma_f32_16x16x32_bf16 v[132:135], v[182:185], v[218:221], v[132:135]
	v_mfma_f32_16x16x32_bf16 v[128:131], v[210:213], v[218:221], v[128:131]
	v_mfma_f32_16x16x32_bf16 v[116:119], v[182:185], v[226:229], v[116:119]
	v_mfma_f32_16x16x32_bf16 v[112:115], v[210:213], v[226:229], v[112:115]
	v_mfma_f32_16x16x32_bf16 v[100:103], v[182:185], v[234:237], v[100:103]
	v_mfma_f32_16x16x32_bf16 v[96:99], v[210:213], v[234:237], v[96:99]
	v_mfma_f32_16x16x32_bf16 v[84:87], v[182:185], v[242:245], v[84:87]
	v_mfma_f32_16x16x32_bf16 v[64:67], v[210:213], v[242:245], v[64:67]
	s_setprio 0
	s_barrier
	s_mov_b32 m0, s30
	s_add_u32 s58, s2, 0x40000
	s_addc_u32 s59, s3, 0
	ds_read_b128 v[214:217], v179 offset:16384
	ds_read_b128 v[218:221], v179 offset:17408
	ds_read_b128 v[222:225], v179 offset:18432
	ds_read_b128 v[226:229], v179 offset:19456
	ds_read_b128 v[230:233], v179 offset:20480
	ds_read_b128 v[234:237], v179 offset:21504
	ds_read_b128 v[238:241], v179 offset:22528
	ds_read_b128 v[242:245], v179 offset:23552
	global_load_lds_dwordx4 v166, s[2:3]
	s_mov_b32 m0, s31
	s_nop 0
	global_load_lds_dwordx4 v162, s[2:3]
	s_mov_b32 m0, s33
	s_nop 0
	global_load_lds_dwordx4 v166, s[58:59]
	s_mov_b32 m0, s34
	s_nop 0
	global_load_lds_dwordx4 v162, s[58:59]
	s_mov_b32 m0, s29
	s_nop 0
	global_load_lds_dwordx4 v168, s[4:5]
	s_mov_b32 m0, s35
	s_nop 0
	global_load_lds_dwordx4 v164, s[4:5]
	s_waitcnt vmcnt(8)
	s_waitcnt lgkmcnt(0)
	s_barrier
	s_setprio 1
	v_mfma_f32_16x16x32_bf16 v[60:63], v[68:71], v[214:217], 0
	v_mfma_f32_16x16x32_bf16 v[56:59], v[76:79], v[214:217], 0
	v_mfma_f32_16x16x32_bf16 v[44:47], v[68:71], v[222:225], 0
	v_mfma_f32_16x16x32_bf16 v[40:43], v[76:79], v[222:225], 0
	v_mfma_f32_16x16x32_bf16 v[28:31], v[68:71], v[230:233], 0
	v_mfma_f32_16x16x32_bf16 v[24:27], v[76:79], v[230:233], 0
	v_mfma_f32_16x16x32_bf16 v[12:15], v[68:71], v[238:241], 0
	v_mfma_f32_16x16x32_bf16 v[8:11], v[76:79], v[238:241], 0
	v_mfma_f32_16x16x32_bf16 v[60:63], v[72:75], v[218:221], v[60:63]
	v_mfma_f32_16x16x32_bf16 v[56:59], v[80:83], v[218:221], v[56:59]
	v_mfma_f32_16x16x32_bf16 v[44:47], v[72:75], v[226:229], v[44:47]
	v_mfma_f32_16x16x32_bf16 v[40:43], v[80:83], v[226:229], v[40:43]
	v_mfma_f32_16x16x32_bf16 v[28:31], v[72:75], v[234:237], v[28:31]
	v_mfma_f32_16x16x32_bf16 v[24:27], v[80:83], v[234:237], v[24:27]
	v_mfma_f32_16x16x32_bf16 v[12:15], v[72:75], v[242:245], v[12:15]
	v_mfma_f32_16x16x32_bf16 v[8:11], v[80:83], v[242:245], v[8:11]
	v_mfma_f32_16x16x32_bf16 v[52:55], v[174:177], v[214:217], 0
	v_mfma_f32_16x16x32_bf16 v[48:51], v[186:189], v[214:217], 0
	v_mfma_f32_16x16x32_bf16 v[36:39], v[174:177], v[222:225], 0
	v_mfma_f32_16x16x32_bf16 v[32:35], v[186:189], v[222:225], 0
	v_mfma_f32_16x16x32_bf16 v[20:23], v[174:177], v[230:233], 0
	v_mfma_f32_16x16x32_bf16 v[16:19], v[186:189], v[230:233], 0
	v_mfma_f32_16x16x32_bf16 v[4:7], v[174:177], v[238:241], 0
	v_mfma_f32_16x16x32_bf16 v[0:3], v[186:189], v[238:241], 0
	v_mfma_f32_16x16x32_bf16 v[52:55], v[182:185], v[218:221], v[52:55]
	v_mfma_f32_16x16x32_bf16 v[48:51], v[210:213], v[218:221], v[48:51]
	v_mfma_f32_16x16x32_bf16 v[36:39], v[182:185], v[226:229], v[36:39]
	v_mfma_f32_16x16x32_bf16 v[32:35], v[210:213], v[226:229], v[32:35]
	v_mfma_f32_16x16x32_bf16 v[20:23], v[182:185], v[234:237], v[20:23]
	v_mfma_f32_16x16x32_bf16 v[16:19], v[210:213], v[234:237], v[16:19]
	v_mfma_f32_16x16x32_bf16 v[4:7], v[182:185], v[242:245], v[4:7]
	v_mfma_f32_16x16x32_bf16 v[0:3], v[210:213], v[242:245], v[0:3]
	s_setprio 0
	s_barrier
; #define PG8_STAGE(bufoff, gbase, voff) do { _Pragma("unroll") for (int _i = 0; _i < 2; ++_i) \
;         __builtin_amdgcn_global_load_lds((const unsigned*)((const char*)(gbase) + (voff)[_i]), (PG8_LAS unsigned*)(lds + (bufoff) + ldsw + _i * 8192), 16, 0, 0); } while (0)
; #define PG8_LDA(dst, b, h) do { _Pragma("unroll") for (int m = 0; m < 4; ++m) _Pragma("unroll") for (int k = 0; k < 2; ++k) dst[m][k] = *(const PG8_LAS bf16x8*)(lds + PG8_SA(b, h) + aoff + m * 2048 + k * 1024); } while (0)
; #define PG8_LDB(dst, b, h) do { _Pragma("unroll") for (int n = 0; n < 2; ++n) _Pragma("unroll") for (int k = 0; k < 2; ++k) dst[n][k] = *(const PG8_LAS bf16x8*)(lds + PG8_SB(b, h) + boff + n * 2048 + k * 1024); } while (0)
; #define PG8_MMA(ai, bj, At, Bt) do { __builtin_amdgcn_s_setprio(1); _Pragma("unroll") for (int m = 0; m < 4; ++m) _Pragma("unroll") for (int n = 0; n < 2; ++n) _Pragma("unroll") for (int k = 0; k < 2; ++k) \
;         acc[ai][bj][m][n] = __builtin_amdgcn_mfma_f32_16x16x32_bf16(Bt[n][k], At[m][k], acc[ai][bj][m][n], 0, 0, 0); __builtin_amdgcn_s_setprio(0); } while (0)
; #define PG8_WAIT_V(n) asm volatile("s_waitcnt vmcnt(" #n ")" ::: "memory")
; #define PG8_WAIT_L(n) asm volatile("s_waitcnt lgkmcnt(" #n ")" ::: "memory")
; #define PG8_BAR __builtin_amdgcn_s_barrier()
; #define PG8_SCHED __builtin_amdgcn_sched_barrier(0)
; template <class Epi, class Sched, bool ALIGN_EPI = false, bool SP2 = false>
; __device__ __forceinline__ void gemm_phase(PG8_LAS unsigned char* lds, const Gemm g, const Sched& S, const Epi& E) {
;     ...
;         for (int t = 0; t < nt; t += 2) {
;     ...
;             PG8_LDB(B0, 1, 0); PG8_LDB(B1, 1, 1); PG8_SCHED; PG8_LDA(At, 1, 0); PG8_STAGE(PG8_SA(0, 1), a2 + hstep, voffA);
;             PG8_WAIT_V(8); PG8_WAIT_L(0); PG8_BAR; PG8_MMA(0, 0, At, B0); PG8_MMA(0, 1, At, B1); PG8_BAR; PG8_SCHED;
;             PG8_LDA(At, 1, 1); PG8_STAGE(PG8_SB(1, 0), b3, voffB); PG8_STAGE(PG8_SB(1, 1), b3 + hstep, voffB); PG8_STAGE(PG8_SA(1, 0), a3, voffA);
;             PG8_WAIT_V(8); PG8_WAIT_L(0); PG8_BAR; PG8_MMA(1, 0, At, B0); PG8_MMA(1, 1, At, B1); PG8_BAR; PG8_SCHED;
	ds_read_b128 v[68:71], v254 offset:32768
	ds_read_b128 v[72:75], v254 offset:33792
	ds_read_b128 v[76:79], v254 offset:34816
	ds_read_b128 v[80:83], v254 offset:35840
	ds_read_b128 v[174:177], v254 offset:49152
	ds_read_b128 v[182:185], v254 offset:50176
	ds_read_b128 v[186:189], v254 offset:51200
	ds_read_b128 v[210:213], v254 offset:52224
	s_add_u32 s4, s4, 0x40000
	s_addc_u32 s5, s5, 0
	s_mov_b32 m0, s40
	ds_read_b128 v[214:217], v179 offset:32768
	ds_read_b128 v[218:221], v179 offset:33792
	ds_read_b128 v[222:225], v179 offset:34816
	ds_read_b128 v[226:229], v179 offset:35840
	ds_read_b128 v[230:233], v179 offset:36864
	ds_read_b128 v[234:237], v179 offset:37888
	ds_read_b128 v[238:241], v179 offset:38912
	ds_read_b128 v[242:245], v179 offset:39936
	global_load_lds_dwordx4 v168, s[4:5]
	s_mov_b32 m0, s41
	s_nop 0
	global_load_lds_dwordx4 v164, s[4:5]
	s_waitcnt vmcnt(8)
	s_waitcnt lgkmcnt(0)
	s_barrier
	s_setprio 1
	v_mfma_f32_16x16x32_bf16 v[140:143], v[68:71], v[214:217], v[140:143]
	v_mfma_f32_16x16x32_bf16 v[136:139], v[76:79], v[214:217], v[136:139]
	v_mfma_f32_16x16x32_bf16 v[124:127], v[68:71], v[222:225], v[124:127]
	v_mfma_f32_16x16x32_bf16 v[120:123], v[76:79], v[222:225], v[120:123]
	v_mfma_f32_16x16x32_bf16 v[108:111], v[68:71], v[230:233], v[108:111]
	v_mfma_f32_16x16x32_bf16 v[104:107], v[76:79], v[230:233], v[104:107]
	v_mfma_f32_16x16x32_bf16 v[92:95], v[68:71], v[238:241], v[92:95]
	v_mfma_f32_16x16x32_bf16 v[88:91], v[76:79], v[238:241], v[88:91]
	v_mfma_f32_16x16x32_bf16 v[140:143], v[72:75], v[218:221], v[140:143]
	v_mfma_f32_16x16x32_bf16 v[136:139], v[80:83], v[218:221], v[136:139]
	v_mfma_f32_16x16x32_bf16 v[124:127], v[72:75], v[226:229], v[124:127]
	v_mfma_f32_16x16x32_bf16 v[120:123], v[80:83], v[226:229], v[120:123]
	v_mfma_f32_16x16x32_bf16 v[108:111], v[72:75], v[234:237], v[108:111]
	v_mfma_f32_16x16x32_bf16 v[104:107], v[80:83], v[234:237], v[104:107]
	v_mfma_f32_16x16x32_bf16 v[92:95], v[72:75], v[242:245], v[92:95]
	v_mfma_f32_16x16x32_bf16 v[88:91], v[80:83], v[242:245], v[88:91]
	v_mfma_f32_16x16x32_bf16 v[132:135], v[174:177], v[214:217], v[132:135]
	v_mfma_f32_16x16x32_bf16 v[128:131], v[186:189], v[214:217], v[128:131]
	v_mfma_f32_16x16x32_bf16 v[116:119], v[174:177], v[222:225], v[116:119]
	v_mfma_f32_16x16x32_bf16 v[112:115], v[186:189], v[222:225], v[112:115]
	v_mfma_f32_16x16x32_bf16 v[100:103], v[174:177], v[230:233], v[100:103]
	v_mfma_f32_16x16x32_bf16 v[96:99], v[186:189], v[230:233], v[96:99]
	v_mfma_f32_16x16x32_bf16 v[84:87], v[174:177], v[238:241], v[84:87]
	v_mfma_f32_16x16x32_bf16 v[64:67], v[186:189], v[238:241], v[64:67]
	v_mfma_f32_16x16x32_bf16 v[132:135], v[182:185], v[218:221], v[132:135]
	v_mfma_f32_16x16x32_bf16 v[128:131], v[210:213], v[218:221], v[128:131]
	v_mfma_f32_16x16x32_bf16 v[116:119], v[182:185], v[226:229], v[116:119]
	v_mfma_f32_16x16x32_bf16 v[112:115], v[210:213], v[226:229], v[112:115]
	v_mfma_f32_16x16x32_bf16 v[100:103], v[182:185], v[234:237], v[100:103]
	v_mfma_f32_16x16x32_bf16 v[96:99], v[210:213], v[234:237], v[96:99]
	v_mfma_f32_16x16x32_bf16 v[84:87], v[182:185], v[242:245], v[84:87]
	v_mfma_f32_16x16x32_bf16 v[64:67], v[210:213], v[242:245], v[64:67]
	s_setprio 0
	s_barrier
	s_mov_b32 m0, s45
	s_add_u32 s2, s2, 0x40080
	s_addc_u32 s3, s3, 0
	ds_read_b128 v[214:217], v179 offset:49152
	ds_read_b128 v[218:221], v179 offset:50176
	ds_read_b128 v[222:225], v179 offset:51200
	ds_read_b128 v[226:229], v179 offset:52224
	ds_read_b128 v[230:233], v179 offset:53248
	ds_read_b128 v[234:237], v179 offset:54272
	ds_read_b128 v[238:241], v179 offset:55296
	ds_read_b128 v[242:245], v179 offset:56320
	s_add_u32 s98, s2, 0xfffc0000
	s_addc_u32 s99, s3, -1
	global_load_lds_dwordx4 v166, s[98:99]
	s_mov_b32 m0, s46
	s_nop 0
	global_load_lds_dwordx4 v162, s[98:99]
	s_mov_b32 m0, s49
	s_nop 0
	global_load_lds_dwordx4 v166, s[2:3]
	s_mov_b32 m0, s50
	s_nop 0
	global_load_lds_dwordx4 v162, s[2:3]
	s_mov_b32 m0, s47
	s_nop 0
	s_add_u32 s100, s4, 0xfffc0080
	s_addc_u32 s101, s5, -1
	global_load_lds_dwordx4 v168, s[100:101]
	s_mov_b32 m0, s48
	s_nop 0
	global_load_lds_dwordx4 v164, s[100:101]
	s_waitcnt vmcnt(8)
	s_waitcnt lgkmcnt(0)
	s_barrier
	s_setprio 1
	v_mfma_f32_16x16x32_bf16 v[60:63], v[68:71], v[214:217], v[60:63]
	v_mfma_f32_16x16x32_bf16 v[56:59], v[76:79], v[214:217], v[56:59]
	v_mfma_f32_16x16x32_bf16 v[44:47], v[68:71], v[222:225], v[44:47]
	v_mfma_f32_16x16x32_bf16 v[40:43], v[76:79], v[222:225], v[40:43]
	v_mfma_f32_16x16x32_bf16 v[28:31], v[68:71], v[230:233], v[28:31]
	v_mfma_f32_16x16x32_bf16 v[24:27], v[76:79], v[230:233], v[24:27]
	v_mfma_f32_16x16x32_bf16 v[12:15], v[68:71], v[238:241], v[12:15]
	v_mfma_f32_16x16x32_bf16 v[8:11], v[76:79], v[238:241], v[8:11]
	v_mfma_f32_16x16x32_bf16 v[60:63], v[72:75], v[218:221], v[60:63]
	v_mfma_f32_16x16x32_bf16 v[56:59], v[80:83], v[218:221], v[56:59]
	v_mfma_f32_16x16x32_bf16 v[44:47], v[72:75], v[226:229], v[44:47]
	v_mfma_f32_16x16x32_bf16 v[40:43], v[80:83], v[226:229], v[40:43]
	v_mfma_f32_16x16x32_bf16 v[28:31], v[72:75], v[234:237], v[28:31]
	v_mfma_f32_16x16x32_bf16 v[24:27], v[80:83], v[234:237], v[24:27]
	v_mfma_f32_16x16x32_bf16 v[12:15], v[72:75], v[242:245], v[12:15]
	v_mfma_f32_16x16x32_bf16 v[8:11], v[80:83], v[242:245], v[8:11]
	v_mfma_f32_16x16x32_bf16 v[52:55], v[174:177], v[214:217], v[52:55]
	v_mfma_f32_16x16x32_bf16 v[48:51], v[186:189], v[214:217], v[48:51]
	v_mfma_f32_16x16x32_bf16 v[36:39], v[174:177], v[222:225], v[36:39]
	v_mfma_f32_16x16x32_bf16 v[32:35], v[186:189], v[222:225], v[32:35]
	v_mfma_f32_16x16x32_bf16 v[20:23], v[174:177], v[230:233], v[20:23]
	v_mfma_f32_16x16x32_bf16 v[16:19], v[186:189], v[230:233], v[16:19]
	v_mfma_f32_16x16x32_bf16 v[4:7], v[174:177], v[238:241], v[4:7]
	v_mfma_f32_16x16x32_bf16 v[0:3], v[186:189], v[238:241], v[0:3]
	v_mfma_f32_16x16x32_bf16 v[52:55], v[182:185], v[218:221], v[52:55]
	v_mfma_f32_16x16x32_bf16 v[48:51], v[210:213], v[218:221], v[48:51]
	v_mfma_f32_16x16x32_bf16 v[36:39], v[182:185], v[226:229], v[36:39]
	v_mfma_f32_16x16x32_bf16 v[32:35], v[210:213], v[226:229], v[32:35]
	v_mfma_f32_16x16x32_bf16 v[20:23], v[182:185], v[234:237], v[20:23]
	v_mfma_f32_16x16x32_bf16 v[16:19], v[210:213], v[234:237], v[16:19]
	v_mfma_f32_16x16x32_bf16 v[4:7], v[182:185], v[242:245], v[4:7]
	v_mfma_f32_16x16x32_bf16 v[0:3], v[210:213], v[242:245], v[0:3]
	s_setprio 0
	s_barrier
	s_add_i32 s56, s56, 2
	s_add_u32 s0, s0, 0x100
	s_addc_u32 s1, s1, 0
	s_add_u32 s54, s54, 0x100
	s_addc_u32 s55, s55, 0
	s_cmp_gt_u32 s56, 13
; #define PG8_STAGE(bufoff, gbase, voff) do { _Pragma("unroll") for (int _i = 0; _i < 2; ++_i) \
;         __builtin_amdgcn_global_load_lds((const unsigned*)((const char*)(gbase) + (voff)[_i]), (PG8_LAS unsigned*)(lds + (bufoff) + ldsw + _i * 8192), 16, 0, 0); } while (0)
; #define PG8_LDA(dst, b, h) do { _Pragma("unroll") for (int m = 0; m < 4; ++m) _Pragma("unroll") for (int k = 0; k < 2; ++k) dst[m][k] = *(const PG8_LAS bf16x8*)(lds + PG8_SA(b, h) + aoff + m * 2048 + k * 1024); } while (0)
; #define PG8_LDB(dst, b, h) do { _Pragma("unroll") for (int n = 0; n < 2; ++n) _Pragma("unroll") for (int k = 0; k < 2; ++k) dst[n][k] = *(const PG8_LAS bf16x8*)(lds + PG8_SB(b, h) + boff + n * 2048 + k * 1024); } while (0)
; #define PG8_MMA(ai, bj, At, Bt) do { __builtin_amdgcn_s_setprio(1); _Pragma("unroll") for (int m = 0; m < 4; ++m) _Pragma("unroll") for (int n = 0; n < 2; ++n) _Pragma("unroll") for (int k = 0; k < 2; ++k) \
;         acc[ai][bj][m][n] = __builtin_amdgcn_mfma_f32_16x16x32_bf16(Bt[n][k], At[m][k], acc[ai][bj][m][n], 0, 0, 0); __builtin_amdgcn_s_setprio(0); } while (0)
; #define PG8_WAIT_V(n) asm volatile("s_waitcnt vmcnt(" #n ")" ::: "memory")
; #define PG8_WAIT_L(n) asm volatile("s_waitcnt lgkmcnt(" #n ")" ::: "memory")
; #define PG8_BAR __builtin_amdgcn_s_barrier()
; #define PG8_SCHED __builtin_amdgcn_sched_barrier(0)
; template <class Epi, class Sched, bool ALIGN_EPI = false, bool SP2 = false>
; __device__ __forceinline__ void gemm_phase(PG8_LAS unsigned char* lds, const Gemm g, const Sched& S, const Epi& E) {
;     ...
;             PG8_LDB(B0, 0, 0); PG8_LDB(B1, 0, 1); PG8_SCHED; PG8_LDA(At, 0, 0); PG8_STAGE(PG8_SA(1, 1), a1 + hstep, voffA);
;             PG8_WAIT_V(8); PG8_WAIT_L(0); PG8_BAR; PG8_MMA(0, 0, At, B0); PG8_MMA(0, 1, At, B1); PG8_BAR; PG8_SCHED;
;             PG8_LDA(At, 0, 1); PG8_STAGE(PG8_SB(0, 0), b2, voffB); PG8_STAGE(PG8_SB(0, 1), b2 + hstep, voffB); PG8_STAGE(PG8_SA(0, 0), a2, voffA);
;             PG8_WAIT_V(8); PG8_WAIT_L(0); PG8_BAR; PG8_MMA(1, 0, At, B0); PG8_MMA(1, 1, At, B1); PG8_BAR; PG8_SCHED;
.LBB0_327:
	ds_read_b128 v[68:71], v254
	ds_read_b128 v[72:75], v254 offset:1024
	ds_read_b128 v[76:79], v254 offset:2048
	ds_read_b128 v[80:83], v254 offset:3072
	ds_read_b128 v[174:177], v254 offset:16384
	ds_read_b128 v[182:185], v254 offset:17408
	ds_read_b128 v[186:189], v254 offset:18432
	ds_read_b128 v[210:213], v254 offset:19456
	s_add_u32 s2, s0, 0xfffc0080
	s_addc_u32 s3, s1, -1
	s_cmp_eq_u32 s56, 12
	s_cselect_b32 s5, s27, s3
	s_cselect_b32 s4, s52, s2
	s_cselect_b32 s3, s25, s55
	s_cselect_b32 s2, s53, s54
	s_add_i32 m0, s29, 0xc000
	ds_read_b128 v[214:217], v179
	ds_read_b128 v[218:221], v179 offset:1024
	ds_read_b128 v[222:225], v179 offset:2048
	ds_read_b128 v[226:229], v179 offset:3072
	ds_read_b128 v[230:233], v179 offset:4096
	ds_read_b128 v[234:237], v179 offset:5120
	ds_read_b128 v[238:241], v179 offset:6144
	ds_read_b128 v[242:245], v179 offset:7168
	global_load_lds_dwordx4 v170, s[0:1]
	s_add_i32 m0, s29, 0xe000
	s_nop 0
	global_load_lds_dwordx4 v172, s[0:1]
	s_waitcnt vmcnt(8)
	s_waitcnt lgkmcnt(0)
	s_barrier
	s_setprio 1
	v_mfma_f32_16x16x32_bf16 v[140:143], v[68:71], v[214:217], v[140:143]
	v_mfma_f32_16x16x32_bf16 v[136:139], v[76:79], v[214:217], v[136:139]
	v_mfma_f32_16x16x32_bf16 v[124:127], v[68:71], v[222:225], v[124:127]
	v_mfma_f32_16x16x32_bf16 v[120:123], v[76:79], v[222:225], v[120:123]
	v_mfma_f32_16x16x32_bf16 v[108:111], v[68:71], v[230:233], v[108:111]
	v_mfma_f32_16x16x32_bf16 v[104:107], v[76:79], v[230:233], v[104:107]
	v_mfma_f32_16x16x32_bf16 v[92:95], v[68:71], v[238:241], v[92:95]
	v_mfma_f32_16x16x32_bf16 v[88:91], v[76:79], v[238:241], v[88:91]
	v_mfma_f32_16x16x32_bf16 v[140:143], v[72:75], v[218:221], v[140:143]
	v_mfma_f32_16x16x32_bf16 v[136:139], v[80:83], v[218:221], v[136:139]
	v_mfma_f32_16x16x32_bf16 v[124:127], v[72:75], v[226:229], v[124:127]
	v_mfma_f32_16x16x32_bf16 v[120:123], v[80:83], v[226:229], v[120:123]
	v_mfma_f32_16x16x32_bf16 v[108:111], v[72:75], v[234:237], v[108:111]
	v_mfma_f32_16x16x32_bf16 v[104:107], v[80:83], v[234:237], v[104:107]
	v_mfma_f32_16x16x32_bf16 v[92:95], v[72:75], v[242:245], v[92:95]
	v_mfma_f32_16x16x32_bf16 v[88:91], v[80:83], v[242:245], v[88:91]
	v_mfma_f32_16x16x32_bf16 v[132:135], v[174:177], v[214:217], v[132:135]
	v_mfma_f32_16x16x32_bf16 v[128:131], v[186:189], v[214:217], v[128:131]
	v_mfma_f32_16x16x32_bf16 v[116:119], v[174:177], v[222:225], v[116:119]
	v_mfma_f32_16x16x32_bf16 v[112:115], v[186:189], v[222:225], v[112:115]
	v_mfma_f32_16x16x32_bf16 v[100:103], v[174:177], v[230:233], v[100:103]
	v_mfma_f32_16x16x32_bf16 v[96:99], v[186:189], v[230:233], v[96:99]
	v_mfma_f32_16x16x32_bf16 v[84:87], v[174:177], v[238:241], v[84:87]
	v_mfma_f32_16x16x32_bf16 v[64:67], v[186:189], v[238:241], v[64:67]
	v_mfma_f32_16x16x32_bf16 v[132:135], v[182:185], v[218:221], v[132:135]
	v_mfma_f32_16x16x32_bf16 v[128:131], v[210:213], v[218:221], v[128:131]
	v_mfma_f32_16x16x32_bf16 v[116:119], v[182:185], v[226:229], v[116:119]
	v_mfma_f32_16x16x32_bf16 v[112:115], v[210:213], v[226:229], v[112:115]
	v_mfma_f32_16x16x32_bf16 v[100:103], v[182:185], v[234:237], v[100:103]
	v_mfma_f32_16x16x32_bf16 v[96:99], v[210:213], v[234:237], v[96:99]
	v_mfma_f32_16x16x32_bf16 v[84:87], v[182:185], v[242:245], v[84:87]
	v_mfma_f32_16x16x32_bf16 v[64:67], v[210:213], v[242:245], v[64:67]
	s_setprio 0
	s_barrier
	s_mov_b32 m0, s30
	s_add_u32 s58, s2, 0x40000
	s_addc_u32 s59, s3, 0
	ds_read_b128 v[214:217], v179 offset:16384
	ds_read_b128 v[218:221], v179 offset:17408
	ds_read_b128 v[222:225], v179 offset:18432
	ds_read_b128 v[226:229], v179 offset:19456
	ds_read_b128 v[230:233], v179 offset:20480
	ds_read_b128 v[234:237], v179 offset:21504
	ds_read_b128 v[238:241], v179 offset:22528
	ds_read_b128 v[242:245], v179 offset:23552
	global_load_lds_dwordx4 v166, s[2:3]
	s_mov_b32 m0, s31
	s_nop 0
	global_load_lds_dwordx4 v162, s[2:3]
	s_mov_b32 m0, s33
	s_nop 0
	global_load_lds_dwordx4 v166, s[58:59]
	s_mov_b32 m0, s34
	s_nop 0
	global_load_lds_dwordx4 v162, s[58:59]
	s_mov_b32 m0, s29
	s_nop 0
	global_load_lds_dwordx4 v168, s[4:5]
	s_mov_b32 m0, s35
	s_nop 0
	global_load_lds_dwordx4 v164, s[4:5]
	s_waitcnt vmcnt(8)
	s_waitcnt lgkmcnt(0)
	s_barrier
	s_setprio 1
	v_mfma_f32_16x16x32_bf16 v[60:63], v[68:71], v[214:217], v[60:63]
	v_mfma_f32_16x16x32_bf16 v[56:59], v[76:79], v[214:217], v[56:59]
	v_mfma_f32_16x16x32_bf16 v[44:47], v[68:71], v[222:225], v[44:47]
	v_mfma_f32_16x16x32_bf16 v[40:43], v[76:79], v[222:225], v[40:43]
	v_mfma_f32_16x16x32_bf16 v[28:31], v[68:71], v[230:233], v[28:31]
	v_mfma_f32_16x16x32_bf16 v[24:27], v[76:79], v[230:233], v[24:27]
	v_mfma_f32_16x16x32_bf16 v[12:15], v[68:71], v[238:241], v[12:15]
	v_mfma_f32_16x16x32_bf16 v[8:11], v[76:79], v[238:241], v[8:11]
	v_mfma_f32_16x16x32_bf16 v[60:63], v[72:75], v[218:221], v[60:63]
	v_mfma_f32_16x16x32_bf16 v[56:59], v[80:83], v[218:221], v[56:59]
	v_mfma_f32_16x16x32_bf16 v[44:47], v[72:75], v[226:229], v[44:47]
	v_mfma_f32_16x16x32_bf16 v[40:43], v[80:83], v[226:229], v[40:43]
	v_mfma_f32_16x16x32_bf16 v[28:31], v[72:75], v[234:237], v[28:31]
	v_mfma_f32_16x16x32_bf16 v[24:27], v[80:83], v[234:237], v[24:27]
	v_mfma_f32_16x16x32_bf16 v[12:15], v[72:75], v[242:245], v[12:15]
	v_mfma_f32_16x16x32_bf16 v[8:11], v[80:83], v[242:245], v[8:11]
	v_mfma_f32_16x16x32_bf16 v[52:55], v[174:177], v[214:217], v[52:55]
	v_mfma_f32_16x16x32_bf16 v[48:51], v[186:189], v[214:217], v[48:51]
	v_mfma_f32_16x16x32_bf16 v[36:39], v[174:177], v[222:225], v[36:39]
	v_mfma_f32_16x16x32_bf16 v[32:35], v[186:189], v[222:225], v[32:35]
	v_mfma_f32_16x16x32_bf16 v[20:23], v[174:177], v[230:233], v[20:23]
	v_mfma_f32_16x16x32_bf16 v[16:19], v[186:189], v[230:233], v[16:19]
	v_mfma_f32_16x16x32_bf16 v[4:7], v[174:177], v[238:241], v[4:7]
	v_mfma_f32_16x16x32_bf16 v[0:3], v[186:189], v[238:241], v[0:3]
	v_mfma_f32_16x16x32_bf16 v[52:55], v[182:185], v[218:221], v[52:55]
	v_mfma_f32_16x16x32_bf16 v[48:51], v[210:213], v[218:221], v[48:51]
	v_mfma_f32_16x16x32_bf16 v[36:39], v[182:185], v[226:229], v[36:39]
	v_mfma_f32_16x16x32_bf16 v[32:35], v[210:213], v[226:229], v[32:35]
	v_mfma_f32_16x16x32_bf16 v[20:23], v[182:185], v[234:237], v[20:23]
	v_mfma_f32_16x16x32_bf16 v[16:19], v[210:213], v[234:237], v[16:19]
	v_mfma_f32_16x16x32_bf16 v[4:7], v[182:185], v[242:245], v[4:7]
	v_mfma_f32_16x16x32_bf16 v[0:3], v[210:213], v[242:245], v[0:3]
	s_setprio 0
	s_barrier
; #define PG8_STAGE(bufoff, gbase, voff) do { _Pragma("unroll") for (int _i = 0; _i < 2; ++_i) \
;         __builtin_amdgcn_global_load_lds((const unsigned*)((const char*)(gbase) + (voff)[_i]), (PG8_LAS unsigned*)(lds + (bufoff) + ldsw + _i * 8192), 16, 0, 0); } while (0)
; #define PG8_LDA(dst, b, h) do { _Pragma("unroll") for (int m = 0; m < 4; ++m) _Pragma("unroll") for (int k = 0; k < 2; ++k) dst[m][k] = *(const PG8_LAS bf16x8*)(lds + PG8_SA(b, h) + aoff + m * 2048 + k * 1024); } while (0)
; #define PG8_LDB(dst, b, h) do { _Pragma("unroll") for (int n = 0; n < 2; ++n) _Pragma("unroll") for (int k = 0; k < 2; ++k) dst[n][k] = *(const PG8_LAS bf16x8*)(lds + PG8_SB(b, h) + boff + n * 2048 + k * 1024); } while (0)
; #define PG8_MMA(ai, bj, At, Bt) do { __builtin_amdgcn_s_setprio(1); _Pragma("unroll") for (int m = 0; m < 4; ++m) _Pragma("unroll") for (int n = 0; n < 2; ++n) _Pragma("unroll") for (int k = 0; k < 2; ++k) \
;         acc[ai][bj][m][n] = __builtin_amdgcn_mfma_f32_16x16x32_bf16(Bt[n][k], At[m][k], acc[ai][bj][m][n], 0, 0, 0); __builtin_amdgcn_s_setprio(0); } while (0)
; #define PG8_WAIT_V(n) asm volatile("s_waitcnt vmcnt(" #n ")" ::: "memory")
; #define PG8_WAIT_L(n) asm volatile("s_waitcnt lgkmcnt(" #n ")" ::: "memory")
; #define PG8_BAR __builtin_amdgcn_s_barrier()
; #define PG8_SCHED __builtin_amdgcn_sched_barrier(0)
; template <class Epi, class Sched, bool ALIGN_EPI = false, bool SP2 = false>
; __device__ __forceinline__ void gemm_phase(PG8_LAS unsigned char* lds, const Gemm g, const Sched& S, const Epi& E) {
;     ...
;         for (int t = 0; t < nt; t += 2) {
;     ...
;             PG8_LDB(B0, 1, 0); PG8_LDB(B1, 1, 1); PG8_SCHED; PG8_LDA(At, 1, 0); PG8_STAGE(PG8_SA(0, 1), a2 + hstep, voffA);
;             PG8_WAIT_V(8); PG8_WAIT_L(0); PG8_BAR; PG8_MMA(0, 0, At, B0); PG8_MMA(0, 1, At, B1); PG8_BAR; PG8_SCHED;
;             PG8_LDA(At, 1, 1); PG8_STAGE(PG8_SB(1, 0), b3, voffB); PG8_STAGE(PG8_SB(1, 1), b3 + hstep, voffB); PG8_STAGE(PG8_SA(1, 0), a3, voffA);
;             PG8_WAIT_V(8); PG8_WAIT_L(0); PG8_BAR; PG8_MMA(1, 0, At, B0); PG8_MMA(1, 1, At, B1); PG8_BAR; PG8_SCHED;
	ds_read_b128 v[68:71], v254 offset:32768
	ds_read_b128 v[72:75], v254 offset:33792
	ds_read_b128 v[76:79], v254 offset:34816
	ds_read_b128 v[80:83], v254 offset:35840
	ds_read_b128 v[174:177], v254 offset:49152
	ds_read_b128 v[182:185], v254 offset:50176
	ds_read_b128 v[186:189], v254 offset:51200
	ds_read_b128 v[210:213], v254 offset:52224
	s_add_u32 s4, s4, 0x40000
	s_addc_u32 s5, s5, 0
	s_mov_b32 m0, s40
	ds_read_b128 v[214:217], v179 offset:32768
	ds_read_b128 v[218:221], v179 offset:33792
	ds_read_b128 v[222:225], v179 offset:34816
	ds_read_b128 v[226:229], v179 offset:35840
	ds_read_b128 v[230:233], v179 offset:36864
	ds_read_b128 v[234:237], v179 offset:37888
	ds_read_b128 v[238:241], v179 offset:38912
	ds_read_b128 v[242:245], v179 offset:39936
	global_load_lds_dwordx4 v168, s[4:5]
	s_mov_b32 m0, s41
	s_nop 0
	global_load_lds_dwordx4 v164, s[4:5]
	s_waitcnt vmcnt(8)
	s_waitcnt lgkmcnt(0)
	s_barrier
	s_setprio 1
	v_mfma_f32_16x16x32_bf16 v[140:143], v[68:71], v[214:217], v[140:143]
	v_mfma_f32_16x16x32_bf16 v[136:139], v[76:79], v[214:217], v[136:139]
	v_mfma_f32_16x16x32_bf16 v[124:127], v[68:71], v[222:225], v[124:127]
	v_mfma_f32_16x16x32_bf16 v[120:123], v[76:79], v[222:225], v[120:123]
	v_mfma_f32_16x16x32_bf16 v[108:111], v[68:71], v[230:233], v[108:111]
	v_mfma_f32_16x16x32_bf16 v[104:107], v[76:79], v[230:233], v[104:107]
	v_mfma_f32_16x16x32_bf16 v[92:95], v[68:71], v[238:241], v[92:95]
	v_mfma_f32_16x16x32_bf16 v[88:91], v[76:79], v[238:241], v[88:91]
	v_mfma_f32_16x16x32_bf16 v[140:143], v[72:75], v[218:221], v[140:143]
	v_mfma_f32_16x16x32_bf16 v[136:139], v[80:83], v[218:221], v[136:139]
	v_mfma_f32_16x16x32_bf16 v[124:127], v[72:75], v[226:229], v[124:127]
	v_mfma_f32_16x16x32_bf16 v[120:123], v[80:83], v[226:229], v[120:123]
	v_mfma_f32_16x16x32_bf16 v[108:111], v[72:75], v[234:237], v[108:111]
	v_mfma_f32_16x16x32_bf16 v[104:107], v[80:83], v[234:237], v[104:107]
	v_mfma_f32_16x16x32_bf16 v[92:95], v[72:75], v[242:245], v[92:95]
	v_mfma_f32_16x16x32_bf16 v[88:91], v[80:83], v[242:245], v[88:91]
	v_mfma_f32_16x16x32_bf16 v[132:135], v[174:177], v[214:217], v[132:135]
	v_mfma_f32_16x16x32_bf16 v[128:131], v[186:189], v[214:217], v[128:131]
	v_mfma_f32_16x16x32_bf16 v[116:119], v[174:177], v[222:225], v[116:119]
	v_mfma_f32_16x16x32_bf16 v[112:115], v[186:189], v[222:225], v[112:115]
	v_mfma_f32_16x16x32_bf16 v[100:103], v[174:177], v[230:233], v[100:103]
	v_mfma_f32_16x16x32_bf16 v[96:99], v[186:189], v[230:233], v[96:99]
	v_mfma_f32_16x16x32_bf16 v[84:87], v[174:177], v[238:241], v[84:87]
	v_mfma_f32_16x16x32_bf16 v[64:67], v[186:189], v[238:241], v[64:67]
	v_mfma_f32_16x16x32_bf16 v[132:135], v[182:185], v[218:221], v[132:135]
	v_mfma_f32_16x16x32_bf16 v[128:131], v[210:213], v[218:221], v[128:131]
	v_mfma_f32_16x16x32_bf16 v[116:119], v[182:185], v[226:229], v[116:119]
	v_mfma_f32_16x16x32_bf16 v[112:115], v[210:213], v[226:229], v[112:115]
	v_mfma_f32_16x16x32_bf16 v[100:103], v[182:185], v[234:237], v[100:103]
	v_mfma_f32_16x16x32_bf16 v[96:99], v[210:213], v[234:237], v[96:99]
	v_mfma_f32_16x16x32_bf16 v[84:87], v[182:185], v[242:245], v[84:87]
	v_mfma_f32_16x16x32_bf16 v[64:67], v[210:213], v[242:245], v[64:67]
	s_setprio 0
	s_barrier
	s_mov_b32 m0, s45
	s_add_u32 s2, s2, 0x40080
	s_addc_u32 s3, s3, 0
	ds_read_b128 v[214:217], v179 offset:49152
	ds_read_b128 v[218:221], v179 offset:50176
	ds_read_b128 v[222:225], v179 offset:51200
	ds_read_b128 v[226:229], v179 offset:52224
	ds_read_b128 v[230:233], v179 offset:53248
	ds_read_b128 v[234:237], v179 offset:54272
	ds_read_b128 v[238:241], v179 offset:55296
	ds_read_b128 v[242:245], v179 offset:56320
	s_add_u32 s98, s2, 0xfffc0000
	s_addc_u32 s99, s3, -1
	global_load_lds_dwordx4 v166, s[98:99]
	s_mov_b32 m0, s46
	s_nop 0
	global_load_lds_dwordx4 v162, s[98:99]
	s_mov_b32 m0, s49
	s_nop 0
	global_load_lds_dwordx4 v166, s[2:3]
	s_mov_b32 m0, s50
	s_nop 0
	global_load_lds_dwordx4 v162, s[2:3]
	s_mov_b32 m0, s47
	s_nop 0
	s_add_u32 s100, s4, 0xfffc0080
	s_addc_u32 s101, s5, -1
	global_load_lds_dwordx4 v168, s[100:101]
	s_mov_b32 m0, s48
	s_nop 0
	global_load_lds_dwordx4 v164, s[100:101]
	s_waitcnt vmcnt(8)
	s_waitcnt lgkmcnt(0)
	s_barrier
	s_setprio 1
	v_mfma_f32_16x16x32_bf16 v[60:63], v[68:71], v[214:217], v[60:63]
	v_mfma_f32_16x16x32_bf16 v[56:59], v[76:79], v[214:217], v[56:59]
	v_mfma_f32_16x16x32_bf16 v[44:47], v[68:71], v[222:225], v[44:47]
	v_mfma_f32_16x16x32_bf16 v[40:43], v[76:79], v[222:225], v[40:43]
	v_mfma_f32_16x16x32_bf16 v[28:31], v[68:71], v[230:233], v[28:31]
	v_mfma_f32_16x16x32_bf16 v[24:27], v[76:79], v[230:233], v[24:27]
	v_mfma_f32_16x16x32_bf16 v[12:15], v[68:71], v[238:241], v[12:15]
	v_mfma_f32_16x16x32_bf16 v[8:11], v[76:79], v[238:241], v[8:11]
	v_mfma_f32_16x16x32_bf16 v[60:63], v[72:75], v[218:221], v[60:63]
	v_mfma_f32_16x16x32_bf16 v[56:59], v[80:83], v[218:221], v[56:59]
	v_mfma_f32_16x16x32_bf16 v[44:47], v[72:75], v[226:229], v[44:47]
	v_mfma_f32_16x16x32_bf16 v[40:43], v[80:83], v[226:229], v[40:43]
	v_mfma_f32_16x16x32_bf16 v[28:31], v[72:75], v[234:237], v[28:31]
	v_mfma_f32_16x16x32_bf16 v[24:27], v[80:83], v[234:237], v[24:27]
	v_mfma_f32_16x16x32_bf16 v[12:15], v[72:75], v[242:245], v[12:15]
	v_mfma_f32_16x16x32_bf16 v[8:11], v[80:83], v[242:245], v[8:11]
	v_mfma_f32_16x16x32_bf16 v[52:55], v[174:177], v[214:217], v[52:55]
	v_mfma_f32_16x16x32_bf16 v[48:51], v[186:189], v[214:217], v[48:51]
	v_mfma_f32_16x16x32_bf16 v[36:39], v[174:177], v[222:225], v[36:39]
	v_mfma_f32_16x16x32_bf16 v[32:35], v[186:189], v[222:225], v[32:35]
	v_mfma_f32_16x16x32_bf16 v[20:23], v[174:177], v[230:233], v[20:23]
	v_mfma_f32_16x16x32_bf16 v[16:19], v[186:189], v[230:233], v[16:19]
	v_mfma_f32_16x16x32_bf16 v[4:7], v[174:177], v[238:241], v[4:7]
	v_mfma_f32_16x16x32_bf16 v[0:3], v[186:189], v[238:241], v[0:3]
	v_mfma_f32_16x16x32_bf16 v[52:55], v[182:185], v[218:221], v[52:55]
	v_mfma_f32_16x16x32_bf16 v[48:51], v[210:213], v[218:221], v[48:51]
	v_mfma_f32_16x16x32_bf16 v[36:39], v[182:185], v[226:229], v[36:39]
	v_mfma_f32_16x16x32_bf16 v[32:35], v[210:213], v[226:229], v[32:35]
	v_mfma_f32_16x16x32_bf16 v[20:23], v[182:185], v[234:237], v[20:23]
	v_mfma_f32_16x16x32_bf16 v[16:19], v[210:213], v[234:237], v[16:19]
	v_mfma_f32_16x16x32_bf16 v[4:7], v[182:185], v[242:245], v[4:7]
	v_mfma_f32_16x16x32_bf16 v[0:3], v[210:213], v[242:245], v[0:3]
	s_setprio 0
	s_barrier
	s_add_i32 s56, s56, 2
	s_add_u32 s0, s0, 0x100
	s_addc_u32 s1, s1, 0
	s_add_u32 s54, s54, 0x100
	s_addc_u32 s55, s55, 0
	s_cmp_gt_u32 s56, 13
	s_cbranch_scc0 .LBB0_327
	s_and_b64 vcc, exec, s[22:23]
	s_cbranch_vccz .LBB0_330
	s_barrier

; #define PG8_STAGE(bufoff, gbase, voff) do { _Pragma("unroll") for (int _i = 0; _i < 2; ++_i) \
;         __builtin_amdgcn_global_load_lds((const unsigned*)((const char*)(gbase) + (voff)[_i]), (PG8_LAS unsigned*)(lds + (bufoff) + ldsw + _i * 8192), 16, 0, 0); } while (0)
; #define PG8_LDA(dst, b, h) do { _Pragma("unroll") for (int m = 0; m < 4; ++m) _Pragma("unroll") for (int k = 0; k < 2; ++k) dst[m][k] = *(const PG8_LAS bf16x8*)(lds + PG8_SA(b, h) + aoff + m * 2048 + k * 1024); } while (0)
; #define PG8_LDB(dst, b, h) do { _Pragma("unroll") for (int n = 0; n < 2; ++n) _Pragma("unroll") for (int k = 0; k < 2; ++k) dst[n][k] = *(const PG8_LAS bf16x8*)(lds + PG8_SB(b, h) + boff + n * 2048 + k * 1024); } while (0)
; #define PG8_MMA(ai, bj, At, Bt) do { __builtin_amdgcn_s_setprio(1); _Pragma("unroll") for (int m = 0; m < 4; ++m) _Pragma("unroll") for (int n = 0; n < 2; ++n) _Pragma("unroll") for (int k = 0; k < 2; ++k) \
;         acc[ai][bj][m][n] = __builtin_amdgcn_mfma_f32_16x16x32_bf16(Bt[n][k], At[m][k], acc[ai][bj][m][n], 0, 0, 0); __builtin_amdgcn_s_setprio(0); } while (0)
; #define PG8_WAIT_V(n) asm volatile("s_waitcnt vmcnt(" #n ")" ::: "memory")
; #define PG8_WAIT_L(n) asm volatile("s_waitcnt lgkmcnt(" #n ")" ::: "memory")
; #define PG8_BAR __builtin_amdgcn_s_barrier()
; #define PG8_SCHED __builtin_amdgcn_sched_barrier(0)
; template <class Epi, class Sched, bool ALIGN_EPI = false, bool SP2 = false>
; __device__ __forceinline__ void gemm_phase(PG8_LAS unsigned char* lds, const Gemm g, const Sched& S, const Epi& E) {
;     ...
;             PG8_LDB(B0, 0, 0); PG8_LDB(B1, 0, 1); PG8_SCHED; PG8_LDA(At, 0, 0); PG8_STAGE(PG8_SA(1, 1), a1 + hstep, voffA);
;             PG8_WAIT_V(8); PG8_WAIT_L(0); PG8_BAR; PG8_MMA(0, 0, At, B0); PG8_MMA(0, 1, At, B1); PG8_BAR; PG8_SCHED;
;             PG8_LDA(At, 0, 1); PG8_STAGE(PG8_SB(0, 0), b2, voffB); PG8_STAGE(PG8_SB(0, 1), b2 + hstep, voffB); PG8_STAGE(PG8_SA(0, 0), a2, voffA);
;             PG8_WAIT_V(8); PG8_WAIT_L(0); PG8_BAR; PG8_MMA(1, 0, At, B0); PG8_MMA(1, 1, At, B1); PG8_BAR; PG8_SCHED;
.Lup_peel:
	ds_read_b128 v[140:143], v254
	ds_read_b128 v[168:171], v254 offset:1024
	ds_read_b128 v[172:175], v254 offset:2048
	ds_read_b128 v[176:179], v254 offset:3072
	ds_read_b128 v[180:183], v254 offset:16384
	ds_read_b128 v[184:187], v254 offset:17408
	ds_read_b128 v[188:191], v254 offset:18432
	ds_read_b128 v[210:213], v254 offset:19456
	s_add_u32 s16, s14, 0xfffc0080
	s_addc_u32 s17, s15, -1
	s_cmp_eq_u32 s53, 12
	s_cselect_b32 s19, s7, s17
	s_cselect_b32 s18, s49, s16
	s_cselect_b32 s17, s5, s52
	s_cselect_b32 s16, s50, s51
	s_mov_b32 m0, s43
	ds_read_b128 v[214:217], v165
	ds_read_b128 v[218:221], v165 offset:1024
	ds_read_b128 v[222:225], v165 offset:2048
	ds_read_b128 v[226:229], v165 offset:3072
	ds_read_b128 v[230:233], v165 offset:4096
	ds_read_b128 v[234:237], v165 offset:5120
	ds_read_b128 v[238:241], v165 offset:6144
	ds_read_b128 v[242:245], v165 offset:7168
	global_load_lds_dwordx4 v136, s[14:15]
	s_mov_b32 m0, s44
	s_nop 0
	global_load_lds_dwordx4 v138, s[14:15]
	s_waitcnt vmcnt(8)
	s_waitcnt lgkmcnt(0)
	s_barrier
	s_setprio 1
	v_mfma_f32_16x16x32_bf16 v[124:127], v[140:143], v[214:217], 0
	v_mfma_f32_16x16x32_bf16 v[116:119], v[172:175], v[214:217], 0
	v_mfma_f32_16x16x32_bf16 v[108:111], v[140:143], v[222:225], 0
	v_mfma_f32_16x16x32_bf16 v[100:103], v[172:175], v[222:225], 0
	v_mfma_f32_16x16x32_bf16 v[92:95], v[140:143], v[230:233], 0
	v_mfma_f32_16x16x32_bf16 v[84:87], v[172:175], v[230:233], 0
	v_mfma_f32_16x16x32_bf16 v[76:79], v[140:143], v[238:241], 0
	v_mfma_f32_16x16x32_bf16 v[68:71], v[172:175], v[238:241], 0
	v_mfma_f32_16x16x32_bf16 v[124:127], v[168:171], v[218:221], v[124:127]
	v_mfma_f32_16x16x32_bf16 v[116:119], v[176:179], v[218:221], v[116:119]
	v_mfma_f32_16x16x32_bf16 v[108:111], v[168:171], v[226:229], v[108:111]
	v_mfma_f32_16x16x32_bf16 v[100:103], v[176:179], v[226:229], v[100:103]
	v_mfma_f32_16x16x32_bf16 v[92:95], v[168:171], v[234:237], v[92:95]
	v_mfma_f32_16x16x32_bf16 v[84:87], v[176:179], v[234:237], v[84:87]
	v_mfma_f32_16x16x32_bf16 v[76:79], v[168:171], v[242:245], v[76:79]
	v_mfma_f32_16x16x32_bf16 v[68:71], v[176:179], v[242:245], v[68:71]
	v_mfma_f32_16x16x32_bf16 v[120:123], v[180:183], v[214:217], 0
	v_mfma_f32_16x16x32_bf16 v[112:115], v[188:191], v[214:217], 0
	v_mfma_f32_16x16x32_bf16 v[104:107], v[180:183], v[222:225], 0
	v_mfma_f32_16x16x32_bf16 v[96:99], v[188:191], v[222:225], 0
	v_mfma_f32_16x16x32_bf16 v[88:91], v[180:183], v[230:233], 0
	v_mfma_f32_16x16x32_bf16 v[80:83], v[188:191], v[230:233], 0
	v_mfma_f32_16x16x32_bf16 v[72:75], v[180:183], v[238:241], 0
	v_mfma_f32_16x16x32_bf16 v[64:67], v[188:191], v[238:241], 0
	v_mfma_f32_16x16x32_bf16 v[120:123], v[184:187], v[218:221], v[120:123]
	v_mfma_f32_16x16x32_bf16 v[112:115], v[210:213], v[218:221], v[112:115]
	v_mfma_f32_16x16x32_bf16 v[104:107], v[184:187], v[226:229], v[104:107]
	v_mfma_f32_16x16x32_bf16 v[96:99], v[210:213], v[226:229], v[96:99]
	v_mfma_f32_16x16x32_bf16 v[88:91], v[184:187], v[234:237], v[88:91]
	v_mfma_f32_16x16x32_bf16 v[80:83], v[210:213], v[234:237], v[80:83]
	v_mfma_f32_16x16x32_bf16 v[72:75], v[184:187], v[242:245], v[72:75]
	v_mfma_f32_16x16x32_bf16 v[64:67], v[210:213], v[242:245], v[64:67]
	s_setprio 0
	s_barrier
	s_mov_b32 m0, s27
	s_add_u32 s54, s16, 0x40000
	s_addc_u32 s55, s17, 0
	ds_read_b128 v[214:217], v165 offset:16384
	ds_read_b128 v[218:221], v165 offset:17408
	ds_read_b128 v[222:225], v165 offset:18432
	ds_read_b128 v[226:229], v165 offset:19456
	ds_read_b128 v[230:233], v165 offset:20480
	ds_read_b128 v[234:237], v165 offset:21504
	ds_read_b128 v[238:241], v165 offset:22528
	ds_read_b128 v[242:245], v165 offset:23552
	global_load_lds_dwordx4 v132, s[16:17]
	s_mov_b32 m0, s28
	s_nop 0
	global_load_lds_dwordx4 v128, s[16:17]
	s_mov_b32 m0, s29
	s_nop 0
	global_load_lds_dwordx4 v132, s[54:55]
	s_mov_b32 m0, s30
	s_nop 0
	global_load_lds_dwordx4 v128, s[54:55]
	s_mov_b32 m0, s22
	s_nop 0
	global_load_lds_dwordx4 v134, s[18:19]
	s_mov_b32 m0, s31
	s_nop 0
	global_load_lds_dwordx4 v130, s[18:19]
	s_waitcnt vmcnt(8)
	s_waitcnt lgkmcnt(0)
	s_barrier
	s_setprio 1
	v_mfma_f32_16x16x32_bf16 v[60:63], v[140:143], v[214:217], 0
	v_mfma_f32_16x16x32_bf16 v[52:55], v[172:175], v[214:217], 0
	v_mfma_f32_16x16x32_bf16 v[44:47], v[140:143], v[222:225], 0
	v_mfma_f32_16x16x32_bf16 v[36:39], v[172:175], v[222:225], 0
	v_mfma_f32_16x16x32_bf16 v[28:31], v[140:143], v[230:233], 0
	v_mfma_f32_16x16x32_bf16 v[20:23], v[172:175], v[230:233], 0
	v_mfma_f32_16x16x32_bf16 v[12:15], v[140:143], v[238:241], 0
	v_mfma_f32_16x16x32_bf16 v[4:7], v[172:175], v[238:241], 0
	v_mfma_f32_16x16x32_bf16 v[60:63], v[168:171], v[218:221], v[60:63]
	v_mfma_f32_16x16x32_bf16 v[52:55], v[176:179], v[218:221], v[52:55]
	v_mfma_f32_16x16x32_bf16 v[44:47], v[168:171], v[226:229], v[44:47]
	v_mfma_f32_16x16x32_bf16 v[36:39], v[176:179], v[226:229], v[36:39]
	v_mfma_f32_16x16x32_bf16 v[28:31], v[168:171], v[234:237], v[28:31]
	v_mfma_f32_16x16x32_bf16 v[20:23], v[176:179], v[234:237], v[20:23]
	v_mfma_f32_16x16x32_bf16 v[12:15], v[168:171], v[242:245], v[12:15]
	v_mfma_f32_16x16x32_bf16 v[4:7], v[176:179], v[242:245], v[4:7]
	v_mfma_f32_16x16x32_bf16 v[56:59], v[180:183], v[214:217], 0
	v_mfma_f32_16x16x32_bf16 v[48:51], v[188:191], v[214:217], 0
	v_mfma_f32_16x16x32_bf16 v[40:43], v[180:183], v[222:225], 0
	v_mfma_f32_16x16x32_bf16 v[32:35], v[188:191], v[222:225], 0
	v_mfma_f32_16x16x32_bf16 v[24:27], v[180:183], v[230:233], 0
	v_mfma_f32_16x16x32_bf16 v[16:19], v[188:191], v[230:233], 0
	v_mfma_f32_16x16x32_bf16 v[8:11], v[180:183], v[238:241], 0
	v_mfma_f32_16x16x32_bf16 v[0:3], v[188:191], v[238:241], 0
	v_mfma_f32_16x16x32_bf16 v[56:59], v[184:187], v[218:221], v[56:59]
	v_mfma_f32_16x16x32_bf16 v[48:51], v[210:213], v[218:221], v[48:51]
	v_mfma_f32_16x16x32_bf16 v[40:43], v[184:187], v[226:229], v[40:43]
	v_mfma_f32_16x16x32_bf16 v[32:35], v[210:213], v[226:229], v[32:35]
	v_mfma_f32_16x16x32_bf16 v[24:27], v[184:187], v[234:237], v[24:27]
	v_mfma_f32_16x16x32_bf16 v[16:19], v[210:213], v[234:237], v[16:19]
	v_mfma_f32_16x16x32_bf16 v[8:11], v[184:187], v[242:245], v[8:11]
	v_mfma_f32_16x16x32_bf16 v[0:3], v[210:213], v[242:245], v[0:3]
	s_setprio 0
	s_barrier
; #define PG8_STAGE(bufoff, gbase, voff) do { _Pragma("unroll") for (int _i = 0; _i < 2; ++_i) \
;         __builtin_amdgcn_global_load_lds((const unsigned*)((const char*)(gbase) + (voff)[_i]), (PG8_LAS unsigned*)(lds + (bufoff) + ldsw + _i * 8192), 16, 0, 0); } while (0)
; #define PG8_LDA(dst, b, h) do { _Pragma("unroll") for (int m = 0; m < 4; ++m) _Pragma("unroll") for (int k = 0; k < 2; ++k) dst[m][k] = *(const PG8_LAS bf16x8*)(lds + PG8_SA(b, h) + aoff + m * 2048 + k * 1024); } while (0)
; #define PG8_LDB(dst, b, h) do { _Pragma("unroll") for (int n = 0; n < 2; ++n) _Pragma("unroll") for (int k = 0; k < 2; ++k) dst[n][k] = *(const PG8_LAS bf16x8*)(lds + PG8_SB(b, h) + boff + n * 2048 + k * 1024); } while (0)
; #define PG8_MMA(ai, bj, At, Bt) do { __builtin_amdgcn_s_setprio(1); _Pragma("unroll") for (int m = 0; m < 4; ++m) _Pragma("unroll") for (int n = 0; n < 2; ++n) _Pragma("unroll") for (int k = 0; k < 2; ++k) \
;         acc[ai][bj][m][n] = __builtin_amdgcn_mfma_f32_16x16x32_bf16(Bt[n][k], At[m][k], acc[ai][bj][m][n], 0, 0, 0); __builtin_amdgcn_s_setprio(0); } while (0)
; #define PG8_WAIT_V(n) asm volatile("s_waitcnt vmcnt(" #n ")" ::: "memory")
; #define PG8_WAIT_L(n) asm volatile("s_waitcnt lgkmcnt(" #n ")" ::: "memory")
; #define PG8_BAR __builtin_amdgcn_s_barrier()
; #define PG8_SCHED __builtin_amdgcn_sched_barrier(0)
; template <class Epi, class Sched, bool ALIGN_EPI = false, bool SP2 = false>
; __device__ __forceinline__ void gemm_phase(PG8_LAS unsigned char* lds, const Gemm g, const Sched& S, const Epi& E) {
;     ...
;         for (int t = 0; t < nt; t += 2) {
;     ...
;             PG8_LDB(B0, 1, 0); PG8_LDB(B1, 1, 1); PG8_SCHED; PG8_LDA(At, 1, 0); PG8_STAGE(PG8_SA(0, 1), a2 + hstep, voffA);
;             PG8_WAIT_V(8); PG8_WAIT_L(0); PG8_BAR; PG8_MMA(0, 0, At, B0); PG8_MMA(0, 1, At, B1); PG8_BAR; PG8_SCHED;
;             PG8_LDA(At, 1, 1); PG8_STAGE(PG8_SB(1, 0), b3, voffB); PG8_STAGE(PG8_SB(1, 1), b3 + hstep, voffB); PG8_STAGE(PG8_SA(1, 0), a3, voffA);
;             PG8_WAIT_V(8); PG8_WAIT_L(0); PG8_BAR; PG8_MMA(1, 0, At, B0); PG8_MMA(1, 1, At, B1); PG8_BAR; PG8_SCHED;
	ds_read_b128 v[140:143], v254 offset:32768
	ds_read_b128 v[168:171], v254 offset:33792
	ds_read_b128 v[172:175], v254 offset:34816
	ds_read_b128 v[176:179], v254 offset:35840
	ds_read_b128 v[180:183], v254 offset:49152
	ds_read_b128 v[184:187], v254 offset:50176
	ds_read_b128 v[188:191], v254 offset:51200
	ds_read_b128 v[210:213], v254 offset:52224
	s_add_u32 s18, s18, 0x40000
	s_addc_u32 s19, s19, 0
	s_mov_b32 m0, s33
	ds_read_b128 v[214:217], v165 offset:32768
	ds_read_b128 v[218:221], v165 offset:33792
	ds_read_b128 v[222:225], v165 offset:34816
	ds_read_b128 v[226:229], v165 offset:35840
	ds_read_b128 v[230:233], v165 offset:36864
	ds_read_b128 v[234:237], v165 offset:37888
	ds_read_b128 v[238:241], v165 offset:38912
	ds_read_b128 v[242:245], v165 offset:39936
	global_load_lds_dwordx4 v134, s[18:19]
	s_mov_b32 m0, s34
	s_nop 0
	global_load_lds_dwordx4 v130, s[18:19]
	s_waitcnt vmcnt(8)
	s_waitcnt lgkmcnt(0)
	s_barrier
	s_setprio 1
	v_mfma_f32_16x16x32_bf16 v[124:127], v[140:143], v[214:217], v[124:127]
	v_mfma_f32_16x16x32_bf16 v[116:119], v[172:175], v[214:217], v[116:119]
	v_mfma_f32_16x16x32_bf16 v[108:111], v[140:143], v[222:225], v[108:111]
	v_mfma_f32_16x16x32_bf16 v[100:103], v[172:175], v[222:225], v[100:103]
	v_mfma_f32_16x16x32_bf16 v[92:95], v[140:143], v[230:233], v[92:95]
	v_mfma_f32_16x16x32_bf16 v[84:87], v[172:175], v[230:233], v[84:87]
	v_mfma_f32_16x16x32_bf16 v[76:79], v[140:143], v[238:241], v[76:79]
	v_mfma_f32_16x16x32_bf16 v[68:71], v[172:175], v[238:241], v[68:71]
	v_mfma_f32_16x16x32_bf16 v[124:127], v[168:171], v[218:221], v[124:127]
	v_mfma_f32_16x16x32_bf16 v[116:119], v[176:179], v[218:221], v[116:119]
	v_mfma_f32_16x16x32_bf16 v[108:111], v[168:171], v[226:229], v[108:111]
	v_mfma_f32_16x16x32_bf16 v[100:103], v[176:179], v[226:229], v[100:103]
	v_mfma_f32_16x16x32_bf16 v[92:95], v[168:171], v[234:237], v[92:95]
	v_mfma_f32_16x16x32_bf16 v[84:87], v[176:179], v[234:237], v[84:87]
	v_mfma_f32_16x16x32_bf16 v[76:79], v[168:171], v[242:245], v[76:79]
	v_mfma_f32_16x16x32_bf16 v[68:71], v[176:179], v[242:245], v[68:71]
	v_mfma_f32_16x16x32_bf16 v[120:123], v[180:183], v[214:217], v[120:123]
	v_mfma_f32_16x16x32_bf16 v[112:115], v[188:191], v[214:217], v[112:115]
	v_mfma_f32_16x16x32_bf16 v[104:107], v[180:183], v[222:225], v[104:107]
	v_mfma_f32_16x16x32_bf16 v[96:99], v[188:191], v[222:225], v[96:99]
	v_mfma_f32_16x16x32_bf16 v[88:91], v[180:183], v[230:233], v[88:91]
	v_mfma_f32_16x16x32_bf16 v[80:83], v[188:191], v[230:233], v[80:83]
	v_mfma_f32_16x16x32_bf16 v[72:75], v[180:183], v[238:241], v[72:75]
	v_mfma_f32_16x16x32_bf16 v[64:67], v[188:191], v[238:241], v[64:67]
	v_mfma_f32_16x16x32_bf16 v[120:123], v[184:187], v[218:221], v[120:123]
	v_mfma_f32_16x16x32_bf16 v[112:115], v[210:213], v[218:221], v[112:115]
	v_mfma_f32_16x16x32_bf16 v[104:107], v[184:187], v[226:229], v[104:107]
	v_mfma_f32_16x16x32_bf16 v[96:99], v[210:213], v[226:229], v[96:99]
	v_mfma_f32_16x16x32_bf16 v[88:91], v[184:187], v[234:237], v[88:91]
	v_mfma_f32_16x16x32_bf16 v[80:83], v[210:213], v[234:237], v[80:83]
	v_mfma_f32_16x16x32_bf16 v[72:75], v[184:187], v[242:245], v[72:75]
	v_mfma_f32_16x16x32_bf16 v[64:67], v[210:213], v[242:245], v[64:67]
	s_setprio 0
	s_barrier
	s_mov_b32 m0, s37
	s_add_u32 s16, s16, 0x40080
	s_addc_u32 s17, s17, 0
	ds_read_b128 v[214:217], v165 offset:49152
	ds_read_b128 v[218:221], v165 offset:50176
	ds_read_b128 v[222:225], v165 offset:51200
	ds_read_b128 v[226:229], v165 offset:52224
	ds_read_b128 v[230:233], v165 offset:53248
	ds_read_b128 v[234:237], v165 offset:54272
	ds_read_b128 v[238:241], v165 offset:55296
	ds_read_b128 v[242:245], v165 offset:56320
	s_add_u32 s98, s16, 0xfffc0000
	s_addc_u32 s99, s17, -1
	global_load_lds_dwordx4 v132, s[98:99]
	s_mov_b32 m0, s38
	s_nop 0
	global_load_lds_dwordx4 v128, s[98:99]
	s_mov_b32 m0, s41
	s_nop 0
	global_load_lds_dwordx4 v132, s[16:17]
	s_mov_b32 m0, s42
	s_nop 0
	global_load_lds_dwordx4 v128, s[16:17]
	s_mov_b32 m0, s39
	s_nop 0
	s_add_u32 s100, s18, 0xfffc0080
	s_addc_u32 s101, s19, -1
	global_load_lds_dwordx4 v134, s[100:101]
	s_mov_b32 m0, s40
	s_nop 0
	global_load_lds_dwordx4 v130, s[100:101]
	s_waitcnt vmcnt(8)
	s_waitcnt lgkmcnt(0)
	s_barrier
	s_setprio 1
	v_mfma_f32_16x16x32_bf16 v[60:63], v[140:143], v[214:217], v[60:63]
	v_mfma_f32_16x16x32_bf16 v[52:55], v[172:175], v[214:217], v[52:55]
	v_mfma_f32_16x16x32_bf16 v[44:47], v[140:143], v[222:225], v[44:47]
	v_mfma_f32_16x16x32_bf16 v[36:39], v[172:175], v[222:225], v[36:39]
	v_mfma_f32_16x16x32_bf16 v[28:31], v[140:143], v[230:233], v[28:31]
	v_mfma_f32_16x16x32_bf16 v[20:23], v[172:175], v[230:233], v[20:23]
	v_mfma_f32_16x16x32_bf16 v[12:15], v[140:143], v[238:241], v[12:15]
	v_mfma_f32_16x16x32_bf16 v[4:7], v[172:175], v[238:241], v[4:7]
	v_mfma_f32_16x16x32_bf16 v[60:63], v[168:171], v[218:221], v[60:63]
	v_mfma_f32_16x16x32_bf16 v[52:55], v[176:179], v[218:221], v[52:55]
	v_mfma_f32_16x16x32_bf16 v[44:47], v[168:171], v[226:229], v[44:47]
	v_mfma_f32_16x16x32_bf16 v[36:39], v[176:179], v[226:229], v[36:39]
	v_mfma_f32_16x16x32_bf16 v[28:31], v[168:171], v[234:237], v[28:31]
	v_mfma_f32_16x16x32_bf16 v[20:23], v[176:179], v[234:237], v[20:23]
	v_mfma_f32_16x16x32_bf16 v[12:15], v[168:171], v[242:245], v[12:15]
	v_mfma_f32_16x16x32_bf16 v[4:7], v[176:179], v[242:245], v[4:7]
	v_mfma_f32_16x16x32_bf16 v[56:59], v[180:183], v[214:217], v[56:59]
	v_mfma_f32_16x16x32_bf16 v[48:51], v[188:191], v[214:217], v[48:51]
	v_mfma_f32_16x16x32_bf16 v[40:43], v[180:183], v[222:225], v[40:43]
	v_mfma_f32_16x16x32_bf16 v[32:35], v[188:191], v[222:225], v[32:35]
	v_mfma_f32_16x16x32_bf16 v[24:27], v[180:183], v[230:233], v[24:27]
	v_mfma_f32_16x16x32_bf16 v[16:19], v[188:191], v[230:233], v[16:19]
	v_mfma_f32_16x16x32_bf16 v[8:11], v[180:183], v[238:241], v[8:11]
	v_mfma_f32_16x16x32_bf16 v[0:3], v[188:191], v[238:241], v[0:3]
	v_mfma_f32_16x16x32_bf16 v[56:59], v[184:187], v[218:221], v[56:59]
	v_mfma_f32_16x16x32_bf16 v[48:51], v[210:213], v[218:221], v[48:51]
	v_mfma_f32_16x16x32_bf16 v[40:43], v[184:187], v[226:229], v[40:43]
	v_mfma_f32_16x16x32_bf16 v[32:35], v[210:213], v[226:229], v[32:35]
	v_mfma_f32_16x16x32_bf16 v[24:27], v[184:187], v[234:237], v[24:27]
	v_mfma_f32_16x16x32_bf16 v[16:19], v[210:213], v[234:237], v[16:19]
	v_mfma_f32_16x16x32_bf16 v[8:11], v[184:187], v[242:245], v[8:11]
	v_mfma_f32_16x16x32_bf16 v[0:3], v[210:213], v[242:245], v[0:3]
	s_setprio 0
	s_barrier
	s_add_i32 s53, s53, 2
	s_add_u32 s14, s14, 0x100
	s_addc_u32 s15, s15, 0
	s_add_u32 s51, s51, 0x100
	s_addc_u32 s52, s52, 0
	s_cmp_gt_u32 s53, 13
; #define PG8_STAGE(bufoff, gbase, voff) do { _Pragma("unroll") for (int _i = 0; _i < 2; ++_i) \
;         __builtin_amdgcn_global_load_lds((const unsigned*)((const char*)(gbase) + (voff)[_i]), (PG8_LAS unsigned*)(lds + (bufoff) + ldsw + _i * 8192), 16, 0, 0); } while (0)
; #define PG8_LDA(dst, b, h) do { _Pragma("unroll") for (int m = 0; m < 4; ++m) _Pragma("unroll") for (int k = 0; k < 2; ++k) dst[m][k] = *(const PG8_LAS bf16x8*)(lds + PG8_SA(b, h) + aoff + m * 2048 + k * 1024); } while (0)
; #define PG8_LDB(dst, b, h) do { _Pragma("unroll") for (int n = 0; n < 2; ++n) _Pragma("unroll") for (int k = 0; k < 2; ++k) dst[n][k] = *(const PG8_LAS bf16x8*)(lds + PG8_SB(b, h) + boff + n * 2048 + k * 1024); } while (0)
; #define PG8_MMA(ai, bj, At, Bt) do { __builtin_amdgcn_s_setprio(1); _Pragma("unroll") for (int m = 0; m < 4; ++m) _Pragma("unroll") for (int n = 0; n < 2; ++n) _Pragma("unroll") for (int k = 0; k < 2; ++k) \
;         acc[ai][bj][m][n] = __builtin_amdgcn_mfma_f32_16x16x32_bf16(Bt[n][k], At[m][k], acc[ai][bj][m][n], 0, 0, 0); __builtin_amdgcn_s_setprio(0); } while (0)
; #define PG8_WAIT_V(n) asm volatile("s_waitcnt vmcnt(" #n ")" ::: "memory")
; #define PG8_WAIT_L(n) asm volatile("s_waitcnt lgkmcnt(" #n ")" ::: "memory")
; #define PG8_BAR __builtin_amdgcn_s_barrier()
; #define PG8_SCHED __builtin_amdgcn_sched_barrier(0)
; template <class Epi, class Sched, bool ALIGN_EPI = false, bool SP2 = false>
; __device__ __forceinline__ void gemm_phase(PG8_LAS unsigned char* lds, const Gemm g, const Sched& S, const Epi& E) {
;     ...
;             PG8_LDB(B0, 0, 0); PG8_LDB(B1, 0, 1); PG8_SCHED; PG8_LDA(At, 0, 0); PG8_STAGE(PG8_SA(1, 1), a1 + hstep, voffA);
;             PG8_WAIT_V(8); PG8_WAIT_L(0); PG8_BAR; PG8_MMA(0, 0, At, B0); PG8_MMA(0, 1, At, B1); PG8_BAR; PG8_SCHED;
;             PG8_LDA(At, 0, 1); PG8_STAGE(PG8_SB(0, 0), b2, voffB); PG8_STAGE(PG8_SB(0, 1), b2 + hstep, voffB); PG8_STAGE(PG8_SA(0, 0), a2, voffA);
;             PG8_WAIT_V(8); PG8_WAIT_L(0); PG8_BAR; PG8_MMA(1, 0, At, B0); PG8_MMA(1, 1, At, B1); PG8_BAR; PG8_SCHED;
.LBB0_446:
	ds_read_b128 v[140:143], v254
	ds_read_b128 v[168:171], v254 offset:1024
	ds_read_b128 v[172:175], v254 offset:2048
	ds_read_b128 v[176:179], v254 offset:3072
	ds_read_b128 v[180:183], v254 offset:16384
	ds_read_b128 v[184:187], v254 offset:17408
	ds_read_b128 v[188:191], v254 offset:18432
	ds_read_b128 v[210:213], v254 offset:19456
	s_add_u32 s16, s14, 0xfffc0080
	s_addc_u32 s17, s15, -1
	s_cmp_eq_u32 s53, 12
	s_cselect_b32 s19, s7, s17
	s_cselect_b32 s18, s49, s16
	s_cselect_b32 s17, s5, s52
	s_cselect_b32 s16, s50, s51
	s_mov_b32 m0, s43
	ds_read_b128 v[214:217], v165
	ds_read_b128 v[218:221], v165 offset:1024
	ds_read_b128 v[222:225], v165 offset:2048
	ds_read_b128 v[226:229], v165 offset:3072
	ds_read_b128 v[230:233], v165 offset:4096
	ds_read_b128 v[234:237], v165 offset:5120
	ds_read_b128 v[238:241], v165 offset:6144
	ds_read_b128 v[242:245], v165 offset:7168
	global_load_lds_dwordx4 v136, s[14:15]
	s_mov_b32 m0, s44
	s_nop 0
	global_load_lds_dwordx4 v138, s[14:15]
	s_waitcnt vmcnt(8)
	s_waitcnt lgkmcnt(0)
	s_barrier
	s_setprio 1
	v_mfma_f32_16x16x32_bf16 v[124:127], v[140:143], v[214:217], v[124:127]
	v_mfma_f32_16x16x32_bf16 v[116:119], v[172:175], v[214:217], v[116:119]
	v_mfma_f32_16x16x32_bf16 v[108:111], v[140:143], v[222:225], v[108:111]
	v_mfma_f32_16x16x32_bf16 v[100:103], v[172:175], v[222:225], v[100:103]
	v_mfma_f32_16x16x32_bf16 v[92:95], v[140:143], v[230:233], v[92:95]
	v_mfma_f32_16x16x32_bf16 v[84:87], v[172:175], v[230:233], v[84:87]
	v_mfma_f32_16x16x32_bf16 v[76:79], v[140:143], v[238:241], v[76:79]
	v_mfma_f32_16x16x32_bf16 v[68:71], v[172:175], v[238:241], v[68:71]
	v_mfma_f32_16x16x32_bf16 v[124:127], v[168:171], v[218:221], v[124:127]
	v_mfma_f32_16x16x32_bf16 v[116:119], v[176:179], v[218:221], v[116:119]
	v_mfma_f32_16x16x32_bf16 v[108:111], v[168:171], v[226:229], v[108:111]
	v_mfma_f32_16x16x32_bf16 v[100:103], v[176:179], v[226:229], v[100:103]
	v_mfma_f32_16x16x32_bf16 v[92:95], v[168:171], v[234:237], v[92:95]
	v_mfma_f32_16x16x32_bf16 v[84:87], v[176:179], v[234:237], v[84:87]
	v_mfma_f32_16x16x32_bf16 v[76:79], v[168:171], v[242:245], v[76:79]
	v_mfma_f32_16x16x32_bf16 v[68:71], v[176:179], v[242:245], v[68:71]
	v_mfma_f32_16x16x32_bf16 v[120:123], v[180:183], v[214:217], v[120:123]
	v_mfma_f32_16x16x32_bf16 v[112:115], v[188:191], v[214:217], v[112:115]
	v_mfma_f32_16x16x32_bf16 v[104:107], v[180:183], v[222:225], v[104:107]
	v_mfma_f32_16x16x32_bf16 v[96:99], v[188:191], v[222:225], v[96:99]
	v_mfma_f32_16x16x32_bf16 v[88:91], v[180:183], v[230:233], v[88:91]
	v_mfma_f32_16x16x32_bf16 v[80:83], v[188:191], v[230:233], v[80:83]
	v_mfma_f32_16x16x32_bf16 v[72:75], v[180:183], v[238:241], v[72:75]
	v_mfma_f32_16x16x32_bf16 v[64:67], v[188:191], v[238:241], v[64:67]
	v_mfma_f32_16x16x32_bf16 v[120:123], v[184:187], v[218:221], v[120:123]
	v_mfma_f32_16x16x32_bf16 v[112:115], v[210:213], v[218:221], v[112:115]
	v_mfma_f32_16x16x32_bf16 v[104:107], v[184:187], v[226:229], v[104:107]
	v_mfma_f32_16x16x32_bf16 v[96:99], v[210:213], v[226:229], v[96:99]
	v_mfma_f32_16x16x32_bf16 v[88:91], v[184:187], v[234:237], v[88:91]
	v_mfma_f32_16x16x32_bf16 v[80:83], v[210:213], v[234:237], v[80:83]
	v_mfma_f32_16x16x32_bf16 v[72:75], v[184:187], v[242:245], v[72:75]
	v_mfma_f32_16x16x32_bf16 v[64:67], v[210:213], v[242:245], v[64:67]
	s_setprio 0
	s_barrier
	s_mov_b32 m0, s27
	s_add_u32 s54, s16, 0x40000
	s_addc_u32 s55, s17, 0
	ds_read_b128 v[214:217], v165 offset:16384
	ds_read_b128 v[218:221], v165 offset:17408
	ds_read_b128 v[222:225], v165 offset:18432
	ds_read_b128 v[226:229], v165 offset:19456
	ds_read_b128 v[230:233], v165 offset:20480
	ds_read_b128 v[234:237], v165 offset:21504
	ds_read_b128 v[238:241], v165 offset:22528
	ds_read_b128 v[242:245], v165 offset:23552
	global_load_lds_dwordx4 v132, s[16:17]
	s_mov_b32 m0, s28
	s_nop 0
	global_load_lds_dwordx4 v128, s[16:17]
	s_mov_b32 m0, s29
	s_nop 0
	global_load_lds_dwordx4 v132, s[54:55]
	s_mov_b32 m0, s30
	s_nop 0
	global_load_lds_dwordx4 v128, s[54:55]
	s_mov_b32 m0, s22
	s_nop 0
	global_load_lds_dwordx4 v134, s[18:19]
	s_mov_b32 m0, s31
	s_nop 0
	global_load_lds_dwordx4 v130, s[18:19]
	s_waitcnt vmcnt(8)
	s_waitcnt lgkmcnt(0)
	s_barrier
	s_setprio 1
	v_mfma_f32_16x16x32_bf16 v[60:63], v[140:143], v[214:217], v[60:63]
	v_mfma_f32_16x16x32_bf16 v[52:55], v[172:175], v[214:217], v[52:55]
	v_mfma_f32_16x16x32_bf16 v[44:47], v[140:143], v[222:225], v[44:47]
	v_mfma_f32_16x16x32_bf16 v[36:39], v[172:175], v[222:225], v[36:39]
	v_mfma_f32_16x16x32_bf16 v[28:31], v[140:143], v[230:233], v[28:31]
	v_mfma_f32_16x16x32_bf16 v[20:23], v[172:175], v[230:233], v[20:23]
	v_mfma_f32_16x16x32_bf16 v[12:15], v[140:143], v[238:241], v[12:15]
	v_mfma_f32_16x16x32_bf16 v[4:7], v[172:175], v[238:241], v[4:7]
	v_mfma_f32_16x16x32_bf16 v[60:63], v[168:171], v[218:221], v[60:63]
	v_mfma_f32_16x16x32_bf16 v[52:55], v[176:179], v[218:221], v[52:55]
	v_mfma_f32_16x16x32_bf16 v[44:47], v[168:171], v[226:229], v[44:47]
	v_mfma_f32_16x16x32_bf16 v[36:39], v[176:179], v[226:229], v[36:39]
	v_mfma_f32_16x16x32_bf16 v[28:31], v[168:171], v[234:237], v[28:31]
	v_mfma_f32_16x16x32_bf16 v[20:23], v[176:179], v[234:237], v[20:23]
	v_mfma_f32_16x16x32_bf16 v[12:15], v[168:171], v[242:245], v[12:15]
	v_mfma_f32_16x16x32_bf16 v[4:7], v[176:179], v[242:245], v[4:7]
	v_mfma_f32_16x16x32_bf16 v[56:59], v[180:183], v[214:217], v[56:59]
	v_mfma_f32_16x16x32_bf16 v[48:51], v[188:191], v[214:217], v[48:51]
	v_mfma_f32_16x16x32_bf16 v[40:43], v[180:183], v[222:225], v[40:43]
	v_mfma_f32_16x16x32_bf16 v[32:35], v[188:191], v[222:225], v[32:35]
	v_mfma_f32_16x16x32_bf16 v[24:27], v[180:183], v[230:233], v[24:27]
	v_mfma_f32_16x16x32_bf16 v[16:19], v[188:191], v[230:233], v[16:19]
	v_mfma_f32_16x16x32_bf16 v[8:11], v[180:183], v[238:241], v[8:11]
	v_mfma_f32_16x16x32_bf16 v[0:3], v[188:191], v[238:241], v[0:3]
	v_mfma_f32_16x16x32_bf16 v[56:59], v[184:187], v[218:221], v[56:59]
	v_mfma_f32_16x16x32_bf16 v[48:51], v[210:213], v[218:221], v[48:51]
	v_mfma_f32_16x16x32_bf16 v[40:43], v[184:187], v[226:229], v[40:43]
	v_mfma_f32_16x16x32_bf16 v[32:35], v[210:213], v[226:229], v[32:35]
	v_mfma_f32_16x16x32_bf16 v[24:27], v[184:187], v[234:237], v[24:27]
	v_mfma_f32_16x16x32_bf16 v[16:19], v[210:213], v[234:237], v[16:19]
	v_mfma_f32_16x16x32_bf16 v[8:11], v[184:187], v[242:245], v[8:11]
	v_mfma_f32_16x16x32_bf16 v[0:3], v[210:213], v[242:245], v[0:3]
	s_setprio 0
	s_barrier
; #define PG8_STAGE(bufoff, gbase, voff) do { _Pragma("unroll") for (int _i = 0; _i < 2; ++_i) \
;         __builtin_amdgcn_global_load_lds((const unsigned*)((const char*)(gbase) + (voff)[_i]), (PG8_LAS unsigned*)(lds + (bufoff) + ldsw + _i * 8192), 16, 0, 0); } while (0)
; #define PG8_LDA(dst, b, h) do { _Pragma("unroll") for (int m = 0; m < 4; ++m) _Pragma("unroll") for (int k = 0; k < 2; ++k) dst[m][k] = *(const PG8_LAS bf16x8*)(lds + PG8_SA(b, h) + aoff + m * 2048 + k * 1024); } while (0)
; #define PG8_LDB(dst, b, h) do { _Pragma("unroll") for (int n = 0; n < 2; ++n) _Pragma("unroll") for (int k = 0; k < 2; ++k) dst[n][k] = *(const PG8_LAS bf16x8*)(lds + PG8_SB(b, h) + boff + n * 2048 + k * 1024); } while (0)
; #define PG8_MMA(ai, bj, At, Bt) do { __builtin_amdgcn_s_setprio(1); _Pragma("unroll") for (int m = 0; m < 4; ++m) _Pragma("unroll") for (int n = 0; n < 2; ++n) _Pragma("unroll") for (int k = 0; k < 2; ++k) \
;         acc[ai][bj][m][n] = __builtin_amdgcn_mfma_f32_16x16x32_bf16(Bt[n][k], At[m][k], acc[ai][bj][m][n], 0, 0, 0); __builtin_amdgcn_s_setprio(0); } while (0)
; #define PG8_WAIT_V(n) asm volatile("s_waitcnt vmcnt(" #n ")" ::: "memory")
; #define PG8_WAIT_L(n) asm volatile("s_waitcnt lgkmcnt(" #n ")" ::: "memory")
; #define PG8_BAR __builtin_amdgcn_s_barrier()
; #define PG8_SCHED __builtin_amdgcn_sched_barrier(0)
; template <class Epi, class Sched, bool ALIGN_EPI = false, bool SP2 = false>
; __device__ __forceinline__ void gemm_phase(PG8_LAS unsigned char* lds, const Gemm g, const Sched& S, const Epi& E) {
;     ...
;         for (int t = 0; t < nt; t += 2) {
;     ...
;             PG8_LDB(B0, 1, 0); PG8_LDB(B1, 1, 1); PG8_SCHED; PG8_LDA(At, 1, 0); PG8_STAGE(PG8_SA(0, 1), a2 + hstep, voffA);
;             PG8_WAIT_V(8); PG8_WAIT_L(0); PG8_BAR; PG8_MMA(0, 0, At, B0); PG8_MMA(0, 1, At, B1); PG8_BAR; PG8_SCHED;
;             PG8_LDA(At, 1, 1); PG8_STAGE(PG8_SB(1, 0), b3, voffB); PG8_STAGE(PG8_SB(1, 1), b3 + hstep, voffB); PG8_STAGE(PG8_SA(1, 0), a3, voffA);
;             PG8_WAIT_V(8); PG8_WAIT_L(0); PG8_BAR; PG8_MMA(1, 0, At, B0); PG8_MMA(1, 1, At, B1); PG8_BAR; PG8_SCHED;
	ds_read_b128 v[140:143], v254 offset:32768
	ds_read_b128 v[168:171], v254 offset:33792
	ds_read_b128 v[172:175], v254 offset:34816
	ds_read_b128 v[176:179], v254 offset:35840
	ds_read_b128 v[180:183], v254 offset:49152
	ds_read_b128 v[184:187], v254 offset:50176
	ds_read_b128 v[188:191], v254 offset:51200
	ds_read_b128 v[210:213], v254 offset:52224
	s_add_u32 s18, s18, 0x40000
	s_addc_u32 s19, s19, 0
	s_mov_b32 m0, s33
	ds_read_b128 v[214:217], v165 offset:32768
	ds_read_b128 v[218:221], v165 offset:33792
	ds_read_b128 v[222:225], v165 offset:34816
	ds_read_b128 v[226:229], v165 offset:35840
	ds_read_b128 v[230:233], v165 offset:36864
	ds_read_b128 v[234:237], v165 offset:37888
	ds_read_b128 v[238:241], v165 offset:38912
	ds_read_b128 v[242:245], v165 offset:39936
	global_load_lds_dwordx4 v134, s[18:19]
	s_mov_b32 m0, s34
	s_nop 0
	global_load_lds_dwordx4 v130, s[18:19]
	s_waitcnt vmcnt(8)
	s_waitcnt lgkmcnt(0)
	s_barrier
	s_setprio 1
	v_mfma_f32_16x16x32_bf16 v[124:127], v[140:143], v[214:217], v[124:127]
	v_mfma_f32_16x16x32_bf16 v[116:119], v[172:175], v[214:217], v[116:119]
	v_mfma_f32_16x16x32_bf16 v[108:111], v[140:143], v[222:225], v[108:111]
	v_mfma_f32_16x16x32_bf16 v[100:103], v[172:175], v[222:225], v[100:103]
	v_mfma_f32_16x16x32_bf16 v[92:95], v[140:143], v[230:233], v[92:95]
	v_mfma_f32_16x16x32_bf16 v[84:87], v[172:175], v[230:233], v[84:87]
	v_mfma_f32_16x16x32_bf16 v[76:79], v[140:143], v[238:241], v[76:79]
	v_mfma_f32_16x16x32_bf16 v[68:71], v[172:175], v[238:241], v[68:71]
	v_mfma_f32_16x16x32_bf16 v[124:127], v[168:171], v[218:221], v[124:127]
	v_mfma_f32_16x16x32_bf16 v[116:119], v[176:179], v[218:221], v[116:119]
	v_mfma_f32_16x16x32_bf16 v[108:111], v[168:171], v[226:229], v[108:111]
	v_mfma_f32_16x16x32_bf16 v[100:103], v[176:179], v[226:229], v[100:103]
	v_mfma_f32_16x16x32_bf16 v[92:95], v[168:171], v[234:237], v[92:95]
	v_mfma_f32_16x16x32_bf16 v[84:87], v[176:179], v[234:237], v[84:87]
	v_mfma_f32_16x16x32_bf16 v[76:79], v[168:171], v[242:245], v[76:79]
	v_mfma_f32_16x16x32_bf16 v[68:71], v[176:179], v[242:245], v[68:71]
	v_mfma_f32_16x16x32_bf16 v[120:123], v[180:183], v[214:217], v[120:123]
	v_mfma_f32_16x16x32_bf16 v[112:115], v[188:191], v[214:217], v[112:115]
	v_mfma_f32_16x16x32_bf16 v[104:107], v[180:183], v[222:225], v[104:107]
	v_mfma_f32_16x16x32_bf16 v[96:99], v[188:191], v[222:225], v[96:99]
	v_mfma_f32_16x16x32_bf16 v[88:91], v[180:183], v[230:233], v[88:91]
	v_mfma_f32_16x16x32_bf16 v[80:83], v[188:191], v[230:233], v[80:83]
	v_mfma_f32_16x16x32_bf16 v[72:75], v[180:183], v[238:241], v[72:75]
	v_mfma_f32_16x16x32_bf16 v[64:67], v[188:191], v[238:241], v[64:67]
	v_mfma_f32_16x16x32_bf16 v[120:123], v[184:187], v[218:221], v[120:123]
	v_mfma_f32_16x16x32_bf16 v[112:115], v[210:213], v[218:221], v[112:115]
	v_mfma_f32_16x16x32_bf16 v[104:107], v[184:187], v[226:229], v[104:107]
	v_mfma_f32_16x16x32_bf16 v[96:99], v[210:213], v[226:229], v[96:99]
	v_mfma_f32_16x16x32_bf16 v[88:91], v[184:187], v[234:237], v[88:91]
	v_mfma_f32_16x16x32_bf16 v[80:83], v[210:213], v[234:237], v[80:83]
	v_mfma_f32_16x16x32_bf16 v[72:75], v[184:187], v[242:245], v[72:75]
	v_mfma_f32_16x16x32_bf16 v[64:67], v[210:213], v[242:245], v[64:67]
	s_setprio 0
	s_barrier
	s_mov_b32 m0, s37
	s_add_u32 s16, s16, 0x40080
	s_addc_u32 s17, s17, 0
	ds_read_b128 v[214:217], v165 offset:49152
	ds_read_b128 v[218:221], v165 offset:50176
	ds_read_b128 v[222:225], v165 offset:51200
	ds_read_b128 v[226:229], v165 offset:52224
	ds_read_b128 v[230:233], v165 offset:53248
	ds_read_b128 v[234:237], v165 offset:54272
	ds_read_b128 v[238:241], v165 offset:55296
	ds_read_b128 v[242:245], v165 offset:56320
	s_add_u32 s98, s16, 0xfffc0000
	s_addc_u32 s99, s17, -1
	global_load_lds_dwordx4 v132, s[98:99]
	s_mov_b32 m0, s38
	s_nop 0
	global_load_lds_dwordx4 v128, s[98:99]
	s_mov_b32 m0, s41
	s_nop 0
	global_load_lds_dwordx4 v132, s[16:17]
	s_mov_b32 m0, s42
	s_nop 0
	global_load_lds_dwordx4 v128, s[16:17]
	s_mov_b32 m0, s39
	s_nop 0
	s_add_u32 s100, s18, 0xfffc0080
	s_addc_u32 s101, s19, -1
	global_load_lds_dwordx4 v134, s[100:101]
	s_mov_b32 m0, s40
	s_nop 0
	global_load_lds_dwordx4 v130, s[100:101]
	s_waitcnt vmcnt(8)
	s_waitcnt lgkmcnt(0)
	s_barrier
	s_setprio 1
	v_mfma_f32_16x16x32_bf16 v[60:63], v[140:143], v[214:217], v[60:63]
	v_mfma_f32_16x16x32_bf16 v[52:55], v[172:175], v[214:217], v[52:55]
	v_mfma_f32_16x16x32_bf16 v[44:47], v[140:143], v[222:225], v[44:47]
	v_mfma_f32_16x16x32_bf16 v[36:39], v[172:175], v[222:225], v[36:39]
	v_mfma_f32_16x16x32_bf16 v[28:31], v[140:143], v[230:233], v[28:31]
	v_mfma_f32_16x16x32_bf16 v[20:23], v[172:175], v[230:233], v[20:23]
	v_mfma_f32_16x16x32_bf16 v[12:15], v[140:143], v[238:241], v[12:15]
	v_mfma_f32_16x16x32_bf16 v[4:7], v[172:175], v[238:241], v[4:7]
	v_mfma_f32_16x16x32_bf16 v[60:63], v[168:171], v[218:221], v[60:63]
	v_mfma_f32_16x16x32_bf16 v[52:55], v[176:179], v[218:221], v[52:55]
	v_mfma_f32_16x16x32_bf16 v[44:47], v[168:171], v[226:229], v[44:47]
	v_mfma_f32_16x16x32_bf16 v[36:39], v[176:179], v[226:229], v[36:39]
	v_mfma_f32_16x16x32_bf16 v[28:31], v[168:171], v[234:237], v[28:31]
	v_mfma_f32_16x16x32_bf16 v[20:23], v[176:179], v[234:237], v[20:23]
	v_mfma_f32_16x16x32_bf16 v[12:15], v[168:171], v[242:245], v[12:15]
	v_mfma_f32_16x16x32_bf16 v[4:7], v[176:179], v[242:245], v[4:7]
	v_mfma_f32_16x16x32_bf16 v[56:59], v[180:183], v[214:217], v[56:59]
	v_mfma_f32_16x16x32_bf16 v[48:51], v[188:191], v[214:217], v[48:51]
	v_mfma_f32_16x16x32_bf16 v[40:43], v[180:183], v[222:225], v[40:43]
	v_mfma_f32_16x16x32_bf16 v[32:35], v[188:191], v[222:225], v[32:35]
	v_mfma_f32_16x16x32_bf16 v[24:27], v[180:183], v[230:233], v[24:27]
	v_mfma_f32_16x16x32_bf16 v[16:19], v[188:191], v[230:233], v[16:19]
	v_mfma_f32_16x16x32_bf16 v[8:11], v[180:183], v[238:241], v[8:11]
	v_mfma_f32_16x16x32_bf16 v[0:3], v[188:191], v[238:241], v[0:3]
	v_mfma_f32_16x16x32_bf16 v[56:59], v[184:187], v[218:221], v[56:59]
	v_mfma_f32_16x16x32_bf16 v[48:51], v[210:213], v[218:221], v[48:51]
	v_mfma_f32_16x16x32_bf16 v[40:43], v[184:187], v[226:229], v[40:43]
	v_mfma_f32_16x16x32_bf16 v[32:35], v[210:213], v[226:229], v[32:35]
	v_mfma_f32_16x16x32_bf16 v[24:27], v[184:187], v[234:237], v[24:27]
	v_mfma_f32_16x16x32_bf16 v[16:19], v[210:213], v[234:237], v[16:19]
	v_mfma_f32_16x16x32_bf16 v[8:11], v[184:187], v[242:245], v[8:11]
	v_mfma_f32_16x16x32_bf16 v[0:3], v[210:213], v[242:245], v[0:3]
	s_setprio 0
	s_barrier
	s_add_i32 s53, s53, 2
	s_add_u32 s14, s14, 0x100
	s_addc_u32 s15, s15, 0
	s_add_u32 s51, s51, 0x100
	s_addc_u32 s52, s52, 0
	s_cmp_gt_u32 s53, 13
	s_cbranch_scc0 .LBB0_446
	s_and_b64 vcc, exec, s[2:3]
	s_cbranch_vccz .LBB0_449
	s_barrier

; #define PG8_STAGE(bufoff, gbase, voff) do { _Pragma("unroll") for (int _i = 0; _i < 2; ++_i) \
;         __builtin_amdgcn_global_load_lds((const unsigned*)((const char*)(gbase) + (voff)[_i]), (PG8_LAS unsigned*)(lds + (bufoff) + ldsw + _i * 8192), 16, 0, 0); } while (0)
; #define PG8_LDA(dst, b, h) do { _Pragma("unroll") for (int m = 0; m < 4; ++m) _Pragma("unroll") for (int k = 0; k < 2; ++k) dst[m][k] = *(const PG8_LAS bf16x8*)(lds + PG8_SA(b, h) + aoff + m * 2048 + k * 1024); } while (0)
; #define PG8_LDB(dst, b, h) do { _Pragma("unroll") for (int n = 0; n < 2; ++n) _Pragma("unroll") for (int k = 0; k < 2; ++k) dst[n][k] = *(const PG8_LAS bf16x8*)(lds + PG8_SB(b, h) + boff + n * 2048 + k * 1024); } while (0)
; #define PG8_MMA(ai, bj, At, Bt) do { __builtin_amdgcn_s_setprio(1); _Pragma("unroll") for (int m = 0; m < 4; ++m) _Pragma("unroll") for (int n = 0; n < 2; ++n) _Pragma("unroll") for (int k = 0; k < 2; ++k) \
;         acc[ai][bj][m][n] = __builtin_amdgcn_mfma_f32_16x16x32_bf16(Bt[n][k], At[m][k], acc[ai][bj][m][n], 0, 0, 0); __builtin_amdgcn_s_setprio(0); } while (0)
; #define PG8_WAIT_V(n) asm volatile("s_waitcnt vmcnt(" #n ")" ::: "memory")
; #define PG8_WAIT_L(n) asm volatile("s_waitcnt lgkmcnt(" #n ")" ::: "memory")
; #define PG8_BAR __builtin_amdgcn_s_barrier()
; #define PG8_SCHED __builtin_amdgcn_sched_barrier(0)
; template <class Epi, class Sched, bool ALIGN_EPI = false, bool SP2 = false>
; __device__ __forceinline__ void gemm_phase(PG8_LAS unsigned char* lds, const Gemm g, const Sched& S, const Epi& E) {
;     ...
;             PG8_LDB(B0, 0, 0); PG8_LDB(B1, 0, 1); PG8_SCHED; PG8_LDA(At, 0, 0); PG8_STAGE(PG8_SA(1, 1), a1 + hstep, voffA);
;             PG8_WAIT_V(8); PG8_WAIT_L(0); PG8_BAR; PG8_MMA(0, 0, At, B0); PG8_MMA(0, 1, At, B1); PG8_BAR; PG8_SCHED;
;             PG8_LDA(At, 0, 1); PG8_STAGE(PG8_SB(0, 0), b2, voffB); PG8_STAGE(PG8_SB(0, 1), b2 + hstep, voffB); PG8_STAGE(PG8_SA(0, 0), a2, voffA);
;             PG8_WAIT_V(8); PG8_WAIT_L(0); PG8_BAR; PG8_MMA(1, 0, At, B0); PG8_MMA(1, 1, At, B1); PG8_BAR; PG8_SCHED;
.Ldn_peel:
	ds_read_b128 v[128:131], v254
	ds_read_b128 v[132:135], v254 offset:1024
	ds_read_b128 v[136:139], v254 offset:2048
	ds_read_b128 v[140:143], v254 offset:3072
	ds_read_b128 v[174:177], v254 offset:16384
	ds_read_b128 v[184:187], v254 offset:17408
	ds_read_b128 v[188:191], v254 offset:18432
	ds_read_b128 v[210:213], v254 offset:19456
	s_add_u32 s2, s0, 0x100
	s_addc_u32 s3, s1, 0
	s_cmp_eq_u32 s13, 40
	s_cselect_b32 s7, s27, s3
	s_cselect_b32 s6, s26, s2
	s_cselect_b32 s5, s37, s11
	s_cselect_b32 s4, s36, s10
	s_add_i32 m0, s29, 0xc000
	ds_read_b128 v[214:217], v181
	ds_read_b128 v[218:221], v181 offset:1024
	ds_read_b128 v[222:225], v181 offset:2048
	ds_read_b128 v[226:229], v181 offset:3072
	ds_read_b128 v[230:233], v181 offset:4096
	ds_read_b128 v[234:237], v181 offset:5120
	ds_read_b128 v[238:241], v181 offset:6144
	ds_read_b128 v[242:245], v181 offset:7168
	global_load_lds_dwordx4 v170, s[0:1]
	s_add_i32 m0, s29, 0xe000
	s_nop 0
	global_load_lds_dwordx4 v172, s[0:1]
	s_waitcnt vmcnt(8)
	s_waitcnt lgkmcnt(0)
	s_barrier
	s_setprio 1
	v_mfma_f32_16x16x32_bf16 v[124:127], v[128:131], v[214:217], 0
	v_mfma_f32_16x16x32_bf16 v[120:123], v[136:139], v[214:217], 0
	v_mfma_f32_16x16x32_bf16 v[108:111], v[128:131], v[222:225], 0
	v_mfma_f32_16x16x32_bf16 v[104:107], v[136:139], v[222:225], 0
	v_mfma_f32_16x16x32_bf16 v[92:95], v[128:131], v[230:233], 0
	v_mfma_f32_16x16x32_bf16 v[88:91], v[136:139], v[230:233], 0
	v_mfma_f32_16x16x32_bf16 v[76:79], v[128:131], v[238:241], 0
	v_mfma_f32_16x16x32_bf16 v[72:75], v[136:139], v[238:241], 0
	v_mfma_f32_16x16x32_bf16 v[124:127], v[132:135], v[218:221], v[124:127]
	v_mfma_f32_16x16x32_bf16 v[120:123], v[140:143], v[218:221], v[120:123]
	v_mfma_f32_16x16x32_bf16 v[108:111], v[132:135], v[226:229], v[108:111]
	v_mfma_f32_16x16x32_bf16 v[104:107], v[140:143], v[226:229], v[104:107]
	v_mfma_f32_16x16x32_bf16 v[92:95], v[132:135], v[234:237], v[92:95]
	v_mfma_f32_16x16x32_bf16 v[88:91], v[140:143], v[234:237], v[88:91]
	v_mfma_f32_16x16x32_bf16 v[76:79], v[132:135], v[242:245], v[76:79]
	v_mfma_f32_16x16x32_bf16 v[72:75], v[140:143], v[242:245], v[72:75]
	v_mfma_f32_16x16x32_bf16 v[116:119], v[174:177], v[214:217], 0
	v_mfma_f32_16x16x32_bf16 v[112:115], v[188:191], v[214:217], 0
	v_mfma_f32_16x16x32_bf16 v[100:103], v[174:177], v[222:225], 0
	v_mfma_f32_16x16x32_bf16 v[96:99], v[188:191], v[222:225], 0
	v_mfma_f32_16x16x32_bf16 v[84:87], v[174:177], v[230:233], 0
	v_mfma_f32_16x16x32_bf16 v[80:83], v[188:191], v[230:233], 0
	v_mfma_f32_16x16x32_bf16 v[68:71], v[174:177], v[238:241], 0
	v_mfma_f32_16x16x32_bf16 v[64:67], v[188:191], v[238:241], 0
	v_mfma_f32_16x16x32_bf16 v[116:119], v[184:187], v[218:221], v[116:119]
	v_mfma_f32_16x16x32_bf16 v[112:115], v[210:213], v[218:221], v[112:115]
	v_mfma_f32_16x16x32_bf16 v[100:103], v[184:187], v[226:229], v[100:103]
	v_mfma_f32_16x16x32_bf16 v[96:99], v[210:213], v[226:229], v[96:99]
	v_mfma_f32_16x16x32_bf16 v[84:87], v[184:187], v[234:237], v[84:87]
	v_mfma_f32_16x16x32_bf16 v[80:83], v[210:213], v[234:237], v[80:83]
	v_mfma_f32_16x16x32_bf16 v[68:71], v[184:187], v[242:245], v[68:71]
	v_mfma_f32_16x16x32_bf16 v[64:67], v[210:213], v[242:245], v[64:67]
	s_setprio 0
	s_barrier
	s_mov_b32 m0, s35
	s_add_u32 s0, s4, 0xb0000
	s_addc_u32 s1, s5, 0
	ds_read_b128 v[214:217], v181 offset:16384
	ds_read_b128 v[218:221], v181 offset:17408
	ds_read_b128 v[222:225], v181 offset:18432
	ds_read_b128 v[226:229], v181 offset:19456
	ds_read_b128 v[230:233], v181 offset:20480
	ds_read_b128 v[234:237], v181 offset:21504
	ds_read_b128 v[238:241], v181 offset:22528
	ds_read_b128 v[242:245], v181 offset:23552
	global_load_lds_dwordx4 v166, s[4:5]
	s_mov_b32 m0, s38
	s_nop 0
	global_load_lds_dwordx4 v162, s[4:5]
	s_mov_b32 m0, s39
	s_nop 0
	global_load_lds_dwordx4 v166, s[0:1]
	s_mov_b32 m0, s40
	s_nop 0
	global_load_lds_dwordx4 v162, s[0:1]
	s_mov_b32 m0, s29
	s_nop 0
	global_load_lds_dwordx4 v168, s[6:7]
	s_mov_b32 m0, s41
	s_nop 0
	global_load_lds_dwordx4 v164, s[6:7]
	s_waitcnt vmcnt(8)
	s_waitcnt lgkmcnt(0)
	s_barrier
	s_setprio 1
	v_mfma_f32_16x16x32_bf16 v[60:63], v[128:131], v[214:217], 0
	v_mfma_f32_16x16x32_bf16 v[56:59], v[136:139], v[214:217], 0
	v_mfma_f32_16x16x32_bf16 v[44:47], v[128:131], v[222:225], 0
	v_mfma_f32_16x16x32_bf16 v[40:43], v[136:139], v[222:225], 0
	v_mfma_f32_16x16x32_bf16 v[28:31], v[128:131], v[230:233], 0
	v_mfma_f32_16x16x32_bf16 v[24:27], v[136:139], v[230:233], 0
	v_mfma_f32_16x16x32_bf16 v[12:15], v[128:131], v[238:241], 0
	v_mfma_f32_16x16x32_bf16 v[8:11], v[136:139], v[238:241], 0
	v_mfma_f32_16x16x32_bf16 v[60:63], v[132:135], v[218:221], v[60:63]
	v_mfma_f32_16x16x32_bf16 v[56:59], v[140:143], v[218:221], v[56:59]
	v_mfma_f32_16x16x32_bf16 v[44:47], v[132:135], v[226:229], v[44:47]
	v_mfma_f32_16x16x32_bf16 v[40:43], v[140:143], v[226:229], v[40:43]
	v_mfma_f32_16x16x32_bf16 v[28:31], v[132:135], v[234:237], v[28:31]
	v_mfma_f32_16x16x32_bf16 v[24:27], v[140:143], v[234:237], v[24:27]
	v_mfma_f32_16x16x32_bf16 v[12:15], v[132:135], v[242:245], v[12:15]
	v_mfma_f32_16x16x32_bf16 v[8:11], v[140:143], v[242:245], v[8:11]
	v_mfma_f32_16x16x32_bf16 v[52:55], v[174:177], v[214:217], 0
	v_mfma_f32_16x16x32_bf16 v[48:51], v[188:191], v[214:217], 0
	v_mfma_f32_16x16x32_bf16 v[36:39], v[174:177], v[222:225], 0
	v_mfma_f32_16x16x32_bf16 v[32:35], v[188:191], v[222:225], 0
	v_mfma_f32_16x16x32_bf16 v[20:23], v[174:177], v[230:233], 0
	v_mfma_f32_16x16x32_bf16 v[16:19], v[188:191], v[230:233], 0
	v_mfma_f32_16x16x32_bf16 v[4:7], v[174:177], v[238:241], 0
	v_mfma_f32_16x16x32_bf16 v[0:3], v[188:191], v[238:241], 0
	v_mfma_f32_16x16x32_bf16 v[52:55], v[184:187], v[218:221], v[52:55]
	v_mfma_f32_16x16x32_bf16 v[48:51], v[210:213], v[218:221], v[48:51]
	v_mfma_f32_16x16x32_bf16 v[36:39], v[184:187], v[226:229], v[36:39]
	v_mfma_f32_16x16x32_bf16 v[32:35], v[210:213], v[226:229], v[32:35]
	v_mfma_f32_16x16x32_bf16 v[20:23], v[184:187], v[234:237], v[20:23]
	v_mfma_f32_16x16x32_bf16 v[16:19], v[210:213], v[234:237], v[16:19]
	v_mfma_f32_16x16x32_bf16 v[4:7], v[184:187], v[242:245], v[4:7]
	v_mfma_f32_16x16x32_bf16 v[0:3], v[210:213], v[242:245], v[0:3]
	s_setprio 0
	s_barrier
; #define PG8_STAGE(bufoff, gbase, voff) do { _Pragma("unroll") for (int _i = 0; _i < 2; ++_i) \
;         __builtin_amdgcn_global_load_lds((const unsigned*)((const char*)(gbase) + (voff)[_i]), (PG8_LAS unsigned*)(lds + (bufoff) + ldsw + _i * 8192), 16, 0, 0); } while (0)
; #define PG8_LDA(dst, b, h) do { _Pragma("unroll") for (int m = 0; m < 4; ++m) _Pragma("unroll") for (int k = 0; k < 2; ++k) dst[m][k] = *(const PG8_LAS bf16x8*)(lds + PG8_SA(b, h) + aoff + m * 2048 + k * 1024); } while (0)
; #define PG8_LDB(dst, b, h) do { _Pragma("unroll") for (int n = 0; n < 2; ++n) _Pragma("unroll") for (int k = 0; k < 2; ++k) dst[n][k] = *(const PG8_LAS bf16x8*)(lds + PG8_SB(b, h) + boff + n * 2048 + k * 1024); } while (0)
; #define PG8_MMA(ai, bj, At, Bt) do { __builtin_amdgcn_s_setprio(1); _Pragma("unroll") for (int m = 0; m < 4; ++m) _Pragma("unroll") for (int n = 0; n < 2; ++n) _Pragma("unroll") for (int k = 0; k < 2; ++k) \
;         acc[ai][bj][m][n] = __builtin_amdgcn_mfma_f32_16x16x32_bf16(Bt[n][k], At[m][k], acc[ai][bj][m][n], 0, 0, 0); __builtin_amdgcn_s_setprio(0); } while (0)
; #define PG8_WAIT_V(n) asm volatile("s_waitcnt vmcnt(" #n ")" ::: "memory")
; #define PG8_WAIT_L(n) asm volatile("s_waitcnt lgkmcnt(" #n ")" ::: "memory")
; #define PG8_BAR __builtin_amdgcn_s_barrier()
; #define PG8_SCHED __builtin_amdgcn_sched_barrier(0)
; template <class Epi, class Sched, bool ALIGN_EPI = false, bool SP2 = false>
; __device__ __forceinline__ void gemm_phase(PG8_LAS unsigned char* lds, const Gemm g, const Sched& S, const Epi& E) {
;     ...
;         for (int t = 0; t < nt; t += 2) {
;     ...
;             PG8_LDB(B0, 1, 0); PG8_LDB(B1, 1, 1); PG8_SCHED; PG8_LDA(At, 1, 0); PG8_STAGE(PG8_SA(0, 1), a2 + hstep, voffA);
;             PG8_WAIT_V(8); PG8_WAIT_L(0); PG8_BAR; PG8_MMA(0, 0, At, B0); PG8_MMA(0, 1, At, B1); PG8_BAR; PG8_SCHED;
;             PG8_LDA(At, 1, 1); PG8_STAGE(PG8_SB(1, 0), b3, voffB); PG8_STAGE(PG8_SB(1, 1), b3 + hstep, voffB); PG8_STAGE(PG8_SA(1, 0), a3, voffA);
;             PG8_WAIT_V(8); PG8_WAIT_L(0); PG8_BAR; PG8_MMA(1, 0, At, B0); PG8_MMA(1, 1, At, B1); PG8_BAR; PG8_SCHED;
	ds_read_b128 v[128:131], v254 offset:32768
	ds_read_b128 v[132:135], v254 offset:33792
	ds_read_b128 v[136:139], v254 offset:34816
	ds_read_b128 v[140:143], v254 offset:35840
	ds_read_b128 v[174:177], v254 offset:49152
	ds_read_b128 v[184:187], v254 offset:50176
	ds_read_b128 v[188:191], v254 offset:51200
	ds_read_b128 v[210:213], v254 offset:52224
	s_add_u32 s0, s6, 0xb0000
	s_addc_u32 s1, s7, 0
	s_mov_b32 m0, s42
	ds_read_b128 v[214:217], v181 offset:32768
	ds_read_b128 v[218:221], v181 offset:33792
	ds_read_b128 v[222:225], v181 offset:34816
	ds_read_b128 v[226:229], v181 offset:35840
	ds_read_b128 v[230:233], v181 offset:36864
	ds_read_b128 v[234:237], v181 offset:37888
	ds_read_b128 v[238:241], v181 offset:38912
	ds_read_b128 v[242:245], v181 offset:39936
	global_load_lds_dwordx4 v168, s[0:1]
	s_mov_b32 m0, s43
	s_nop 0
	global_load_lds_dwordx4 v164, s[0:1]
	s_waitcnt vmcnt(8)
	s_waitcnt lgkmcnt(0)
	s_barrier
	s_setprio 1
	v_mfma_f32_16x16x32_bf16 v[124:127], v[128:131], v[214:217], v[124:127]
	v_mfma_f32_16x16x32_bf16 v[120:123], v[136:139], v[214:217], v[120:123]
	v_mfma_f32_16x16x32_bf16 v[108:111], v[128:131], v[222:225], v[108:111]
	v_mfma_f32_16x16x32_bf16 v[104:107], v[136:139], v[222:225], v[104:107]
	v_mfma_f32_16x16x32_bf16 v[92:95], v[128:131], v[230:233], v[92:95]
	v_mfma_f32_16x16x32_bf16 v[88:91], v[136:139], v[230:233], v[88:91]
	v_mfma_f32_16x16x32_bf16 v[76:79], v[128:131], v[238:241], v[76:79]
	v_mfma_f32_16x16x32_bf16 v[72:75], v[136:139], v[238:241], v[72:75]
	v_mfma_f32_16x16x32_bf16 v[124:127], v[132:135], v[218:221], v[124:127]
	v_mfma_f32_16x16x32_bf16 v[120:123], v[140:143], v[218:221], v[120:123]
	v_mfma_f32_16x16x32_bf16 v[108:111], v[132:135], v[226:229], v[108:111]
	v_mfma_f32_16x16x32_bf16 v[104:107], v[140:143], v[226:229], v[104:107]
	v_mfma_f32_16x16x32_bf16 v[92:95], v[132:135], v[234:237], v[92:95]
	v_mfma_f32_16x16x32_bf16 v[88:91], v[140:143], v[234:237], v[88:91]
	v_mfma_f32_16x16x32_bf16 v[76:79], v[132:135], v[242:245], v[76:79]
	v_mfma_f32_16x16x32_bf16 v[72:75], v[140:143], v[242:245], v[72:75]
	v_mfma_f32_16x16x32_bf16 v[116:119], v[174:177], v[214:217], v[116:119]
	v_mfma_f32_16x16x32_bf16 v[112:115], v[188:191], v[214:217], v[112:115]
	v_mfma_f32_16x16x32_bf16 v[100:103], v[174:177], v[222:225], v[100:103]
	v_mfma_f32_16x16x32_bf16 v[96:99], v[188:191], v[222:225], v[96:99]
	v_mfma_f32_16x16x32_bf16 v[84:87], v[174:177], v[230:233], v[84:87]
	v_mfma_f32_16x16x32_bf16 v[80:83], v[188:191], v[230:233], v[80:83]
	v_mfma_f32_16x16x32_bf16 v[68:71], v[174:177], v[238:241], v[68:71]
	v_mfma_f32_16x16x32_bf16 v[64:67], v[188:191], v[238:241], v[64:67]
	v_mfma_f32_16x16x32_bf16 v[116:119], v[184:187], v[218:221], v[116:119]
	v_mfma_f32_16x16x32_bf16 v[112:115], v[210:213], v[218:221], v[112:115]
	v_mfma_f32_16x16x32_bf16 v[100:103], v[184:187], v[226:229], v[100:103]
	v_mfma_f32_16x16x32_bf16 v[96:99], v[210:213], v[226:229], v[96:99]
	v_mfma_f32_16x16x32_bf16 v[84:87], v[184:187], v[234:237], v[84:87]
	v_mfma_f32_16x16x32_bf16 v[80:83], v[210:213], v[234:237], v[80:83]
	v_mfma_f32_16x16x32_bf16 v[68:71], v[184:187], v[242:245], v[68:71]
	v_mfma_f32_16x16x32_bf16 v[64:67], v[210:213], v[242:245], v[64:67]
	s_setprio 0
	s_barrier
	s_mov_b32 m0, s47
	s_add_u32 s0, s4, 0xb0080
	s_addc_u32 s1, s5, 0
	ds_read_b128 v[214:217], v181 offset:49152
	ds_read_b128 v[218:221], v181 offset:50176
	ds_read_b128 v[222:225], v181 offset:51200
	ds_read_b128 v[226:229], v181 offset:52224
	ds_read_b128 v[230:233], v181 offset:53248
	ds_read_b128 v[234:237], v181 offset:54272
	ds_read_b128 v[238:241], v181 offset:55296
	ds_read_b128 v[242:245], v181 offset:56320
	s_add_u32 s98, s4, 0x80
	s_addc_u32 s99, s5, 0
	global_load_lds_dwordx4 v166, s[98:99]
	s_mov_b32 m0, s48
	s_nop 0
	global_load_lds_dwordx4 v162, s[98:99]
	s_mov_b32 m0, s51
	s_nop 0
	global_load_lds_dwordx4 v166, s[0:1]
	s_mov_b32 m0, s52
	s_nop 0
	global_load_lds_dwordx4 v162, s[0:1]
	s_mov_b32 m0, s49
	s_nop 0
	s_add_u32 s100, s6, 0x80
	s_addc_u32 s101, s7, 0
	global_load_lds_dwordx4 v168, s[100:101]
	s_mov_b32 m0, s50
	s_nop 0
	global_load_lds_dwordx4 v164, s[100:101]
	s_waitcnt vmcnt(8)
	s_waitcnt lgkmcnt(0)
	s_barrier
	s_setprio 1
	v_mfma_f32_16x16x32_bf16 v[60:63], v[128:131], v[214:217], v[60:63]
	v_mfma_f32_16x16x32_bf16 v[56:59], v[136:139], v[214:217], v[56:59]
	v_mfma_f32_16x16x32_bf16 v[44:47], v[128:131], v[222:225], v[44:47]
	v_mfma_f32_16x16x32_bf16 v[40:43], v[136:139], v[222:225], v[40:43]
	v_mfma_f32_16x16x32_bf16 v[28:31], v[128:131], v[230:233], v[28:31]
	v_mfma_f32_16x16x32_bf16 v[24:27], v[136:139], v[230:233], v[24:27]
	v_mfma_f32_16x16x32_bf16 v[12:15], v[128:131], v[238:241], v[12:15]
	v_mfma_f32_16x16x32_bf16 v[8:11], v[136:139], v[238:241], v[8:11]
	v_mfma_f32_16x16x32_bf16 v[60:63], v[132:135], v[218:221], v[60:63]
	v_mfma_f32_16x16x32_bf16 v[56:59], v[140:143], v[218:221], v[56:59]
	v_mfma_f32_16x16x32_bf16 v[44:47], v[132:135], v[226:229], v[44:47]
	v_mfma_f32_16x16x32_bf16 v[40:43], v[140:143], v[226:229], v[40:43]
	v_mfma_f32_16x16x32_bf16 v[28:31], v[132:135], v[234:237], v[28:31]
	v_mfma_f32_16x16x32_bf16 v[24:27], v[140:143], v[234:237], v[24:27]
	v_mfma_f32_16x16x32_bf16 v[12:15], v[132:135], v[242:245], v[12:15]
	v_mfma_f32_16x16x32_bf16 v[8:11], v[140:143], v[242:245], v[8:11]
	v_mfma_f32_16x16x32_bf16 v[52:55], v[174:177], v[214:217], v[52:55]
	v_mfma_f32_16x16x32_bf16 v[48:51], v[188:191], v[214:217], v[48:51]
	v_mfma_f32_16x16x32_bf16 v[36:39], v[174:177], v[222:225], v[36:39]
	v_mfma_f32_16x16x32_bf16 v[32:35], v[188:191], v[222:225], v[32:35]
	v_mfma_f32_16x16x32_bf16 v[20:23], v[174:177], v[230:233], v[20:23]
	v_mfma_f32_16x16x32_bf16 v[16:19], v[188:191], v[230:233], v[16:19]
	v_mfma_f32_16x16x32_bf16 v[4:7], v[174:177], v[238:241], v[4:7]
	v_mfma_f32_16x16x32_bf16 v[0:3], v[188:191], v[238:241], v[0:3]
	v_mfma_f32_16x16x32_bf16 v[52:55], v[184:187], v[218:221], v[52:55]
	v_mfma_f32_16x16x32_bf16 v[48:51], v[210:213], v[218:221], v[48:51]
	v_mfma_f32_16x16x32_bf16 v[36:39], v[184:187], v[226:229], v[36:39]
	v_mfma_f32_16x16x32_bf16 v[32:35], v[210:213], v[226:229], v[32:35]
	v_mfma_f32_16x16x32_bf16 v[20:23], v[184:187], v[234:237], v[20:23]
	v_mfma_f32_16x16x32_bf16 v[16:19], v[210:213], v[234:237], v[16:19]
	v_mfma_f32_16x16x32_bf16 v[4:7], v[184:187], v[242:245], v[4:7]
	v_mfma_f32_16x16x32_bf16 v[0:3], v[210:213], v[242:245], v[0:3]
	s_setprio 0
	s_barrier
	s_add_i32 s13, s13, 2
	s_add_u32 s10, s10, 0x100
	s_addc_u32 s11, s11, 0
	s_cmp_gt_u32 s13, 41
	s_mov_b64 s[0:1], s[2:3]
; #define PG8_STAGE(bufoff, gbase, voff) do { _Pragma("unroll") for (int _i = 0; _i < 2; ++_i) \
;         __builtin_amdgcn_global_load_lds((const unsigned*)((const char*)(gbase) + (voff)[_i]), (PG8_LAS unsigned*)(lds + (bufoff) + ldsw + _i * 8192), 16, 0, 0); } while (0)
; #define PG8_LDA(dst, b, h) do { _Pragma("unroll") for (int m = 0; m < 4; ++m) _Pragma("unroll") for (int k = 0; k < 2; ++k) dst[m][k] = *(const PG8_LAS bf16x8*)(lds + PG8_SA(b, h) + aoff + m * 2048 + k * 1024); } while (0)
; #define PG8_LDB(dst, b, h) do { _Pragma("unroll") for (int n = 0; n < 2; ++n) _Pragma("unroll") for (int k = 0; k < 2; ++k) dst[n][k] = *(const PG8_LAS bf16x8*)(lds + PG8_SB(b, h) + boff + n * 2048 + k * 1024); } while (0)
; #define PG8_MMA(ai, bj, At, Bt) do { __builtin_amdgcn_s_setprio(1); _Pragma("unroll") for (int m = 0; m < 4; ++m) _Pragma("unroll") for (int n = 0; n < 2; ++n) _Pragma("unroll") for (int k = 0; k < 2; ++k) \
;         acc[ai][bj][m][n] = __builtin_amdgcn_mfma_f32_16x16x32_bf16(Bt[n][k], At[m][k], acc[ai][bj][m][n], 0, 0, 0); __builtin_amdgcn_s_setprio(0); } while (0)
; #define PG8_WAIT_V(n) asm volatile("s_waitcnt vmcnt(" #n ")" ::: "memory")
; #define PG8_WAIT_L(n) asm volatile("s_waitcnt lgkmcnt(" #n ")" ::: "memory")
; #define PG8_BAR __builtin_amdgcn_s_barrier()
; #define PG8_SCHED __builtin_amdgcn_sched_barrier(0)
; template <class Epi, class Sched, bool ALIGN_EPI = false, bool SP2 = false>
; __device__ __forceinline__ void gemm_phase(PG8_LAS unsigned char* lds, const Gemm g, const Sched& S, const Epi& E) {
;     ...
;             PG8_LDB(B0, 0, 0); PG8_LDB(B1, 0, 1); PG8_SCHED; PG8_LDA(At, 0, 0); PG8_STAGE(PG8_SA(1, 1), a1 + hstep, voffA);
;             PG8_WAIT_V(8); PG8_WAIT_L(0); PG8_BAR; PG8_MMA(0, 0, At, B0); PG8_MMA(0, 1, At, B1); PG8_BAR; PG8_SCHED;
;             PG8_LDA(At, 0, 1); PG8_STAGE(PG8_SB(0, 0), b2, voffB); PG8_STAGE(PG8_SB(0, 1), b2 + hstep, voffB); PG8_STAGE(PG8_SA(0, 0), a2, voffA);
;             PG8_WAIT_V(8); PG8_WAIT_L(0); PG8_BAR; PG8_MMA(1, 0, At, B0); PG8_MMA(1, 1, At, B1); PG8_BAR; PG8_SCHED;
.LBB0_545:
	ds_read_b128 v[128:131], v254
	ds_read_b128 v[132:135], v254 offset:1024
	ds_read_b128 v[136:139], v254 offset:2048
	ds_read_b128 v[140:143], v254 offset:3072
	ds_read_b128 v[174:177], v254 offset:16384
	ds_read_b128 v[184:187], v254 offset:17408
	ds_read_b128 v[188:191], v254 offset:18432
	ds_read_b128 v[210:213], v254 offset:19456
	s_add_u32 s2, s0, 0x100
	s_addc_u32 s3, s1, 0
	s_cmp_eq_u32 s13, 40
	s_cselect_b32 s7, s27, s3
	s_cselect_b32 s6, s26, s2
	s_cselect_b32 s5, s37, s11
	s_cselect_b32 s4, s36, s10
	s_add_i32 m0, s29, 0xc000
	ds_read_b128 v[214:217], v181
	ds_read_b128 v[218:221], v181 offset:1024
	ds_read_b128 v[222:225], v181 offset:2048
	ds_read_b128 v[226:229], v181 offset:3072
	ds_read_b128 v[230:233], v181 offset:4096
	ds_read_b128 v[234:237], v181 offset:5120
	ds_read_b128 v[238:241], v181 offset:6144
	ds_read_b128 v[242:245], v181 offset:7168
	global_load_lds_dwordx4 v170, s[0:1]
	s_add_i32 m0, s29, 0xe000
	s_nop 0
	global_load_lds_dwordx4 v172, s[0:1]
	s_waitcnt vmcnt(8)
	s_waitcnt lgkmcnt(0)
	s_barrier
	s_setprio 1
	v_mfma_f32_16x16x32_bf16 v[124:127], v[128:131], v[214:217], v[124:127]
	v_mfma_f32_16x16x32_bf16 v[120:123], v[136:139], v[214:217], v[120:123]
	v_mfma_f32_16x16x32_bf16 v[108:111], v[128:131], v[222:225], v[108:111]
	v_mfma_f32_16x16x32_bf16 v[104:107], v[136:139], v[222:225], v[104:107]
	v_mfma_f32_16x16x32_bf16 v[92:95], v[128:131], v[230:233], v[92:95]
	v_mfma_f32_16x16x32_bf16 v[88:91], v[136:139], v[230:233], v[88:91]
	v_mfma_f32_16x16x32_bf16 v[76:79], v[128:131], v[238:241], v[76:79]
	v_mfma_f32_16x16x32_bf16 v[72:75], v[136:139], v[238:241], v[72:75]
	v_mfma_f32_16x16x32_bf16 v[124:127], v[132:135], v[218:221], v[124:127]
	v_mfma_f32_16x16x32_bf16 v[120:123], v[140:143], v[218:221], v[120:123]
	v_mfma_f32_16x16x32_bf16 v[108:111], v[132:135], v[226:229], v[108:111]
	v_mfma_f32_16x16x32_bf16 v[104:107], v[140:143], v[226:229], v[104:107]
	v_mfma_f32_16x16x32_bf16 v[92:95], v[132:135], v[234:237], v[92:95]
	v_mfma_f32_16x16x32_bf16 v[88:91], v[140:143], v[234:237], v[88:91]
	v_mfma_f32_16x16x32_bf16 v[76:79], v[132:135], v[242:245], v[76:79]
	v_mfma_f32_16x16x32_bf16 v[72:75], v[140:143], v[242:245], v[72:75]
	v_mfma_f32_16x16x32_bf16 v[116:119], v[174:177], v[214:217], v[116:119]
	v_mfma_f32_16x16x32_bf16 v[112:115], v[188:191], v[214:217], v[112:115]
	v_mfma_f32_16x16x32_bf16 v[100:103], v[174:177], v[222:225], v[100:103]
	v_mfma_f32_16x16x32_bf16 v[96:99], v[188:191], v[222:225], v[96:99]
	v_mfma_f32_16x16x32_bf16 v[84:87], v[174:177], v[230:233], v[84:87]
	v_mfma_f32_16x16x32_bf16 v[80:83], v[188:191], v[230:233], v[80:83]
	v_mfma_f32_16x16x32_bf16 v[68:71], v[174:177], v[238:241], v[68:71]
	v_mfma_f32_16x16x32_bf16 v[64:67], v[188:191], v[238:241], v[64:67]
	v_mfma_f32_16x16x32_bf16 v[116:119], v[184:187], v[218:221], v[116:119]
	v_mfma_f32_16x16x32_bf16 v[112:115], v[210:213], v[218:221], v[112:115]
	v_mfma_f32_16x16x32_bf16 v[100:103], v[184:187], v[226:229], v[100:103]
	v_mfma_f32_16x16x32_bf16 v[96:99], v[210:213], v[226:229], v[96:99]
	v_mfma_f32_16x16x32_bf16 v[84:87], v[184:187], v[234:237], v[84:87]
	v_mfma_f32_16x16x32_bf16 v[80:83], v[210:213], v[234:237], v[80:83]
	v_mfma_f32_16x16x32_bf16 v[68:71], v[184:187], v[242:245], v[68:71]
	v_mfma_f32_16x16x32_bf16 v[64:67], v[210:213], v[242:245], v[64:67]
	s_setprio 0
	s_barrier
	s_mov_b32 m0, s35
	s_add_u32 s0, s4, 0xb0000
	s_addc_u32 s1, s5, 0
	ds_read_b128 v[214:217], v181 offset:16384
	ds_read_b128 v[218:221], v181 offset:17408
	ds_read_b128 v[222:225], v181 offset:18432
	ds_read_b128 v[226:229], v181 offset:19456
	ds_read_b128 v[230:233], v181 offset:20480
	ds_read_b128 v[234:237], v181 offset:21504
	ds_read_b128 v[238:241], v181 offset:22528
	ds_read_b128 v[242:245], v181 offset:23552
	global_load_lds_dwordx4 v166, s[4:5]
	s_mov_b32 m0, s38
	s_nop 0
	global_load_lds_dwordx4 v162, s[4:5]
	s_mov_b32 m0, s39
	s_nop 0
	global_load_lds_dwordx4 v166, s[0:1]
	s_mov_b32 m0, s40
	s_nop 0
	global_load_lds_dwordx4 v162, s[0:1]
	s_mov_b32 m0, s29
	s_nop 0
	global_load_lds_dwordx4 v168, s[6:7]
	s_mov_b32 m0, s41
	s_nop 0
	global_load_lds_dwordx4 v164, s[6:7]
	s_waitcnt vmcnt(8)
	s_waitcnt lgkmcnt(0)
	s_barrier
	s_setprio 1
	v_mfma_f32_16x16x32_bf16 v[60:63], v[128:131], v[214:217], v[60:63]
	v_mfma_f32_16x16x32_bf16 v[56:59], v[136:139], v[214:217], v[56:59]
	v_mfma_f32_16x16x32_bf16 v[44:47], v[128:131], v[222:225], v[44:47]
	v_mfma_f32_16x16x32_bf16 v[40:43], v[136:139], v[222:225], v[40:43]
	v_mfma_f32_16x16x32_bf16 v[28:31], v[128:131], v[230:233], v[28:31]
	v_mfma_f32_16x16x32_bf16 v[24:27], v[136:139], v[230:233], v[24:27]
	v_mfma_f32_16x16x32_bf16 v[12:15], v[128:131], v[238:241], v[12:15]
	v_mfma_f32_16x16x32_bf16 v[8:11], v[136:139], v[238:241], v[8:11]
	v_mfma_f32_16x16x32_bf16 v[60:63], v[132:135], v[218:221], v[60:63]
	v_mfma_f32_16x16x32_bf16 v[56:59], v[140:143], v[218:221], v[56:59]
	v_mfma_f32_16x16x32_bf16 v[44:47], v[132:135], v[226:229], v[44:47]
	v_mfma_f32_16x16x32_bf16 v[40:43], v[140:143], v[226:229], v[40:43]
	v_mfma_f32_16x16x32_bf16 v[28:31], v[132:135], v[234:237], v[28:31]
	v_mfma_f32_16x16x32_bf16 v[24:27], v[140:143], v[234:237], v[24:27]
	v_mfma_f32_16x16x32_bf16 v[12:15], v[132:135], v[242:245], v[12:15]
	v_mfma_f32_16x16x32_bf16 v[8:11], v[140:143], v[242:245], v[8:11]
	v_mfma_f32_16x16x32_bf16 v[52:55], v[174:177], v[214:217], v[52:55]
	v_mfma_f32_16x16x32_bf16 v[48:51], v[188:191], v[214:217], v[48:51]
	v_mfma_f32_16x16x32_bf16 v[36:39], v[174:177], v[222:225], v[36:39]
	v_mfma_f32_16x16x32_bf16 v[32:35], v[188:191], v[222:225], v[32:35]
	v_mfma_f32_16x16x32_bf16 v[20:23], v[174:177], v[230:233], v[20:23]
	v_mfma_f32_16x16x32_bf16 v[16:19], v[188:191], v[230:233], v[16:19]
	v_mfma_f32_16x16x32_bf16 v[4:7], v[174:177], v[238:241], v[4:7]
	v_mfma_f32_16x16x32_bf16 v[0:3], v[188:191], v[238:241], v[0:3]
	v_mfma_f32_16x16x32_bf16 v[52:55], v[184:187], v[218:221], v[52:55]
	v_mfma_f32_16x16x32_bf16 v[48:51], v[210:213], v[218:221], v[48:51]
	v_mfma_f32_16x16x32_bf16 v[36:39], v[184:187], v[226:229], v[36:39]
	v_mfma_f32_16x16x32_bf16 v[32:35], v[210:213], v[226:229], v[32:35]
	v_mfma_f32_16x16x32_bf16 v[20:23], v[184:187], v[234:237], v[20:23]
	v_mfma_f32_16x16x32_bf16 v[16:19], v[210:213], v[234:237], v[16:19]
	v_mfma_f32_16x16x32_bf16 v[4:7], v[184:187], v[242:245], v[4:7]
	v_mfma_f32_16x16x32_bf16 v[0:3], v[210:213], v[242:245], v[0:3]
	s_setprio 0
	s_barrier
; #define PG8_STAGE(bufoff, gbase, voff) do { _Pragma("unroll") for (int _i = 0; _i < 2; ++_i) \
;         __builtin_amdgcn_global_load_lds((const unsigned*)((const char*)(gbase) + (voff)[_i]), (PG8_LAS unsigned*)(lds + (bufoff) + ldsw + _i * 8192), 16, 0, 0); } while (0)
; #define PG8_LDA(dst, b, h) do { _Pragma("unroll") for (int m = 0; m < 4; ++m) _Pragma("unroll") for (int k = 0; k < 2; ++k) dst[m][k] = *(const PG8_LAS bf16x8*)(lds + PG8_SA(b, h) + aoff + m * 2048 + k * 1024); } while (0)
; #define PG8_LDB(dst, b, h) do { _Pragma("unroll") for (int n = 0; n < 2; ++n) _Pragma("unroll") for (int k = 0; k < 2; ++k) dst[n][k] = *(const PG8_LAS bf16x8*)(lds + PG8_SB(b, h) + boff + n * 2048 + k * 1024); } while (0)
; #define PG8_MMA(ai, bj, At, Bt) do { __builtin_amdgcn_s_setprio(1); _Pragma("unroll") for (int m = 0; m < 4; ++m) _Pragma("unroll") for (int n = 0; n < 2; ++n) _Pragma("unroll") for (int k = 0; k < 2; ++k) \
;         acc[ai][bj][m][n] = __builtin_amdgcn_mfma_f32_16x16x32_bf16(Bt[n][k], At[m][k], acc[ai][bj][m][n], 0, 0, 0); __builtin_amdgcn_s_setprio(0); } while (0)
; #define PG8_WAIT_V(n) asm volatile("s_waitcnt vmcnt(" #n ")" ::: "memory")
; #define PG8_WAIT_L(n) asm volatile("s_waitcnt lgkmcnt(" #n ")" ::: "memory")
; #define PG8_BAR __builtin_amdgcn_s_barrier()
; #define PG8_SCHED __builtin_amdgcn_sched_barrier(0)
; template <class Epi, class Sched, bool ALIGN_EPI = false, bool SP2 = false>
; __device__ __forceinline__ void gemm_phase(PG8_LAS unsigned char* lds, const Gemm g, const Sched& S, const Epi& E) {
;     ...
;         for (int t = 0; t < nt; t += 2) {
;     ...
;             PG8_LDB(B0, 1, 0); PG8_LDB(B1, 1, 1); PG8_SCHED; PG8_LDA(At, 1, 0); PG8_STAGE(PG8_SA(0, 1), a2 + hstep, voffA);
;             PG8_WAIT_V(8); PG8_WAIT_L(0); PG8_BAR; PG8_MMA(0, 0, At, B0); PG8_MMA(0, 1, At, B1); PG8_BAR; PG8_SCHED;
;             PG8_LDA(At, 1, 1); PG8_STAGE(PG8_SB(1, 0), b3, voffB); PG8_STAGE(PG8_SB(1, 1), b3 + hstep, voffB); PG8_STAGE(PG8_SA(1, 0), a3, voffA);
;             PG8_WAIT_V(8); PG8_WAIT_L(0); PG8_BAR; PG8_MMA(1, 0, At, B0); PG8_MMA(1, 1, At, B1); PG8_BAR; PG8_SCHED;
	ds_read_b128 v[128:131], v254 offset:32768
	ds_read_b128 v[132:135], v254 offset:33792
	ds_read_b128 v[136:139], v254 offset:34816
	ds_read_b128 v[140:143], v254 offset:35840
	ds_read_b128 v[174:177], v254 offset:49152
	ds_read_b128 v[184:187], v254 offset:50176
	ds_read_b128 v[188:191], v254 offset:51200
	ds_read_b128 v[210:213], v254 offset:52224
	s_add_u32 s0, s6, 0xb0000
	s_addc_u32 s1, s7, 0
	s_mov_b32 m0, s42
	ds_read_b128 v[214:217], v181 offset:32768
	ds_read_b128 v[218:221], v181 offset:33792
	ds_read_b128 v[222:225], v181 offset:34816
	ds_read_b128 v[226:229], v181 offset:35840
	ds_read_b128 v[230:233], v181 offset:36864
	ds_read_b128 v[234:237], v181 offset:37888
	ds_read_b128 v[238:241], v181 offset:38912
	ds_read_b128 v[242:245], v181 offset:39936
	global_load_lds_dwordx4 v168, s[0:1]
	s_mov_b32 m0, s43
	s_nop 0
	global_load_lds_dwordx4 v164, s[0:1]
	s_waitcnt vmcnt(8)
	s_waitcnt lgkmcnt(0)
	s_barrier
	s_setprio 1
	v_mfma_f32_16x16x32_bf16 v[124:127], v[128:131], v[214:217], v[124:127]
	v_mfma_f32_16x16x32_bf16 v[120:123], v[136:139], v[214:217], v[120:123]
	v_mfma_f32_16x16x32_bf16 v[108:111], v[128:131], v[222:225], v[108:111]
	v_mfma_f32_16x16x32_bf16 v[104:107], v[136:139], v[222:225], v[104:107]
	v_mfma_f32_16x16x32_bf16 v[92:95], v[128:131], v[230:233], v[92:95]
	v_mfma_f32_16x16x32_bf16 v[88:91], v[136:139], v[230:233], v[88:91]
	v_mfma_f32_16x16x32_bf16 v[76:79], v[128:131], v[238:241], v[76:79]
	v_mfma_f32_16x16x32_bf16 v[72:75], v[136:139], v[238:241], v[72:75]
	v_mfma_f32_16x16x32_bf16 v[124:127], v[132:135], v[218:221], v[124:127]
	v_mfma_f32_16x16x32_bf16 v[120:123], v[140:143], v[218:221], v[120:123]
	v_mfma_f32_16x16x32_bf16 v[108:111], v[132:135], v[226:229], v[108:111]
	v_mfma_f32_16x16x32_bf16 v[104:107], v[140:143], v[226:229], v[104:107]
	v_mfma_f32_16x16x32_bf16 v[92:95], v[132:135], v[234:237], v[92:95]
	v_mfma_f32_16x16x32_bf16 v[88:91], v[140:143], v[234:237], v[88:91]
	v_mfma_f32_16x16x32_bf16 v[76:79], v[132:135], v[242:245], v[76:79]
	v_mfma_f32_16x16x32_bf16 v[72:75], v[140:143], v[242:245], v[72:75]
	v_mfma_f32_16x16x32_bf16 v[116:119], v[174:177], v[214:217], v[116:119]
	v_mfma_f32_16x16x32_bf16 v[112:115], v[188:191], v[214:217], v[112:115]
	v_mfma_f32_16x16x32_bf16 v[100:103], v[174:177], v[222:225], v[100:103]
	v_mfma_f32_16x16x32_bf16 v[96:99], v[188:191], v[222:225], v[96:99]
	v_mfma_f32_16x16x32_bf16 v[84:87], v[174:177], v[230:233], v[84:87]
	v_mfma_f32_16x16x32_bf16 v[80:83], v[188:191], v[230:233], v[80:83]
	v_mfma_f32_16x16x32_bf16 v[68:71], v[174:177], v[238:241], v[68:71]
	v_mfma_f32_16x16x32_bf16 v[64:67], v[188:191], v[238:241], v[64:67]
	v_mfma_f32_16x16x32_bf16 v[116:119], v[184:187], v[218:221], v[116:119]
	v_mfma_f32_16x16x32_bf16 v[112:115], v[210:213], v[218:221], v[112:115]
	v_mfma_f32_16x16x32_bf16 v[100:103], v[184:187], v[226:229], v[100:103]
	v_mfma_f32_16x16x32_bf16 v[96:99], v[210:213], v[226:229], v[96:99]
	v_mfma_f32_16x16x32_bf16 v[84:87], v[184:187], v[234:237], v[84:87]
	v_mfma_f32_16x16x32_bf16 v[80:83], v[210:213], v[234:237], v[80:83]
	v_mfma_f32_16x16x32_bf16 v[68:71], v[184:187], v[242:245], v[68:71]
	v_mfma_f32_16x16x32_bf16 v[64:67], v[210:213], v[242:245], v[64:67]
	s_setprio 0
	s_barrier
	s_mov_b32 m0, s47
	s_add_u32 s0, s4, 0xb0080
	s_addc_u32 s1, s5, 0
	ds_read_b128 v[214:217], v181 offset:49152
	ds_read_b128 v[218:221], v181 offset:50176
	ds_read_b128 v[222:225], v181 offset:51200
	ds_read_b128 v[226:229], v181 offset:52224
	ds_read_b128 v[230:233], v181 offset:53248
	ds_read_b128 v[234:237], v181 offset:54272
	ds_read_b128 v[238:241], v181 offset:55296
	ds_read_b128 v[242:245], v181 offset:56320
	s_add_u32 s98, s4, 0x80
	s_addc_u32 s99, s5, 0
	global_load_lds_dwordx4 v166, s[98:99]
	s_mov_b32 m0, s48
	s_nop 0
	global_load_lds_dwordx4 v162, s[98:99]
	s_mov_b32 m0, s51
	s_nop 0
	global_load_lds_dwordx4 v166, s[0:1]
	s_mov_b32 m0, s52
	s_nop 0
	global_load_lds_dwordx4 v162, s[0:1]
	s_mov_b32 m0, s49
	s_nop 0
	s_add_u32 s100, s6, 0x80
	s_addc_u32 s101, s7, 0
	global_load_lds_dwordx4 v168, s[100:101]
	s_mov_b32 m0, s50
	s_nop 0
	global_load_lds_dwordx4 v164, s[100:101]
	s_waitcnt vmcnt(8)
	s_waitcnt lgkmcnt(0)
	s_barrier
	s_setprio 1
	v_mfma_f32_16x16x32_bf16 v[60:63], v[128:131], v[214:217], v[60:63]
	v_mfma_f32_16x16x32_bf16 v[56:59], v[136:139], v[214:217], v[56:59]
	v_mfma_f32_16x16x32_bf16 v[44:47], v[128:131], v[222:225], v[44:47]
	v_mfma_f32_16x16x32_bf16 v[40:43], v[136:139], v[222:225], v[40:43]
	v_mfma_f32_16x16x32_bf16 v[28:31], v[128:131], v[230:233], v[28:31]
	v_mfma_f32_16x16x32_bf16 v[24:27], v[136:139], v[230:233], v[24:27]
	v_mfma_f32_16x16x32_bf16 v[12:15], v[128:131], v[238:241], v[12:15]
	v_mfma_f32_16x16x32_bf16 v[8:11], v[136:139], v[238:241], v[8:11]
	v_mfma_f32_16x16x32_bf16 v[60:63], v[132:135], v[218:221], v[60:63]
	v_mfma_f32_16x16x32_bf16 v[56:59], v[140:143], v[218:221], v[56:59]
	v_mfma_f32_16x16x32_bf16 v[44:47], v[132:135], v[226:229], v[44:47]
	v_mfma_f32_16x16x32_bf16 v[40:43], v[140:143], v[226:229], v[40:43]
	v_mfma_f32_16x16x32_bf16 v[28:31], v[132:135], v[234:237], v[28:31]
	v_mfma_f32_16x16x32_bf16 v[24:27], v[140:143], v[234:237], v[24:27]
	v_mfma_f32_16x16x32_bf16 v[12:15], v[132:135], v[242:245], v[12:15]
	v_mfma_f32_16x16x32_bf16 v[8:11], v[140:143], v[242:245], v[8:11]
	v_mfma_f32_16x16x32_bf16 v[52:55], v[174:177], v[214:217], v[52:55]
	v_mfma_f32_16x16x32_bf16 v[48:51], v[188:191], v[214:217], v[48:51]
	v_mfma_f32_16x16x32_bf16 v[36:39], v[174:177], v[222:225], v[36:39]
	v_mfma_f32_16x16x32_bf16 v[32:35], v[188:191], v[222:225], v[32:35]
	v_mfma_f32_16x16x32_bf16 v[20:23], v[174:177], v[230:233], v[20:23]
	v_mfma_f32_16x16x32_bf16 v[16:19], v[188:191], v[230:233], v[16:19]
	v_mfma_f32_16x16x32_bf16 v[4:7], v[174:177], v[238:241], v[4:7]
	v_mfma_f32_16x16x32_bf16 v[0:3], v[188:191], v[238:241], v[0:3]
	v_mfma_f32_16x16x32_bf16 v[52:55], v[184:187], v[218:221], v[52:55]
	v_mfma_f32_16x16x32_bf16 v[48:51], v[210:213], v[218:221], v[48:51]
	v_mfma_f32_16x16x32_bf16 v[36:39], v[184:187], v[226:229], v[36:39]
	v_mfma_f32_16x16x32_bf16 v[32:35], v[210:213], v[226:229], v[32:35]
	v_mfma_f32_16x16x32_bf16 v[20:23], v[184:187], v[234:237], v[20:23]
	v_mfma_f32_16x16x32_bf16 v[16:19], v[210:213], v[234:237], v[16:19]
	v_mfma_f32_16x16x32_bf16 v[4:7], v[184:187], v[242:245], v[4:7]
	v_mfma_f32_16x16x32_bf16 v[0:3], v[210:213], v[242:245], v[0:3]
	s_setprio 0
	s_barrier
	s_add_i32 s13, s13, 2
	s_add_u32 s10, s10, 0x100
	s_addc_u32 s11, s11, 0
	s_cmp_gt_u32 s13, 41
	s_mov_b64 s[0:1], s[2:3]
	s_cbranch_scc0 .LBB0_545
	s_and_b64 vcc, exec, s[22:23]
	s_cbranch_vccz .LBB0_548
	s_barrier

; #define PG8_STAGE(bufoff, gbase, voff) do { _Pragma("unroll") for (int _i = 0; _i < 2; ++_i) \
;         __builtin_amdgcn_global_load_lds((const unsigned*)((const char*)(gbase) + (voff)[_i]), (PG8_LAS unsigned*)(lds + (bufoff) + ldsw + _i * 8192), 16, 0, 0); } while (0)
; #define PG8_LDA(dst, b, h) do { _Pragma("unroll") for (int m = 0; m < 4; ++m) _Pragma("unroll") for (int k = 0; k < 2; ++k) dst[m][k] = *(const PG8_LAS bf16x8*)(lds + PG8_SA(b, h) + aoff + m * 2048 + k * 1024); } while (0)
; #define PG8_LDB(dst, b, h) do { _Pragma("unroll") for (int n = 0; n < 2; ++n) _Pragma("unroll") for (int k = 0; k < 2; ++k) dst[n][k] = *(const PG8_LAS bf16x8*)(lds + PG8_SB(b, h) + boff + n * 2048 + k * 1024); } while (0)
; #define PG8_MMA(ai, bj, At, Bt) do { __builtin_amdgcn_s_setprio(1); _Pragma("unroll") for (int m = 0; m < 4; ++m) _Pragma("unroll") for (int n = 0; n < 2; ++n) _Pragma("unroll") for (int k = 0; k < 2; ++k) \
;         acc[ai][bj][m][n] = __builtin_amdgcn_mfma_f32_16x16x32_bf16(Bt[n][k], At[m][k], acc[ai][bj][m][n], 0, 0, 0); __builtin_amdgcn_s_setprio(0); } while (0)
; #define PG8_WAIT_V(n) asm volatile("s_waitcnt vmcnt(" #n ")" ::: "memory")
; #define PG8_WAIT_L(n) asm volatile("s_waitcnt lgkmcnt(" #n ")" ::: "memory")
; #define PG8_BAR __builtin_amdgcn_s_barrier()
; #define PG8_SCHED __builtin_amdgcn_sched_barrier(0)
; template <class Epi, class Sched, bool ALIGN_EPI = false, bool SP2 = false>
; __device__ __forceinline__ void gemm_phase(PG8_LAS unsigned char* lds, const Gemm g, const Sched& S, const Epi& E) {
;     ...
;             PG8_LDB(B0, 0, 0); PG8_LDB(B1, 0, 1); PG8_SCHED; PG8_LDA(At, 0, 0); PG8_STAGE(PG8_SA(1, 1), a1 + hstep, voffA);
;             PG8_WAIT_V(8); PG8_WAIT_L(0); PG8_BAR; PG8_MMA(0, 0, At, B0); PG8_MMA(0, 1, At, B1); PG8_BAR; PG8_SCHED;
;             PG8_LDA(At, 0, 1); PG8_STAGE(PG8_SB(0, 0), b2, voffB); PG8_STAGE(PG8_SB(0, 1), b2 + hstep, voffB); PG8_STAGE(PG8_SA(0, 0), a2, voffA);
;             PG8_WAIT_V(8); PG8_WAIT_L(0); PG8_BAR; PG8_MMA(1, 0, At, B0); PG8_MMA(1, 1, At, B1); PG8_BAR; PG8_SCHED;
.Lsgi_peel:
	ds_read_b128 v[140:143], v254
	ds_read_b128 v[162:165], v254 offset:1024
	ds_read_b128 v[166:169], v254 offset:2048
	ds_read_b128 v[170:173], v254 offset:3072
	ds_read_b128 v[180:183], v254 offset:16384
	ds_read_b128 v[184:187], v254 offset:17408
	ds_read_b128 v[188:191], v254 offset:18432
	ds_read_b128 v[210:213], v254 offset:19456
	s_add_u32 s2, s0, 0xfffc0080
	s_addc_u32 s3, s1, -1
	s_cmp_eq_u32 s55, 12
	s_cselect_b32 s5, s13, s3
	s_cselect_b32 s4, s25, s2
	s_cselect_b32 s3, s23, s39
	s_cselect_b32 s2, s33, s38
	s_add_i32 m0, s6, 0xc000
	ds_read_b128 v[214:217], v178
	ds_read_b128 v[218:221], v178 offset:1024
	ds_read_b128 v[222:225], v178 offset:2048
	ds_read_b128 v[226:229], v178 offset:3072
	ds_read_b128 v[230:233], v178 offset:4096
	ds_read_b128 v[234:237], v178 offset:5120
	ds_read_b128 v[238:241], v178 offset:6144
	ds_read_b128 v[242:245], v178 offset:7168
	global_load_lds_dwordx4 v136, s[0:1]
	s_add_i32 m0, s6, 0xe000
	s_nop 0
	global_load_lds_dwordx4 v138, s[0:1]
	s_waitcnt vmcnt(8)
	s_waitcnt lgkmcnt(0)
	s_barrier
	s_setprio 1
	v_mfma_f32_16x16x32_bf16 v[124:127], v[140:143], v[214:217], 0
	v_mfma_f32_16x16x32_bf16 v[120:123], v[166:169], v[214:217], 0
	v_mfma_f32_16x16x32_bf16 v[108:111], v[140:143], v[222:225], 0
	v_mfma_f32_16x16x32_bf16 v[104:107], v[166:169], v[222:225], 0
	v_mfma_f32_16x16x32_bf16 v[92:95], v[140:143], v[230:233], 0
	v_mfma_f32_16x16x32_bf16 v[88:91], v[166:169], v[230:233], 0
	v_mfma_f32_16x16x32_bf16 v[76:79], v[140:143], v[238:241], 0
	v_mfma_f32_16x16x32_bf16 v[72:75], v[166:169], v[238:241], 0
	v_mfma_f32_16x16x32_bf16 v[124:127], v[162:165], v[218:221], v[124:127]
	v_mfma_f32_16x16x32_bf16 v[120:123], v[170:173], v[218:221], v[120:123]
	v_mfma_f32_16x16x32_bf16 v[108:111], v[162:165], v[226:229], v[108:111]
	v_mfma_f32_16x16x32_bf16 v[104:107], v[170:173], v[226:229], v[104:107]
	v_mfma_f32_16x16x32_bf16 v[92:95], v[162:165], v[234:237], v[92:95]
	v_mfma_f32_16x16x32_bf16 v[88:91], v[170:173], v[234:237], v[88:91]
	v_mfma_f32_16x16x32_bf16 v[76:79], v[162:165], v[242:245], v[76:79]
	v_mfma_f32_16x16x32_bf16 v[72:75], v[170:173], v[242:245], v[72:75]
	v_mfma_f32_16x16x32_bf16 v[116:119], v[180:183], v[214:217], 0
	v_mfma_f32_16x16x32_bf16 v[112:115], v[188:191], v[214:217], 0
	v_mfma_f32_16x16x32_bf16 v[100:103], v[180:183], v[222:225], 0
	v_mfma_f32_16x16x32_bf16 v[96:99], v[188:191], v[222:225], 0
	v_mfma_f32_16x16x32_bf16 v[84:87], v[180:183], v[230:233], 0
	v_mfma_f32_16x16x32_bf16 v[80:83], v[188:191], v[230:233], 0
	v_mfma_f32_16x16x32_bf16 v[68:71], v[180:183], v[238:241], 0
	v_mfma_f32_16x16x32_bf16 v[64:67], v[188:191], v[238:241], 0
	v_mfma_f32_16x16x32_bf16 v[116:119], v[184:187], v[218:221], v[116:119]
	v_mfma_f32_16x16x32_bf16 v[112:115], v[210:213], v[218:221], v[112:115]
	v_mfma_f32_16x16x32_bf16 v[100:103], v[184:187], v[226:229], v[100:103]
	v_mfma_f32_16x16x32_bf16 v[96:99], v[210:213], v[226:229], v[96:99]
	v_mfma_f32_16x16x32_bf16 v[84:87], v[184:187], v[234:237], v[84:87]
	v_mfma_f32_16x16x32_bf16 v[80:83], v[210:213], v[234:237], v[80:83]
	v_mfma_f32_16x16x32_bf16 v[68:71], v[184:187], v[242:245], v[68:71]
	v_mfma_f32_16x16x32_bf16 v[64:67], v[210:213], v[242:245], v[64:67]
	s_setprio 0
	s_barrier
	s_mov_b32 m0, s31
	s_add_u32 s56, s2, 0x40000
	s_addc_u32 s57, s3, 0
	ds_read_b128 v[214:217], v178 offset:16384
	ds_read_b128 v[218:221], v178 offset:17408
	ds_read_b128 v[222:225], v178 offset:18432
	ds_read_b128 v[226:229], v178 offset:19456
	ds_read_b128 v[230:233], v178 offset:20480
	ds_read_b128 v[234:237], v178 offset:21504
	ds_read_b128 v[238:241], v178 offset:22528
	ds_read_b128 v[242:245], v178 offset:23552
	global_load_lds_dwordx4 v132, s[2:3]
	s_mov_b32 m0, s34
	s_nop 0
	global_load_lds_dwordx4 v128, s[2:3]
	s_mov_b32 m0, s35
	s_nop 0
	global_load_lds_dwordx4 v132, s[56:57]
	s_mov_b32 m0, s40
	s_nop 0
	global_load_lds_dwordx4 v128, s[56:57]
	s_mov_b32 m0, s6
	s_nop 0
	global_load_lds_dwordx4 v134, s[4:5]
	s_mov_b32 m0, s41
	s_nop 0
	global_load_lds_dwordx4 v130, s[4:5]
	s_waitcnt vmcnt(8)
	s_waitcnt lgkmcnt(0)
	s_barrier
	s_setprio 1
	v_mfma_f32_16x16x32_bf16 v[60:63], v[140:143], v[214:217], 0
	v_mfma_f32_16x16x32_bf16 v[56:59], v[166:169], v[214:217], 0
	v_mfma_f32_16x16x32_bf16 v[44:47], v[140:143], v[222:225], 0
	v_mfma_f32_16x16x32_bf16 v[40:43], v[166:169], v[222:225], 0
	v_mfma_f32_16x16x32_bf16 v[28:31], v[140:143], v[230:233], 0
	v_mfma_f32_16x16x32_bf16 v[24:27], v[166:169], v[230:233], 0
	v_mfma_f32_16x16x32_bf16 v[12:15], v[140:143], v[238:241], 0
	v_mfma_f32_16x16x32_bf16 v[8:11], v[166:169], v[238:241], 0
	v_mfma_f32_16x16x32_bf16 v[60:63], v[162:165], v[218:221], v[60:63]
	v_mfma_f32_16x16x32_bf16 v[56:59], v[170:173], v[218:221], v[56:59]
	v_mfma_f32_16x16x32_bf16 v[44:47], v[162:165], v[226:229], v[44:47]
	v_mfma_f32_16x16x32_bf16 v[40:43], v[170:173], v[226:229], v[40:43]
	v_mfma_f32_16x16x32_bf16 v[28:31], v[162:165], v[234:237], v[28:31]
	v_mfma_f32_16x16x32_bf16 v[24:27], v[170:173], v[234:237], v[24:27]
	v_mfma_f32_16x16x32_bf16 v[12:15], v[162:165], v[242:245], v[12:15]
	v_mfma_f32_16x16x32_bf16 v[8:11], v[170:173], v[242:245], v[8:11]
	v_mfma_f32_16x16x32_bf16 v[52:55], v[180:183], v[214:217], 0
	v_mfma_f32_16x16x32_bf16 v[48:51], v[188:191], v[214:217], 0
	v_mfma_f32_16x16x32_bf16 v[36:39], v[180:183], v[222:225], 0
	v_mfma_f32_16x16x32_bf16 v[32:35], v[188:191], v[222:225], 0
	v_mfma_f32_16x16x32_bf16 v[20:23], v[180:183], v[230:233], 0
	v_mfma_f32_16x16x32_bf16 v[16:19], v[188:191], v[230:233], 0
	v_mfma_f32_16x16x32_bf16 v[4:7], v[180:183], v[238:241], 0
	v_mfma_f32_16x16x32_bf16 v[0:3], v[188:191], v[238:241], 0
	v_mfma_f32_16x16x32_bf16 v[52:55], v[184:187], v[218:221], v[52:55]
	v_mfma_f32_16x16x32_bf16 v[48:51], v[210:213], v[218:221], v[48:51]
	v_mfma_f32_16x16x32_bf16 v[36:39], v[184:187], v[226:229], v[36:39]
	v_mfma_f32_16x16x32_bf16 v[32:35], v[210:213], v[226:229], v[32:35]
	v_mfma_f32_16x16x32_bf16 v[20:23], v[184:187], v[234:237], v[20:23]
	v_mfma_f32_16x16x32_bf16 v[16:19], v[210:213], v[234:237], v[16:19]
	v_mfma_f32_16x16x32_bf16 v[4:7], v[184:187], v[242:245], v[4:7]
	v_mfma_f32_16x16x32_bf16 v[0:3], v[210:213], v[242:245], v[0:3]
	s_setprio 0
	s_barrier
; #define PG8_STAGE(bufoff, gbase, voff) do { _Pragma("unroll") for (int _i = 0; _i < 2; ++_i) \
;         __builtin_amdgcn_global_load_lds((const unsigned*)((const char*)(gbase) + (voff)[_i]), (PG8_LAS unsigned*)(lds + (bufoff) + ldsw + _i * 8192), 16, 0, 0); } while (0)
; #define PG8_LDA(dst, b, h) do { _Pragma("unroll") for (int m = 0; m < 4; ++m) _Pragma("unroll") for (int k = 0; k < 2; ++k) dst[m][k] = *(const PG8_LAS bf16x8*)(lds + PG8_SA(b, h) + aoff + m * 2048 + k * 1024); } while (0)
; #define PG8_LDB(dst, b, h) do { _Pragma("unroll") for (int n = 0; n < 2; ++n) _Pragma("unroll") for (int k = 0; k < 2; ++k) dst[n][k] = *(const PG8_LAS bf16x8*)(lds + PG8_SB(b, h) + boff + n * 2048 + k * 1024); } while (0)
; #define PG8_MMA(ai, bj, At, Bt) do { __builtin_amdgcn_s_setprio(1); _Pragma("unroll") for (int m = 0; m < 4; ++m) _Pragma("unroll") for (int n = 0; n < 2; ++n) _Pragma("unroll") for (int k = 0; k < 2; ++k) \
;         acc[ai][bj][m][n] = __builtin_amdgcn_mfma_f32_16x16x32_bf16(Bt[n][k], At[m][k], acc[ai][bj][m][n], 0, 0, 0); __builtin_amdgcn_s_setprio(0); } while (0)
; #define PG8_WAIT_V(n) asm volatile("s_waitcnt vmcnt(" #n ")" ::: "memory")
; #define PG8_WAIT_L(n) asm volatile("s_waitcnt lgkmcnt(" #n ")" ::: "memory")
; #define PG8_BAR __builtin_amdgcn_s_barrier()
; #define PG8_SCHED __builtin_amdgcn_sched_barrier(0)
; template <class Epi, class Sched, bool ALIGN_EPI = false, bool SP2 = false>
; __device__ __forceinline__ void gemm_phase(PG8_LAS unsigned char* lds, const Gemm g, const Sched& S, const Epi& E) {
;     ...
;             PG8_LDB(B0, 1, 0); PG8_LDB(B1, 1, 1); PG8_SCHED; PG8_LDA(At, 1, 0); PG8_STAGE(PG8_SA(0, 1), a2 + hstep, voffA);
;             PG8_WAIT_V(8); PG8_WAIT_L(0); PG8_BAR; PG8_MMA(0, 0, At, B0); PG8_MMA(0, 1, At, B1); PG8_BAR; PG8_SCHED;
;             PG8_LDA(At, 1, 1); PG8_STAGE(PG8_SB(1, 0), b3, voffB); PG8_STAGE(PG8_SB(1, 1), b3 + hstep, voffB); PG8_STAGE(PG8_SA(1, 0), a3, voffA);
;             PG8_WAIT_V(8); PG8_WAIT_L(0); PG8_BAR; PG8_MMA(1, 0, At, B0); PG8_MMA(1, 1, At, B1); PG8_BAR; PG8_SCHED;
	ds_read_b128 v[140:143], v254 offset:32768
	ds_read_b128 v[162:165], v254 offset:33792
	ds_read_b128 v[166:169], v254 offset:34816
	ds_read_b128 v[170:173], v254 offset:35840
	ds_read_b128 v[180:183], v254 offset:49152
	ds_read_b128 v[184:187], v254 offset:50176
	ds_read_b128 v[188:191], v254 offset:51200
	ds_read_b128 v[210:213], v254 offset:52224
	s_add_u32 s4, s4, 0x40000
	s_addc_u32 s5, s5, 0
	s_mov_b32 m0, s42
	ds_read_b128 v[214:217], v178 offset:32768
	ds_read_b128 v[218:221], v178 offset:33792
	ds_read_b128 v[222:225], v178 offset:34816
	ds_read_b128 v[226:229], v178 offset:35840
	ds_read_b128 v[230:233], v178 offset:36864
	ds_read_b128 v[234:237], v178 offset:37888
	ds_read_b128 v[238:241], v178 offset:38912
	ds_read_b128 v[242:245], v178 offset:39936
	global_load_lds_dwordx4 v134, s[4:5]
	s_mov_b32 m0, s43
	s_nop 0
	global_load_lds_dwordx4 v130, s[4:5]
	s_waitcnt vmcnt(8)
	s_waitcnt lgkmcnt(0)
	s_barrier
	s_setprio 1
	v_mfma_f32_16x16x32_bf16 v[124:127], v[140:143], v[214:217], v[124:127]
	v_mfma_f32_16x16x32_bf16 v[120:123], v[166:169], v[214:217], v[120:123]
	v_mfma_f32_16x16x32_bf16 v[108:111], v[140:143], v[222:225], v[108:111]
	v_mfma_f32_16x16x32_bf16 v[104:107], v[166:169], v[222:225], v[104:107]
	v_mfma_f32_16x16x32_bf16 v[92:95], v[140:143], v[230:233], v[92:95]
	v_mfma_f32_16x16x32_bf16 v[88:91], v[166:169], v[230:233], v[88:91]
	v_mfma_f32_16x16x32_bf16 v[76:79], v[140:143], v[238:241], v[76:79]
	v_mfma_f32_16x16x32_bf16 v[72:75], v[166:169], v[238:241], v[72:75]
	v_mfma_f32_16x16x32_bf16 v[124:127], v[162:165], v[218:221], v[124:127]
	v_mfma_f32_16x16x32_bf16 v[120:123], v[170:173], v[218:221], v[120:123]
	v_mfma_f32_16x16x32_bf16 v[108:111], v[162:165], v[226:229], v[108:111]
	v_mfma_f32_16x16x32_bf16 v[104:107], v[170:173], v[226:229], v[104:107]
	v_mfma_f32_16x16x32_bf16 v[92:95], v[162:165], v[234:237], v[92:95]
	v_mfma_f32_16x16x32_bf16 v[88:91], v[170:173], v[234:237], v[88:91]
	v_mfma_f32_16x16x32_bf16 v[76:79], v[162:165], v[242:245], v[76:79]
	v_mfma_f32_16x16x32_bf16 v[72:75], v[170:173], v[242:245], v[72:75]
	v_mfma_f32_16x16x32_bf16 v[116:119], v[180:183], v[214:217], v[116:119]
	v_mfma_f32_16x16x32_bf16 v[112:115], v[188:191], v[214:217], v[112:115]
	v_mfma_f32_16x16x32_bf16 v[100:103], v[180:183], v[222:225], v[100:103]
	v_mfma_f32_16x16x32_bf16 v[96:99], v[188:191], v[222:225], v[96:99]
	v_mfma_f32_16x16x32_bf16 v[84:87], v[180:183], v[230:233], v[84:87]
	v_mfma_f32_16x16x32_bf16 v[80:83], v[188:191], v[230:233], v[80:83]
	v_mfma_f32_16x16x32_bf16 v[68:71], v[180:183], v[238:241], v[68:71]
	v_mfma_f32_16x16x32_bf16 v[64:67], v[188:191], v[238:241], v[64:67]
	v_mfma_f32_16x16x32_bf16 v[116:119], v[184:187], v[218:221], v[116:119]
	v_mfma_f32_16x16x32_bf16 v[112:115], v[210:213], v[218:221], v[112:115]
	v_mfma_f32_16x16x32_bf16 v[100:103], v[184:187], v[226:229], v[100:103]
	v_mfma_f32_16x16x32_bf16 v[96:99], v[210:213], v[226:229], v[96:99]
	v_mfma_f32_16x16x32_bf16 v[84:87], v[184:187], v[234:237], v[84:87]
	v_mfma_f32_16x16x32_bf16 v[80:83], v[210:213], v[234:237], v[80:83]
	v_mfma_f32_16x16x32_bf16 v[68:71], v[184:187], v[242:245], v[68:71]
	v_mfma_f32_16x16x32_bf16 v[64:67], v[210:213], v[242:245], v[64:67]
	s_setprio 0
	s_barrier
	s_mov_b32 m0, s48
	s_add_u32 s2, s2, 0x40080
	s_addc_u32 s3, s3, 0
	ds_read_b128 v[214:217], v178 offset:49152
	ds_read_b128 v[218:221], v178 offset:50176
	ds_read_b128 v[222:225], v178 offset:51200
	ds_read_b128 v[226:229], v178 offset:52224
	ds_read_b128 v[230:233], v178 offset:53248
	ds_read_b128 v[234:237], v178 offset:54272
	ds_read_b128 v[238:241], v178 offset:55296
	ds_read_b128 v[242:245], v178 offset:56320
	s_add_u32 s98, s2, 0xfffc0000
	s_addc_u32 s99, s3, -1
	global_load_lds_dwordx4 v132, s[98:99]
	s_mov_b32 m0, s49
	s_nop 0
	global_load_lds_dwordx4 v128, s[98:99]
	s_mov_b32 m0, s52
	s_nop 0
	global_load_lds_dwordx4 v132, s[2:3]
	s_mov_b32 m0, s53
	s_nop 0
	global_load_lds_dwordx4 v128, s[2:3]
	s_mov_b32 m0, s50
	s_nop 0
	s_add_u32 s100, s4, 0xfffc0080
	s_addc_u32 s101, s5, -1
	global_load_lds_dwordx4 v134, s[100:101]
	s_mov_b32 m0, s51
	s_nop 0
	global_load_lds_dwordx4 v130, s[100:101]
	s_waitcnt vmcnt(8)
	s_waitcnt lgkmcnt(0)
	s_barrier
	s_setprio 1
	v_mfma_f32_16x16x32_bf16 v[60:63], v[140:143], v[214:217], v[60:63]
	v_mfma_f32_16x16x32_bf16 v[56:59], v[166:169], v[214:217], v[56:59]
	v_mfma_f32_16x16x32_bf16 v[44:47], v[140:143], v[222:225], v[44:47]
	v_mfma_f32_16x16x32_bf16 v[40:43], v[166:169], v[222:225], v[40:43]
	v_mfma_f32_16x16x32_bf16 v[28:31], v[140:143], v[230:233], v[28:31]
	v_mfma_f32_16x16x32_bf16 v[24:27], v[166:169], v[230:233], v[24:27]
	v_mfma_f32_16x16x32_bf16 v[12:15], v[140:143], v[238:241], v[12:15]
	v_mfma_f32_16x16x32_bf16 v[8:11], v[166:169], v[238:241], v[8:11]
	v_mfma_f32_16x16x32_bf16 v[60:63], v[162:165], v[218:221], v[60:63]
	v_mfma_f32_16x16x32_bf16 v[56:59], v[170:173], v[218:221], v[56:59]
	v_mfma_f32_16x16x32_bf16 v[44:47], v[162:165], v[226:229], v[44:47]
	v_mfma_f32_16x16x32_bf16 v[40:43], v[170:173], v[226:229], v[40:43]
	v_mfma_f32_16x16x32_bf16 v[28:31], v[162:165], v[234:237], v[28:31]
	v_mfma_f32_16x16x32_bf16 v[24:27], v[170:173], v[234:237], v[24:27]
	v_mfma_f32_16x16x32_bf16 v[12:15], v[162:165], v[242:245], v[12:15]
	v_mfma_f32_16x16x32_bf16 v[8:11], v[170:173], v[242:245], v[8:11]
	v_mfma_f32_16x16x32_bf16 v[52:55], v[180:183], v[214:217], v[52:55]
	v_mfma_f32_16x16x32_bf16 v[48:51], v[188:191], v[214:217], v[48:51]
	v_mfma_f32_16x16x32_bf16 v[36:39], v[180:183], v[222:225], v[36:39]
	v_mfma_f32_16x16x32_bf16 v[32:35], v[188:191], v[222:225], v[32:35]
	v_mfma_f32_16x16x32_bf16 v[20:23], v[180:183], v[230:233], v[20:23]
	v_mfma_f32_16x16x32_bf16 v[16:19], v[188:191], v[230:233], v[16:19]
	v_mfma_f32_16x16x32_bf16 v[4:7], v[180:183], v[238:241], v[4:7]
	v_mfma_f32_16x16x32_bf16 v[0:3], v[188:191], v[238:241], v[0:3]
	v_mfma_f32_16x16x32_bf16 v[52:55], v[184:187], v[218:221], v[52:55]
	v_mfma_f32_16x16x32_bf16 v[48:51], v[210:213], v[218:221], v[48:51]
	v_mfma_f32_16x16x32_bf16 v[36:39], v[184:187], v[226:229], v[36:39]
	v_mfma_f32_16x16x32_bf16 v[32:35], v[210:213], v[226:229], v[32:35]
	v_mfma_f32_16x16x32_bf16 v[20:23], v[184:187], v[234:237], v[20:23]
	v_mfma_f32_16x16x32_bf16 v[16:19], v[210:213], v[234:237], v[16:19]
	v_mfma_f32_16x16x32_bf16 v[4:7], v[184:187], v[242:245], v[4:7]
	v_mfma_f32_16x16x32_bf16 v[0:3], v[210:213], v[242:245], v[0:3]
	s_setprio 0
	s_barrier
	s_add_i32 s55, s55, 2
	s_add_u32 s0, s0, 0x100
	s_addc_u32 s1, s1, 0
	s_add_u32 s38, s38, 0x100
	s_addc_u32 s39, s39, 0
	s_cmp_gt_u32 s55, 13
; #define PG8_STAGE(bufoff, gbase, voff) do { _Pragma("unroll") for (int _i = 0; _i < 2; ++_i) \
;         __builtin_amdgcn_global_load_lds((const unsigned*)((const char*)(gbase) + (voff)[_i]), (PG8_LAS unsigned*)(lds + (bufoff) + ldsw + _i * 8192), 16, 0, 0); } while (0)
; #define PG8_LDA(dst, b, h) do { _Pragma("unroll") for (int m = 0; m < 4; ++m) _Pragma("unroll") for (int k = 0; k < 2; ++k) dst[m][k] = *(const PG8_LAS bf16x8*)(lds + PG8_SA(b, h) + aoff + m * 2048 + k * 1024); } while (0)
; #define PG8_LDB(dst, b, h) do { _Pragma("unroll") for (int n = 0; n < 2; ++n) _Pragma("unroll") for (int k = 0; k < 2; ++k) dst[n][k] = *(const PG8_LAS bf16x8*)(lds + PG8_SB(b, h) + boff + n * 2048 + k * 1024); } while (0)
; #define PG8_MMA(ai, bj, At, Bt) do { __builtin_amdgcn_s_setprio(1); _Pragma("unroll") for (int m = 0; m < 4; ++m) _Pragma("unroll") for (int n = 0; n < 2; ++n) _Pragma("unroll") for (int k = 0; k < 2; ++k) \
;         acc[ai][bj][m][n] = __builtin_amdgcn_mfma_f32_16x16x32_bf16(Bt[n][k], At[m][k], acc[ai][bj][m][n], 0, 0, 0); __builtin_amdgcn_s_setprio(0); } while (0)
; #define PG8_WAIT_V(n) asm volatile("s_waitcnt vmcnt(" #n ")" ::: "memory")
; #define PG8_WAIT_L(n) asm volatile("s_waitcnt lgkmcnt(" #n ")" ::: "memory")
; #define PG8_BAR __builtin_amdgcn_s_barrier()
; #define PG8_SCHED __builtin_amdgcn_sched_barrier(0)
; template <class Epi, class Sched, bool ALIGN_EPI = false, bool SP2 = false>
; __device__ __forceinline__ void gemm_phase(PG8_LAS unsigned char* lds, const Gemm g, const Sched& S, const Epi& E) {
;     ...
;             PG8_LDB(B0, 0, 0); PG8_LDB(B1, 0, 1); PG8_SCHED; PG8_LDA(At, 0, 0); PG8_STAGE(PG8_SA(1, 1), a1 + hstep, voffA);
;             PG8_WAIT_V(8); PG8_WAIT_L(0); PG8_BAR; PG8_MMA(0, 0, At, B0); PG8_MMA(0, 1, At, B1); PG8_BAR; PG8_SCHED;
;             PG8_LDA(At, 0, 1); PG8_STAGE(PG8_SB(0, 0), b2, voffB); PG8_STAGE(PG8_SB(0, 1), b2 + hstep, voffB); PG8_STAGE(PG8_SA(0, 0), a2, voffA);
;             PG8_WAIT_V(8); PG8_WAIT_L(0); PG8_BAR; PG8_MMA(1, 0, At, B0); PG8_MMA(1, 1, At, B1); PG8_BAR; PG8_SCHED;
.LBB0_749:
	ds_read_b128 v[140:143], v254
	ds_read_b128 v[162:165], v254 offset:1024
	ds_read_b128 v[166:169], v254 offset:2048
	ds_read_b128 v[170:173], v254 offset:3072
	ds_read_b128 v[180:183], v254 offset:16384
	ds_read_b128 v[184:187], v254 offset:17408
	ds_read_b128 v[188:191], v254 offset:18432
	ds_read_b128 v[210:213], v254 offset:19456
	s_add_u32 s2, s0, 0xfffc0080
	s_addc_u32 s3, s1, -1
	s_cmp_eq_u32 s55, 12
	s_cselect_b32 s5, s13, s3
	s_cselect_b32 s4, s25, s2
	s_cselect_b32 s3, s23, s39
	s_cselect_b32 s2, s33, s38
	s_add_i32 m0, s6, 0xc000
	ds_read_b128 v[214:217], v178
	ds_read_b128 v[218:221], v178 offset:1024
	ds_read_b128 v[222:225], v178 offset:2048
	ds_read_b128 v[226:229], v178 offset:3072
	ds_read_b128 v[230:233], v178 offset:4096
	ds_read_b128 v[234:237], v178 offset:5120
	ds_read_b128 v[238:241], v178 offset:6144
	ds_read_b128 v[242:245], v178 offset:7168
	global_load_lds_dwordx4 v136, s[0:1]
	s_add_i32 m0, s6, 0xe000
	s_nop 0
	global_load_lds_dwordx4 v138, s[0:1]
	s_waitcnt vmcnt(8)
	s_waitcnt lgkmcnt(0)
	s_barrier
	s_setprio 1
	v_mfma_f32_16x16x32_bf16 v[124:127], v[140:143], v[214:217], v[124:127]
	v_mfma_f32_16x16x32_bf16 v[120:123], v[166:169], v[214:217], v[120:123]
	v_mfma_f32_16x16x32_bf16 v[108:111], v[140:143], v[222:225], v[108:111]
	v_mfma_f32_16x16x32_bf16 v[104:107], v[166:169], v[222:225], v[104:107]
	v_mfma_f32_16x16x32_bf16 v[92:95], v[140:143], v[230:233], v[92:95]
	v_mfma_f32_16x16x32_bf16 v[88:91], v[166:169], v[230:233], v[88:91]
	v_mfma_f32_16x16x32_bf16 v[76:79], v[140:143], v[238:241], v[76:79]
	v_mfma_f32_16x16x32_bf16 v[72:75], v[166:169], v[238:241], v[72:75]
	v_mfma_f32_16x16x32_bf16 v[124:127], v[162:165], v[218:221], v[124:127]
	v_mfma_f32_16x16x32_bf16 v[120:123], v[170:173], v[218:221], v[120:123]
	v_mfma_f32_16x16x32_bf16 v[108:111], v[162:165], v[226:229], v[108:111]
	v_mfma_f32_16x16x32_bf16 v[104:107], v[170:173], v[226:229], v[104:107]
	v_mfma_f32_16x16x32_bf16 v[92:95], v[162:165], v[234:237], v[92:95]
	v_mfma_f32_16x16x32_bf16 v[88:91], v[170:173], v[234:237], v[88:91]
	v_mfma_f32_16x16x32_bf16 v[76:79], v[162:165], v[242:245], v[76:79]
	v_mfma_f32_16x16x32_bf16 v[72:75], v[170:173], v[242:245], v[72:75]
	v_mfma_f32_16x16x32_bf16 v[116:119], v[180:183], v[214:217], v[116:119]
	v_mfma_f32_16x16x32_bf16 v[112:115], v[188:191], v[214:217], v[112:115]
	v_mfma_f32_16x16x32_bf16 v[100:103], v[180:183], v[222:225], v[100:103]
	v_mfma_f32_16x16x32_bf16 v[96:99], v[188:191], v[222:225], v[96:99]
	v_mfma_f32_16x16x32_bf16 v[84:87], v[180:183], v[230:233], v[84:87]
	v_mfma_f32_16x16x32_bf16 v[80:83], v[188:191], v[230:233], v[80:83]
	v_mfma_f32_16x16x32_bf16 v[68:71], v[180:183], v[238:241], v[68:71]
	v_mfma_f32_16x16x32_bf16 v[64:67], v[188:191], v[238:241], v[64:67]
	v_mfma_f32_16x16x32_bf16 v[116:119], v[184:187], v[218:221], v[116:119]
	v_mfma_f32_16x16x32_bf16 v[112:115], v[210:213], v[218:221], v[112:115]
	v_mfma_f32_16x16x32_bf16 v[100:103], v[184:187], v[226:229], v[100:103]
	v_mfma_f32_16x16x32_bf16 v[96:99], v[210:213], v[226:229], v[96:99]
	v_mfma_f32_16x16x32_bf16 v[84:87], v[184:187], v[234:237], v[84:87]
	v_mfma_f32_16x16x32_bf16 v[80:83], v[210:213], v[234:237], v[80:83]
	v_mfma_f32_16x16x32_bf16 v[68:71], v[184:187], v[242:245], v[68:71]
	v_mfma_f32_16x16x32_bf16 v[64:67], v[210:213], v[242:245], v[64:67]
	s_setprio 0
	s_barrier
	s_mov_b32 m0, s31
	s_add_u32 s56, s2, 0x40000
	s_addc_u32 s57, s3, 0
	ds_read_b128 v[214:217], v178 offset:16384
	ds_read_b128 v[218:221], v178 offset:17408
	ds_read_b128 v[222:225], v178 offset:18432
	ds_read_b128 v[226:229], v178 offset:19456
	ds_read_b128 v[230:233], v178 offset:20480
	ds_read_b128 v[234:237], v178 offset:21504
	ds_read_b128 v[238:241], v178 offset:22528
	ds_read_b128 v[242:245], v178 offset:23552
	global_load_lds_dwordx4 v132, s[2:3]
	s_mov_b32 m0, s34
	s_nop 0
	global_load_lds_dwordx4 v128, s[2:3]
	s_mov_b32 m0, s35
	s_nop 0
	global_load_lds_dwordx4 v132, s[56:57]
	s_mov_b32 m0, s40
	s_nop 0
	global_load_lds_dwordx4 v128, s[56:57]
	s_mov_b32 m0, s6
	s_nop 0
	global_load_lds_dwordx4 v134, s[4:5]
	s_mov_b32 m0, s41
	s_nop 0
	global_load_lds_dwordx4 v130, s[4:5]
	s_waitcnt vmcnt(8)
	s_waitcnt lgkmcnt(0)
	s_barrier
	s_setprio 1
	v_mfma_f32_16x16x32_bf16 v[60:63], v[140:143], v[214:217], v[60:63]
	v_mfma_f32_16x16x32_bf16 v[56:59], v[166:169], v[214:217], v[56:59]
	v_mfma_f32_16x16x32_bf16 v[44:47], v[140:143], v[222:225], v[44:47]
	v_mfma_f32_16x16x32_bf16 v[40:43], v[166:169], v[222:225], v[40:43]
	v_mfma_f32_16x16x32_bf16 v[28:31], v[140:143], v[230:233], v[28:31]
	v_mfma_f32_16x16x32_bf16 v[24:27], v[166:169], v[230:233], v[24:27]
	v_mfma_f32_16x16x32_bf16 v[12:15], v[140:143], v[238:241], v[12:15]
	v_mfma_f32_16x16x32_bf16 v[8:11], v[166:169], v[238:241], v[8:11]
	v_mfma_f32_16x16x32_bf16 v[60:63], v[162:165], v[218:221], v[60:63]
	v_mfma_f32_16x16x32_bf16 v[56:59], v[170:173], v[218:221], v[56:59]
	v_mfma_f32_16x16x32_bf16 v[44:47], v[162:165], v[226:229], v[44:47]
	v_mfma_f32_16x16x32_bf16 v[40:43], v[170:173], v[226:229], v[40:43]
	v_mfma_f32_16x16x32_bf16 v[28:31], v[162:165], v[234:237], v[28:31]
	v_mfma_f32_16x16x32_bf16 v[24:27], v[170:173], v[234:237], v[24:27]
	v_mfma_f32_16x16x32_bf16 v[12:15], v[162:165], v[242:245], v[12:15]
	v_mfma_f32_16x16x32_bf16 v[8:11], v[170:173], v[242:245], v[8:11]
	v_mfma_f32_16x16x32_bf16 v[52:55], v[180:183], v[214:217], v[52:55]
	v_mfma_f32_16x16x32_bf16 v[48:51], v[188:191], v[214:217], v[48:51]
	v_mfma_f32_16x16x32_bf16 v[36:39], v[180:183], v[222:225], v[36:39]
	v_mfma_f32_16x16x32_bf16 v[32:35], v[188:191], v[222:225], v[32:35]
	v_mfma_f32_16x16x32_bf16 v[20:23], v[180:183], v[230:233], v[20:23]
	v_mfma_f32_16x16x32_bf16 v[16:19], v[188:191], v[230:233], v[16:19]
	v_mfma_f32_16x16x32_bf16 v[4:7], v[180:183], v[238:241], v[4:7]
	v_mfma_f32_16x16x32_bf16 v[0:3], v[188:191], v[238:241], v[0:3]
	v_mfma_f32_16x16x32_bf16 v[52:55], v[184:187], v[218:221], v[52:55]
	v_mfma_f32_16x16x32_bf16 v[48:51], v[210:213], v[218:221], v[48:51]
	v_mfma_f32_16x16x32_bf16 v[36:39], v[184:187], v[226:229], v[36:39]
	v_mfma_f32_16x16x32_bf16 v[32:35], v[210:213], v[226:229], v[32:35]
	v_mfma_f32_16x16x32_bf16 v[20:23], v[184:187], v[234:237], v[20:23]
	v_mfma_f32_16x16x32_bf16 v[16:19], v[210:213], v[234:237], v[16:19]
	v_mfma_f32_16x16x32_bf16 v[4:7], v[184:187], v[242:245], v[4:7]
	v_mfma_f32_16x16x32_bf16 v[0:3], v[210:213], v[242:245], v[0:3]
	s_setprio 0
	s_barrier
; #define PG8_STAGE(bufoff, gbase, voff) do { _Pragma("unroll") for (int _i = 0; _i < 2; ++_i) \
;         __builtin_amdgcn_global_load_lds((const unsigned*)((const char*)(gbase) + (voff)[_i]), (PG8_LAS unsigned*)(lds + (bufoff) + ldsw + _i * 8192), 16, 0, 0); } while (0)
; #define PG8_LDA(dst, b, h) do { _Pragma("unroll") for (int m = 0; m < 4; ++m) _Pragma("unroll") for (int k = 0; k < 2; ++k) dst[m][k] = *(const PG8_LAS bf16x8*)(lds + PG8_SA(b, h) + aoff + m * 2048 + k * 1024); } while (0)
; #define PG8_LDB(dst, b, h) do { _Pragma("unroll") for (int n = 0; n < 2; ++n) _Pragma("unroll") for (int k = 0; k < 2; ++k) dst[n][k] = *(const PG8_LAS bf16x8*)(lds + PG8_SB(b, h) + boff + n * 2048 + k * 1024); } while (0)
; #define PG8_MMA(ai, bj, At, Bt) do { __builtin_amdgcn_s_setprio(1); _Pragma("unroll") for (int m = 0; m < 4; ++m) _Pragma("unroll") for (int n = 0; n < 2; ++n) _Pragma("unroll") for (int k = 0; k < 2; ++k) \
;         acc[ai][bj][m][n] = __builtin_amdgcn_mfma_f32_16x16x32_bf16(Bt[n][k], At[m][k], acc[ai][bj][m][n], 0, 0, 0); __builtin_amdgcn_s_setprio(0); } while (0)
; #define PG8_WAIT_V(n) asm volatile("s_waitcnt vmcnt(" #n ")" ::: "memory")
; #define PG8_WAIT_L(n) asm volatile("s_waitcnt lgkmcnt(" #n ")" ::: "memory")
; #define PG8_BAR __builtin_amdgcn_s_barrier()
; #define PG8_SCHED __builtin_amdgcn_sched_barrier(0)
; template <class Epi, class Sched, bool ALIGN_EPI = false, bool SP2 = false>
; __device__ __forceinline__ void gemm_phase(PG8_LAS unsigned char* lds, const Gemm g, const Sched& S, const Epi& E) {
;     ...
;             PG8_LDB(B0, 1, 0); PG8_LDB(B1, 1, 1); PG8_SCHED; PG8_LDA(At, 1, 0); PG8_STAGE(PG8_SA(0, 1), a2 + hstep, voffA);
;             PG8_WAIT_V(8); PG8_WAIT_L(0); PG8_BAR; PG8_MMA(0, 0, At, B0); PG8_MMA(0, 1, At, B1); PG8_BAR; PG8_SCHED;
;             PG8_LDA(At, 1, 1); PG8_STAGE(PG8_SB(1, 0), b3, voffB); PG8_STAGE(PG8_SB(1, 1), b3 + hstep, voffB); PG8_STAGE(PG8_SA(1, 0), a3, voffA);
;             PG8_WAIT_V(8); PG8_WAIT_L(0); PG8_BAR; PG8_MMA(1, 0, At, B0); PG8_MMA(1, 1, At, B1); PG8_BAR; PG8_SCHED;
;     ...
;         if constexpr (ALIGN_EPI) { if (wr == 0) PG8_BAR; }
	ds_read_b128 v[140:143], v254 offset:32768
	ds_read_b128 v[162:165], v254 offset:33792
	ds_read_b128 v[166:169], v254 offset:34816
	ds_read_b128 v[170:173], v254 offset:35840
	ds_read_b128 v[180:183], v254 offset:49152
	ds_read_b128 v[184:187], v254 offset:50176
	ds_read_b128 v[188:191], v254 offset:51200
	ds_read_b128 v[210:213], v254 offset:52224
	s_add_u32 s4, s4, 0x40000
	s_addc_u32 s5, s5, 0
	s_mov_b32 m0, s42
	ds_read_b128 v[214:217], v178 offset:32768
	ds_read_b128 v[218:221], v178 offset:33792
	ds_read_b128 v[222:225], v178 offset:34816
	ds_read_b128 v[226:229], v178 offset:35840
	ds_read_b128 v[230:233], v178 offset:36864
	ds_read_b128 v[234:237], v178 offset:37888
	ds_read_b128 v[238:241], v178 offset:38912
	ds_read_b128 v[242:245], v178 offset:39936
	global_load_lds_dwordx4 v134, s[4:5]
	s_mov_b32 m0, s43
	s_nop 0
	global_load_lds_dwordx4 v130, s[4:5]
	s_waitcnt vmcnt(8)
	s_waitcnt lgkmcnt(0)
	s_barrier
	s_setprio 1
	v_mfma_f32_16x16x32_bf16 v[124:127], v[140:143], v[214:217], v[124:127]
	v_mfma_f32_16x16x32_bf16 v[120:123], v[166:169], v[214:217], v[120:123]
	v_mfma_f32_16x16x32_bf16 v[108:111], v[140:143], v[222:225], v[108:111]
	v_mfma_f32_16x16x32_bf16 v[104:107], v[166:169], v[222:225], v[104:107]
	v_mfma_f32_16x16x32_bf16 v[92:95], v[140:143], v[230:233], v[92:95]
	v_mfma_f32_16x16x32_bf16 v[88:91], v[166:169], v[230:233], v[88:91]
	v_mfma_f32_16x16x32_bf16 v[76:79], v[140:143], v[238:241], v[76:79]
	v_mfma_f32_16x16x32_bf16 v[72:75], v[166:169], v[238:241], v[72:75]
	v_mfma_f32_16x16x32_bf16 v[124:127], v[162:165], v[218:221], v[124:127]
	v_mfma_f32_16x16x32_bf16 v[120:123], v[170:173], v[218:221], v[120:123]
	v_mfma_f32_16x16x32_bf16 v[108:111], v[162:165], v[226:229], v[108:111]
	v_mfma_f32_16x16x32_bf16 v[104:107], v[170:173], v[226:229], v[104:107]
	v_mfma_f32_16x16x32_bf16 v[92:95], v[162:165], v[234:237], v[92:95]
	v_mfma_f32_16x16x32_bf16 v[88:91], v[170:173], v[234:237], v[88:91]
	v_mfma_f32_16x16x32_bf16 v[76:79], v[162:165], v[242:245], v[76:79]
	v_mfma_f32_16x16x32_bf16 v[72:75], v[170:173], v[242:245], v[72:75]
	v_mfma_f32_16x16x32_bf16 v[116:119], v[180:183], v[214:217], v[116:119]
	v_mfma_f32_16x16x32_bf16 v[112:115], v[188:191], v[214:217], v[112:115]
	v_mfma_f32_16x16x32_bf16 v[100:103], v[180:183], v[222:225], v[100:103]
	v_mfma_f32_16x16x32_bf16 v[96:99], v[188:191], v[222:225], v[96:99]
	v_mfma_f32_16x16x32_bf16 v[84:87], v[180:183], v[230:233], v[84:87]
	v_mfma_f32_16x16x32_bf16 v[80:83], v[188:191], v[230:233], v[80:83]
	v_mfma_f32_16x16x32_bf16 v[68:71], v[180:183], v[238:241], v[68:71]
	v_mfma_f32_16x16x32_bf16 v[64:67], v[188:191], v[238:241], v[64:67]
	v_mfma_f32_16x16x32_bf16 v[116:119], v[184:187], v[218:221], v[116:119]
	v_mfma_f32_16x16x32_bf16 v[112:115], v[210:213], v[218:221], v[112:115]
	v_mfma_f32_16x16x32_bf16 v[100:103], v[184:187], v[226:229], v[100:103]
	v_mfma_f32_16x16x32_bf16 v[96:99], v[210:213], v[226:229], v[96:99]
	v_mfma_f32_16x16x32_bf16 v[84:87], v[184:187], v[234:237], v[84:87]
	v_mfma_f32_16x16x32_bf16 v[80:83], v[210:213], v[234:237], v[80:83]
	v_mfma_f32_16x16x32_bf16 v[68:71], v[184:187], v[242:245], v[68:71]
	v_mfma_f32_16x16x32_bf16 v[64:67], v[210:213], v[242:245], v[64:67]
	s_setprio 0
	s_barrier
	s_mov_b32 m0, s48
	s_add_u32 s2, s2, 0x40080
	s_addc_u32 s3, s3, 0
	ds_read_b128 v[214:217], v178 offset:49152
	ds_read_b128 v[218:221], v178 offset:50176
	ds_read_b128 v[222:225], v178 offset:51200
	ds_read_b128 v[226:229], v178 offset:52224
	ds_read_b128 v[230:233], v178 offset:53248
	ds_read_b128 v[234:237], v178 offset:54272
	ds_read_b128 v[238:241], v178 offset:55296
	ds_read_b128 v[242:245], v178 offset:56320
	s_add_u32 s98, s2, 0xfffc0000
	s_addc_u32 s99, s3, -1
	global_load_lds_dwordx4 v132, s[98:99]
	s_mov_b32 m0, s49
	s_nop 0
	global_load_lds_dwordx4 v128, s[98:99]
	s_mov_b32 m0, s52
	s_nop 0
	global_load_lds_dwordx4 v132, s[2:3]
	s_mov_b32 m0, s53
	s_nop 0
	global_load_lds_dwordx4 v128, s[2:3]
	s_mov_b32 m0, s50
	s_nop 0
	s_add_u32 s100, s4, 0xfffc0080
	s_addc_u32 s101, s5, -1
	global_load_lds_dwordx4 v134, s[100:101]
	s_mov_b32 m0, s51
	s_nop 0
	global_load_lds_dwordx4 v130, s[100:101]
	s_waitcnt vmcnt(8)
	s_waitcnt lgkmcnt(0)
	s_barrier
	s_setprio 1
	v_mfma_f32_16x16x32_bf16 v[60:63], v[140:143], v[214:217], v[60:63]
	v_mfma_f32_16x16x32_bf16 v[56:59], v[166:169], v[214:217], v[56:59]
	v_mfma_f32_16x16x32_bf16 v[44:47], v[140:143], v[222:225], v[44:47]
	v_mfma_f32_16x16x32_bf16 v[40:43], v[166:169], v[222:225], v[40:43]
	v_mfma_f32_16x16x32_bf16 v[28:31], v[140:143], v[230:233], v[28:31]
	v_mfma_f32_16x16x32_bf16 v[24:27], v[166:169], v[230:233], v[24:27]
	v_mfma_f32_16x16x32_bf16 v[12:15], v[140:143], v[238:241], v[12:15]
	v_mfma_f32_16x16x32_bf16 v[8:11], v[166:169], v[238:241], v[8:11]
	v_mfma_f32_16x16x32_bf16 v[60:63], v[162:165], v[218:221], v[60:63]
	v_mfma_f32_16x16x32_bf16 v[56:59], v[170:173], v[218:221], v[56:59]
	v_mfma_f32_16x16x32_bf16 v[44:47], v[162:165], v[226:229], v[44:47]
	v_mfma_f32_16x16x32_bf16 v[40:43], v[170:173], v[226:229], v[40:43]
	v_mfma_f32_16x16x32_bf16 v[28:31], v[162:165], v[234:237], v[28:31]
	v_mfma_f32_16x16x32_bf16 v[24:27], v[170:173], v[234:237], v[24:27]
	v_mfma_f32_16x16x32_bf16 v[12:15], v[162:165], v[242:245], v[12:15]
	v_mfma_f32_16x16x32_bf16 v[8:11], v[170:173], v[242:245], v[8:11]
	v_mfma_f32_16x16x32_bf16 v[52:55], v[180:183], v[214:217], v[52:55]
	v_mfma_f32_16x16x32_bf16 v[48:51], v[188:191], v[214:217], v[48:51]
	v_mfma_f32_16x16x32_bf16 v[36:39], v[180:183], v[222:225], v[36:39]
	v_mfma_f32_16x16x32_bf16 v[32:35], v[188:191], v[222:225], v[32:35]
	v_mfma_f32_16x16x32_bf16 v[20:23], v[180:183], v[230:233], v[20:23]
	v_mfma_f32_16x16x32_bf16 v[16:19], v[188:191], v[230:233], v[16:19]
	v_mfma_f32_16x16x32_bf16 v[4:7], v[180:183], v[238:241], v[4:7]
	v_mfma_f32_16x16x32_bf16 v[0:3], v[188:191], v[238:241], v[0:3]
	v_mfma_f32_16x16x32_bf16 v[52:55], v[184:187], v[218:221], v[52:55]
	v_mfma_f32_16x16x32_bf16 v[48:51], v[210:213], v[218:221], v[48:51]
	v_mfma_f32_16x16x32_bf16 v[36:39], v[184:187], v[226:229], v[36:39]
	v_mfma_f32_16x16x32_bf16 v[32:35], v[210:213], v[226:229], v[32:35]
	v_mfma_f32_16x16x32_bf16 v[20:23], v[184:187], v[234:237], v[20:23]
	v_mfma_f32_16x16x32_bf16 v[16:19], v[210:213], v[234:237], v[16:19]
	v_mfma_f32_16x16x32_bf16 v[4:7], v[184:187], v[242:245], v[4:7]
	v_mfma_f32_16x16x32_bf16 v[0:3], v[210:213], v[242:245], v[0:3]
	s_setprio 0
	s_barrier
	s_add_i32 s55, s55, 2
	s_add_u32 s0, s0, 0x100
	s_addc_u32 s1, s1, 0
	s_add_u32 s38, s38, 0x100
	s_addc_u32 s39, s39, 0
	s_cmp_gt_u32 s55, 13
	s_cbranch_scc0 .LBB0_749
	s_and_b64 vcc, exec, s[18:19]
	s_cbranch_vccz .LBB0_752
	s_barrier

; #define PG8_STAGE(bufoff, gbase, voff) do { _Pragma("unroll") for (int _i = 0; _i < 2; ++_i) \
;         __builtin_amdgcn_global_load_lds((const unsigned*)((const char*)(gbase) + (voff)[_i]), (PG8_LAS unsigned*)(lds + (bufoff) + ldsw + _i * 8192), 16, 0, 0); } while (0)
; #define PG8_LDA(dst, b, h) do { _Pragma("unroll") for (int m = 0; m < 4; ++m) _Pragma("unroll") for (int k = 0; k < 2; ++k) dst[m][k] = *(const PG8_LAS bf16x8*)(lds + PG8_SA(b, h) + aoff + m * 2048 + k * 1024); } while (0)
; #define PG8_LDB(dst, b, h) do { _Pragma("unroll") for (int n = 0; n < 2; ++n) _Pragma("unroll") for (int k = 0; k < 2; ++k) dst[n][k] = *(const PG8_LAS bf16x8*)(lds + PG8_SB(b, h) + boff + n * 2048 + k * 1024); } while (0)
; #define PG8_MMA(ai, bj, At, Bt) do { __builtin_amdgcn_s_setprio(1); _Pragma("unroll") for (int m = 0; m < 4; ++m) _Pragma("unroll") for (int n = 0; n < 2; ++n) _Pragma("unroll") for (int k = 0; k < 2; ++k) \
;         acc[ai][bj][m][n] = __builtin_amdgcn_mfma_f32_16x16x32_bf16(Bt[n][k], At[m][k], acc[ai][bj][m][n], 0, 0, 0); __builtin_amdgcn_s_setprio(0); } while (0)
; #define PG8_WAIT_V(n) asm volatile("s_waitcnt vmcnt(" #n ")" ::: "memory")
; #define PG8_WAIT_L(n) asm volatile("s_waitcnt lgkmcnt(" #n ")" ::: "memory")
; #define PG8_BAR __builtin_amdgcn_s_barrier()
; #define PG8_SCHED __builtin_amdgcn_sched_barrier(0)
; template <class Epi, class Sched, bool ALIGN_EPI = false, bool SP2 = false>
; __device__ __forceinline__ void gemm_phase(PG8_LAS unsigned char* lds, const Gemm g, const Sched& S, const Epi& E) {
;     ...
;             PG8_LDB(B0, 0, 0); PG8_LDB(B1, 0, 1); PG8_SCHED; PG8_LDA(At, 0, 0); PG8_STAGE(PG8_SA(1, 1), a1 + hstep, voffA);
;             PG8_WAIT_V(8); PG8_WAIT_L(0); PG8_BAR; PG8_MMA(0, 0, At, B0); PG8_MMA(0, 1, At, B1); PG8_BAR; PG8_SCHED;
;             PG8_LDA(At, 0, 1); PG8_STAGE(PG8_SB(0, 0), b2, voffB); PG8_STAGE(PG8_SB(0, 1), b2 + hstep, voffB); PG8_STAGE(PG8_SA(0, 0), a2, voffA);
;             PG8_WAIT_V(8); PG8_WAIT_L(0); PG8_BAR; PG8_MMA(1, 0, At, B0); PG8_MMA(1, 1, At, B1); PG8_BAR; PG8_SCHED;
.Labi_peel:
	s_waitcnt lgkmcnt(0)
	ds_read_b128 v[140:143], v254
	ds_read_b128 v[162:165], v254 offset:1024
	ds_read_b128 v[166:169], v254 offset:2048
	ds_read_b128 v[176:179], v254 offset:3072
	ds_read_b128 v[180:183], v254 offset:16384
	ds_read_b128 v[184:187], v254 offset:17408
	ds_read_b128 v[188:191], v254 offset:18432
	ds_read_b128 v[210:213], v254 offset:19456
	s_add_u32 s2, s0, 0xfffc0080
	s_addc_u32 s3, s1, -1
	s_cmp_eq_u32 s52, 12
	s_cselect_b32 s5, s17, s3
	s_cselect_b32 s4, s48, s2
	s_cselect_b32 s3, s15, s51
	s_cselect_b32 s2, s49, s50
	s_add_i32 m0, s6, 0xc000
	ds_read_b128 v[214:217], v173
	ds_read_b128 v[218:221], v173 offset:1024
	ds_read_b128 v[222:225], v173 offset:2048
	ds_read_b128 v[226:229], v173 offset:3072
	ds_read_b128 v[230:233], v173 offset:4096
	ds_read_b128 v[234:237], v173 offset:5120
	ds_read_b128 v[238:241], v173 offset:6144
	ds_read_b128 v[242:245], v173 offset:7168
	global_load_lds_dwordx4 v136, s[0:1]
	s_add_i32 m0, s6, 0xe000
	s_nop 0
	global_load_lds_dwordx4 v138, s[0:1]
	s_waitcnt vmcnt(8)
	s_waitcnt lgkmcnt(0)
	s_barrier
	s_setprio 1
	v_mfma_f32_16x16x32_bf16 v[124:127], v[140:143], v[214:217], 0
	v_mfma_f32_16x16x32_bf16 v[120:123], v[166:169], v[214:217], 0
	v_mfma_f32_16x16x32_bf16 v[112:115], v[140:143], v[222:225], 0
	v_mfma_f32_16x16x32_bf16 v[104:107], v[166:169], v[222:225], 0
	v_mfma_f32_16x16x32_bf16 v[96:99], v[140:143], v[230:233], 0
	v_mfma_f32_16x16x32_bf16 v[88:91], v[166:169], v[230:233], 0
	v_mfma_f32_16x16x32_bf16 v[80:83], v[140:143], v[238:241], 0
	v_mfma_f32_16x16x32_bf16 v[72:75], v[166:169], v[238:241], 0
	v_mfma_f32_16x16x32_bf16 v[124:127], v[162:165], v[218:221], v[124:127]
	v_mfma_f32_16x16x32_bf16 v[120:123], v[176:179], v[218:221], v[120:123]
	v_mfma_f32_16x16x32_bf16 v[112:115], v[162:165], v[226:229], v[112:115]
	v_mfma_f32_16x16x32_bf16 v[104:107], v[176:179], v[226:229], v[104:107]
	v_mfma_f32_16x16x32_bf16 v[96:99], v[162:165], v[234:237], v[96:99]
	v_mfma_f32_16x16x32_bf16 v[88:91], v[176:179], v[234:237], v[88:91]
	v_mfma_f32_16x16x32_bf16 v[80:83], v[162:165], v[242:245], v[80:83]
	v_mfma_f32_16x16x32_bf16 v[72:75], v[176:179], v[242:245], v[72:75]
	v_mfma_f32_16x16x32_bf16 v[116:119], v[180:183], v[214:217], 0
	v_mfma_f32_16x16x32_bf16 v[108:111], v[188:191], v[214:217], 0
	v_mfma_f32_16x16x32_bf16 v[100:103], v[180:183], v[222:225], 0
	v_mfma_f32_16x16x32_bf16 v[92:95], v[188:191], v[222:225], 0
	v_mfma_f32_16x16x32_bf16 v[84:87], v[180:183], v[230:233], 0
	v_mfma_f32_16x16x32_bf16 v[76:79], v[188:191], v[230:233], 0
	v_mfma_f32_16x16x32_bf16 v[68:71], v[180:183], v[238:241], 0
	v_mfma_f32_16x16x32_bf16 v[64:67], v[188:191], v[238:241], 0
	v_mfma_f32_16x16x32_bf16 v[116:119], v[184:187], v[218:221], v[116:119]
	v_mfma_f32_16x16x32_bf16 v[108:111], v[210:213], v[218:221], v[108:111]
	v_mfma_f32_16x16x32_bf16 v[100:103], v[184:187], v[226:229], v[100:103]
	v_mfma_f32_16x16x32_bf16 v[92:95], v[210:213], v[226:229], v[92:95]
	v_mfma_f32_16x16x32_bf16 v[84:87], v[184:187], v[234:237], v[84:87]
	v_mfma_f32_16x16x32_bf16 v[76:79], v[210:213], v[234:237], v[76:79]
	v_mfma_f32_16x16x32_bf16 v[68:71], v[184:187], v[242:245], v[68:71]
	v_mfma_f32_16x16x32_bf16 v[64:67], v[210:213], v[242:245], v[64:67]
	s_setprio 0
	s_barrier
	s_mov_b32 m0, s27
	s_add_u32 s54, s2, 0x40000
	s_addc_u32 s55, s3, 0
	ds_read_b128 v[214:217], v173 offset:16384
	ds_read_b128 v[218:221], v173 offset:17408
	ds_read_b128 v[222:225], v173 offset:18432
	ds_read_b128 v[226:229], v173 offset:19456
	ds_read_b128 v[230:233], v173 offset:20480
	ds_read_b128 v[234:237], v173 offset:21504
	ds_read_b128 v[238:241], v173 offset:22528
	ds_read_b128 v[242:245], v173 offset:23552
	global_load_lds_dwordx4 v132, s[2:3]
	s_mov_b32 m0, s28
	s_nop 0
	global_load_lds_dwordx4 v128, s[2:3]
	s_mov_b32 m0, s29
	s_nop 0
	global_load_lds_dwordx4 v132, s[54:55]
	s_mov_b32 m0, s30
	s_nop 0
	global_load_lds_dwordx4 v128, s[54:55]
	s_mov_b32 m0, s6
	s_nop 0
	global_load_lds_dwordx4 v134, s[4:5]
	s_mov_b32 m0, s31
	s_nop 0
	global_load_lds_dwordx4 v130, s[4:5]
	s_waitcnt vmcnt(8)
	s_waitcnt lgkmcnt(0)
	s_barrier
	s_setprio 1
	v_mfma_f32_16x16x32_bf16 v[60:63], v[140:143], v[214:217], 0
	v_mfma_f32_16x16x32_bf16 v[56:59], v[166:169], v[214:217], 0
	v_mfma_f32_16x16x32_bf16 v[48:51], v[140:143], v[222:225], 0
	v_mfma_f32_16x16x32_bf16 v[40:43], v[166:169], v[222:225], 0
	v_mfma_f32_16x16x32_bf16 v[32:35], v[140:143], v[230:233], 0
	v_mfma_f32_16x16x32_bf16 v[24:27], v[166:169], v[230:233], 0
	v_mfma_f32_16x16x32_bf16 v[16:19], v[140:143], v[238:241], 0
	v_mfma_f32_16x16x32_bf16 v[8:11], v[166:169], v[238:241], 0
	v_mfma_f32_16x16x32_bf16 v[60:63], v[162:165], v[218:221], v[60:63]
	v_mfma_f32_16x16x32_bf16 v[56:59], v[176:179], v[218:221], v[56:59]
	v_mfma_f32_16x16x32_bf16 v[48:51], v[162:165], v[226:229], v[48:51]
	v_mfma_f32_16x16x32_bf16 v[40:43], v[176:179], v[226:229], v[40:43]
	v_mfma_f32_16x16x32_bf16 v[32:35], v[162:165], v[234:237], v[32:35]
	v_mfma_f32_16x16x32_bf16 v[24:27], v[176:179], v[234:237], v[24:27]
	v_mfma_f32_16x16x32_bf16 v[16:19], v[162:165], v[242:245], v[16:19]
	v_mfma_f32_16x16x32_bf16 v[8:11], v[176:179], v[242:245], v[8:11]
	v_mfma_f32_16x16x32_bf16 v[52:55], v[180:183], v[214:217], 0
	v_mfma_f32_16x16x32_bf16 v[44:47], v[188:191], v[214:217], 0
	v_mfma_f32_16x16x32_bf16 v[36:39], v[180:183], v[222:225], 0
	v_mfma_f32_16x16x32_bf16 v[28:31], v[188:191], v[222:225], 0
	v_mfma_f32_16x16x32_bf16 v[20:23], v[180:183], v[230:233], 0
	v_mfma_f32_16x16x32_bf16 v[12:15], v[188:191], v[230:233], 0
	v_mfma_f32_16x16x32_bf16 v[4:7], v[180:183], v[238:241], 0
	v_mfma_f32_16x16x32_bf16 v[0:3], v[188:191], v[238:241], 0
	v_mfma_f32_16x16x32_bf16 v[52:55], v[184:187], v[218:221], v[52:55]
	v_mfma_f32_16x16x32_bf16 v[44:47], v[210:213], v[218:221], v[44:47]
	v_mfma_f32_16x16x32_bf16 v[36:39], v[184:187], v[226:229], v[36:39]
	v_mfma_f32_16x16x32_bf16 v[28:31], v[210:213], v[226:229], v[28:31]
	v_mfma_f32_16x16x32_bf16 v[20:23], v[184:187], v[234:237], v[20:23]
	v_mfma_f32_16x16x32_bf16 v[12:15], v[210:213], v[234:237], v[12:15]
	v_mfma_f32_16x16x32_bf16 v[4:7], v[184:187], v[242:245], v[4:7]
	v_mfma_f32_16x16x32_bf16 v[0:3], v[210:213], v[242:245], v[0:3]
	s_setprio 0
	s_barrier
; #define PG8_STAGE(bufoff, gbase, voff) do { _Pragma("unroll") for (int _i = 0; _i < 2; ++_i) \
;         __builtin_amdgcn_global_load_lds((const unsigned*)((const char*)(gbase) + (voff)[_i]), (PG8_LAS unsigned*)(lds + (bufoff) + ldsw + _i * 8192), 16, 0, 0); } while (0)
; #define PG8_LDA(dst, b, h) do { _Pragma("unroll") for (int m = 0; m < 4; ++m) _Pragma("unroll") for (int k = 0; k < 2; ++k) dst[m][k] = *(const PG8_LAS bf16x8*)(lds + PG8_SA(b, h) + aoff + m * 2048 + k * 1024); } while (0)
; #define PG8_LDB(dst, b, h) do { _Pragma("unroll") for (int n = 0; n < 2; ++n) _Pragma("unroll") for (int k = 0; k < 2; ++k) dst[n][k] = *(const PG8_LAS bf16x8*)(lds + PG8_SB(b, h) + boff + n * 2048 + k * 1024); } while (0)
; #define PG8_MMA(ai, bj, At, Bt) do { __builtin_amdgcn_s_setprio(1); _Pragma("unroll") for (int m = 0; m < 4; ++m) _Pragma("unroll") for (int n = 0; n < 2; ++n) _Pragma("unroll") for (int k = 0; k < 2; ++k) \
;         acc[ai][bj][m][n] = __builtin_amdgcn_mfma_f32_16x16x32_bf16(Bt[n][k], At[m][k], acc[ai][bj][m][n], 0, 0, 0); __builtin_amdgcn_s_setprio(0); } while (0)
; #define PG8_WAIT_V(n) asm volatile("s_waitcnt vmcnt(" #n ")" ::: "memory")
; #define PG8_WAIT_L(n) asm volatile("s_waitcnt lgkmcnt(" #n ")" ::: "memory")
; #define PG8_BAR __builtin_amdgcn_s_barrier()
; #define PG8_SCHED __builtin_amdgcn_sched_barrier(0)
; template <class Epi, class Sched, bool ALIGN_EPI = false, bool SP2 = false>
; __device__ __forceinline__ void gemm_phase(PG8_LAS unsigned char* lds, const Gemm g, const Sched& S, const Epi& E) {
;     ...
;             PG8_LDB(B0, 1, 0); PG8_LDB(B1, 1, 1); PG8_SCHED; PG8_LDA(At, 1, 0); PG8_STAGE(PG8_SA(0, 1), a2 + hstep, voffA);
;             PG8_WAIT_V(8); PG8_WAIT_L(0); PG8_BAR; PG8_MMA(0, 0, At, B0); PG8_MMA(0, 1, At, B1); PG8_BAR; PG8_SCHED;
;             PG8_LDA(At, 1, 1); PG8_STAGE(PG8_SB(1, 0), b3, voffB); PG8_STAGE(PG8_SB(1, 1), b3 + hstep, voffB); PG8_STAGE(PG8_SA(1, 0), a3, voffA);
;             PG8_WAIT_V(8); PG8_WAIT_L(0); PG8_BAR; PG8_MMA(1, 0, At, B0); PG8_MMA(1, 1, At, B1); PG8_BAR; PG8_SCHED;
	ds_read_b128 v[140:143], v254 offset:32768
	ds_read_b128 v[162:165], v254 offset:33792
	ds_read_b128 v[166:169], v254 offset:34816
	ds_read_b128 v[176:179], v254 offset:35840
	ds_read_b128 v[180:183], v254 offset:49152
	ds_read_b128 v[184:187], v254 offset:50176
	ds_read_b128 v[188:191], v254 offset:51200
	ds_read_b128 v[210:213], v254 offset:52224
	s_add_u32 s4, s4, 0x40000
	s_addc_u32 s5, s5, 0
	s_mov_b32 m0, s33
	ds_read_b128 v[214:217], v173 offset:32768
	ds_read_b128 v[218:221], v173 offset:33792
	ds_read_b128 v[222:225], v173 offset:34816
	ds_read_b128 v[226:229], v173 offset:35840
	ds_read_b128 v[230:233], v173 offset:36864
	ds_read_b128 v[234:237], v173 offset:37888
	ds_read_b128 v[238:241], v173 offset:38912
	ds_read_b128 v[242:245], v173 offset:39936
	global_load_lds_dwordx4 v134, s[4:5]
	s_mov_b32 m0, s34
	s_nop 0
	global_load_lds_dwordx4 v130, s[4:5]
	s_waitcnt vmcnt(8)
	s_waitcnt lgkmcnt(0)
	s_barrier
	s_setprio 1
	v_mfma_f32_16x16x32_bf16 v[124:127], v[140:143], v[214:217], v[124:127]
	v_mfma_f32_16x16x32_bf16 v[120:123], v[166:169], v[214:217], v[120:123]
	v_mfma_f32_16x16x32_bf16 v[112:115], v[140:143], v[222:225], v[112:115]
	v_mfma_f32_16x16x32_bf16 v[104:107], v[166:169], v[222:225], v[104:107]
	v_mfma_f32_16x16x32_bf16 v[96:99], v[140:143], v[230:233], v[96:99]
	v_mfma_f32_16x16x32_bf16 v[88:91], v[166:169], v[230:233], v[88:91]
	v_mfma_f32_16x16x32_bf16 v[80:83], v[140:143], v[238:241], v[80:83]
	v_mfma_f32_16x16x32_bf16 v[72:75], v[166:169], v[238:241], v[72:75]
	v_mfma_f32_16x16x32_bf16 v[124:127], v[162:165], v[218:221], v[124:127]
	v_mfma_f32_16x16x32_bf16 v[120:123], v[176:179], v[218:221], v[120:123]
	v_mfma_f32_16x16x32_bf16 v[112:115], v[162:165], v[226:229], v[112:115]
	v_mfma_f32_16x16x32_bf16 v[104:107], v[176:179], v[226:229], v[104:107]
	v_mfma_f32_16x16x32_bf16 v[96:99], v[162:165], v[234:237], v[96:99]
	v_mfma_f32_16x16x32_bf16 v[88:91], v[176:179], v[234:237], v[88:91]
	v_mfma_f32_16x16x32_bf16 v[80:83], v[162:165], v[242:245], v[80:83]
	v_mfma_f32_16x16x32_bf16 v[72:75], v[176:179], v[242:245], v[72:75]
	v_mfma_f32_16x16x32_bf16 v[116:119], v[180:183], v[214:217], v[116:119]
	v_mfma_f32_16x16x32_bf16 v[108:111], v[188:191], v[214:217], v[108:111]
	v_mfma_f32_16x16x32_bf16 v[100:103], v[180:183], v[222:225], v[100:103]
	v_mfma_f32_16x16x32_bf16 v[92:95], v[188:191], v[222:225], v[92:95]
	v_mfma_f32_16x16x32_bf16 v[84:87], v[180:183], v[230:233], v[84:87]
	v_mfma_f32_16x16x32_bf16 v[76:79], v[188:191], v[230:233], v[76:79]
	v_mfma_f32_16x16x32_bf16 v[68:71], v[180:183], v[238:241], v[68:71]
	v_mfma_f32_16x16x32_bf16 v[64:67], v[188:191], v[238:241], v[64:67]
	v_mfma_f32_16x16x32_bf16 v[116:119], v[184:187], v[218:221], v[116:119]
	v_mfma_f32_16x16x32_bf16 v[108:111], v[210:213], v[218:221], v[108:111]
	v_mfma_f32_16x16x32_bf16 v[100:103], v[184:187], v[226:229], v[100:103]
	v_mfma_f32_16x16x32_bf16 v[92:95], v[210:213], v[226:229], v[92:95]
	v_mfma_f32_16x16x32_bf16 v[84:87], v[184:187], v[234:237], v[84:87]
	v_mfma_f32_16x16x32_bf16 v[76:79], v[210:213], v[234:237], v[76:79]
	v_mfma_f32_16x16x32_bf16 v[68:71], v[184:187], v[242:245], v[68:71]
	v_mfma_f32_16x16x32_bf16 v[64:67], v[210:213], v[242:245], v[64:67]
	s_setprio 0
	s_barrier
	s_mov_b32 m0, s37
	s_add_u32 s2, s2, 0x40080
	s_addc_u32 s3, s3, 0
	ds_read_b128 v[214:217], v173 offset:49152
	ds_read_b128 v[218:221], v173 offset:50176
	ds_read_b128 v[222:225], v173 offset:51200
	ds_read_b128 v[226:229], v173 offset:52224
	ds_read_b128 v[230:233], v173 offset:53248
	ds_read_b128 v[234:237], v173 offset:54272
	ds_read_b128 v[238:241], v173 offset:55296
	ds_read_b128 v[242:245], v173 offset:56320
	s_add_u32 s98, s2, 0xfffc0000
	s_addc_u32 s99, s3, -1
	global_load_lds_dwordx4 v132, s[98:99]
	s_mov_b32 m0, s38
	s_nop 0
	global_load_lds_dwordx4 v128, s[98:99]
	s_mov_b32 m0, s41
	s_nop 0
	global_load_lds_dwordx4 v132, s[2:3]
	s_mov_b32 m0, s42
	s_nop 0
	global_load_lds_dwordx4 v128, s[2:3]
	s_mov_b32 m0, s39
	s_nop 0
	s_add_u32 s100, s4, 0xfffc0080
	s_addc_u32 s101, s5, -1
	global_load_lds_dwordx4 v134, s[100:101]
	s_mov_b32 m0, s40
	s_nop 0
	global_load_lds_dwordx4 v130, s[100:101]
	s_waitcnt vmcnt(8)
	s_waitcnt lgkmcnt(0)
	s_barrier
	s_setprio 1
	v_mfma_f32_16x16x32_bf16 v[60:63], v[140:143], v[214:217], v[60:63]
	v_mfma_f32_16x16x32_bf16 v[56:59], v[166:169], v[214:217], v[56:59]
	v_mfma_f32_16x16x32_bf16 v[48:51], v[140:143], v[222:225], v[48:51]
	v_mfma_f32_16x16x32_bf16 v[40:43], v[166:169], v[222:225], v[40:43]
	v_mfma_f32_16x16x32_bf16 v[32:35], v[140:143], v[230:233], v[32:35]
	v_mfma_f32_16x16x32_bf16 v[24:27], v[166:169], v[230:233], v[24:27]
	v_mfma_f32_16x16x32_bf16 v[16:19], v[140:143], v[238:241], v[16:19]
	v_mfma_f32_16x16x32_bf16 v[8:11], v[166:169], v[238:241], v[8:11]
	v_mfma_f32_16x16x32_bf16 v[60:63], v[162:165], v[218:221], v[60:63]
	v_mfma_f32_16x16x32_bf16 v[56:59], v[176:179], v[218:221], v[56:59]
	v_mfma_f32_16x16x32_bf16 v[48:51], v[162:165], v[226:229], v[48:51]
	v_mfma_f32_16x16x32_bf16 v[40:43], v[176:179], v[226:229], v[40:43]
	v_mfma_f32_16x16x32_bf16 v[32:35], v[162:165], v[234:237], v[32:35]
	v_mfma_f32_16x16x32_bf16 v[24:27], v[176:179], v[234:237], v[24:27]
	v_mfma_f32_16x16x32_bf16 v[16:19], v[162:165], v[242:245], v[16:19]
	v_mfma_f32_16x16x32_bf16 v[8:11], v[176:179], v[242:245], v[8:11]
	v_mfma_f32_16x16x32_bf16 v[52:55], v[180:183], v[214:217], v[52:55]
	v_mfma_f32_16x16x32_bf16 v[44:47], v[188:191], v[214:217], v[44:47]
	v_mfma_f32_16x16x32_bf16 v[36:39], v[180:183], v[222:225], v[36:39]
	v_mfma_f32_16x16x32_bf16 v[28:31], v[188:191], v[222:225], v[28:31]
	v_mfma_f32_16x16x32_bf16 v[20:23], v[180:183], v[230:233], v[20:23]
	v_mfma_f32_16x16x32_bf16 v[12:15], v[188:191], v[230:233], v[12:15]
	v_mfma_f32_16x16x32_bf16 v[4:7], v[180:183], v[238:241], v[4:7]
	v_mfma_f32_16x16x32_bf16 v[0:3], v[188:191], v[238:241], v[0:3]
	v_mfma_f32_16x16x32_bf16 v[52:55], v[184:187], v[218:221], v[52:55]
	v_mfma_f32_16x16x32_bf16 v[44:47], v[210:213], v[218:221], v[44:47]
	v_mfma_f32_16x16x32_bf16 v[36:39], v[184:187], v[226:229], v[36:39]
	v_mfma_f32_16x16x32_bf16 v[28:31], v[210:213], v[226:229], v[28:31]
	v_mfma_f32_16x16x32_bf16 v[20:23], v[184:187], v[234:237], v[20:23]
	v_mfma_f32_16x16x32_bf16 v[12:15], v[210:213], v[234:237], v[12:15]
	v_mfma_f32_16x16x32_bf16 v[4:7], v[184:187], v[242:245], v[4:7]
	v_mfma_f32_16x16x32_bf16 v[0:3], v[210:213], v[242:245], v[0:3]
	s_setprio 0
	s_barrier
	s_add_i32 s52, s52, 2
	s_add_u32 s0, s0, 0x100
	s_addc_u32 s1, s1, 0
	s_add_u32 s50, s50, 0x100
	s_addc_u32 s51, s51, 0
	s_cmp_gt_u32 s52, 13
; #define PG8_STAGE(bufoff, gbase, voff) do { _Pragma("unroll") for (int _i = 0; _i < 2; ++_i) \
;         __builtin_amdgcn_global_load_lds((const unsigned*)((const char*)(gbase) + (voff)[_i]), (PG8_LAS unsigned*)(lds + (bufoff) + ldsw + _i * 8192), 16, 0, 0); } while (0)
; #define PG8_LDA(dst, b, h) do { _Pragma("unroll") for (int m = 0; m < 4; ++m) _Pragma("unroll") for (int k = 0; k < 2; ++k) dst[m][k] = *(const PG8_LAS bf16x8*)(lds + PG8_SA(b, h) + aoff + m * 2048 + k * 1024); } while (0)
; #define PG8_LDB(dst, b, h) do { _Pragma("unroll") for (int n = 0; n < 2; ++n) _Pragma("unroll") for (int k = 0; k < 2; ++k) dst[n][k] = *(const PG8_LAS bf16x8*)(lds + PG8_SB(b, h) + boff + n * 2048 + k * 1024); } while (0)
; #define PG8_MMA(ai, bj, At, Bt) do { __builtin_amdgcn_s_setprio(1); _Pragma("unroll") for (int m = 0; m < 4; ++m) _Pragma("unroll") for (int n = 0; n < 2; ++n) _Pragma("unroll") for (int k = 0; k < 2; ++k) \
;         acc[ai][bj][m][n] = __builtin_amdgcn_mfma_f32_16x16x32_bf16(Bt[n][k], At[m][k], acc[ai][bj][m][n], 0, 0, 0); __builtin_amdgcn_s_setprio(0); } while (0)
; #define PG8_WAIT_V(n) asm volatile("s_waitcnt vmcnt(" #n ")" ::: "memory")
; #define PG8_WAIT_L(n) asm volatile("s_waitcnt lgkmcnt(" #n ")" ::: "memory")
; #define PG8_BAR __builtin_amdgcn_s_barrier()
; #define PG8_SCHED __builtin_amdgcn_sched_barrier(0)
; template <class Epi, class Sched, bool ALIGN_EPI = false, bool SP2 = false>
; __device__ __forceinline__ void gemm_phase(PG8_LAS unsigned char* lds, const Gemm g, const Sched& S, const Epi& E) {
;     ...
;             PG8_LDB(B0, 0, 0); PG8_LDB(B1, 0, 1); PG8_SCHED; PG8_LDA(At, 0, 0); PG8_STAGE(PG8_SA(1, 1), a1 + hstep, voffA);
;             PG8_WAIT_V(8); PG8_WAIT_L(0); PG8_BAR; PG8_MMA(0, 0, At, B0); PG8_MMA(0, 1, At, B1); PG8_BAR; PG8_SCHED;
;             PG8_LDA(At, 0, 1); PG8_STAGE(PG8_SB(0, 0), b2, voffB); PG8_STAGE(PG8_SB(0, 1), b2 + hstep, voffB); PG8_STAGE(PG8_SA(0, 0), a2, voffA);
;             PG8_WAIT_V(8); PG8_WAIT_L(0); PG8_BAR; PG8_MMA(1, 0, At, B0); PG8_MMA(1, 1, At, B1); PG8_BAR; PG8_SCHED;
.LBB0_792:
	s_waitcnt lgkmcnt(0)
	ds_read_b128 v[140:143], v254
	ds_read_b128 v[162:165], v254 offset:1024
	ds_read_b128 v[166:169], v254 offset:2048
	ds_read_b128 v[176:179], v254 offset:3072
	ds_read_b128 v[180:183], v254 offset:16384
	ds_read_b128 v[184:187], v254 offset:17408
	ds_read_b128 v[188:191], v254 offset:18432
	ds_read_b128 v[210:213], v254 offset:19456
	s_add_u32 s2, s0, 0xfffc0080
	s_addc_u32 s3, s1, -1
	s_cmp_eq_u32 s52, 12
	s_cselect_b32 s5, s17, s3
	s_cselect_b32 s4, s48, s2
	s_cselect_b32 s3, s15, s51
	s_cselect_b32 s2, s49, s50
	s_add_i32 m0, s6, 0xc000
	ds_read_b128 v[214:217], v173
	ds_read_b128 v[218:221], v173 offset:1024
	ds_read_b128 v[222:225], v173 offset:2048
	ds_read_b128 v[226:229], v173 offset:3072
	ds_read_b128 v[230:233], v173 offset:4096
	ds_read_b128 v[234:237], v173 offset:5120
	ds_read_b128 v[238:241], v173 offset:6144
	ds_read_b128 v[242:245], v173 offset:7168
	global_load_lds_dwordx4 v136, s[0:1]
	s_add_i32 m0, s6, 0xe000
	s_nop 0
	global_load_lds_dwordx4 v138, s[0:1]
	s_waitcnt vmcnt(8)
	s_waitcnt lgkmcnt(0)
	s_barrier
	s_setprio 1
	v_mfma_f32_16x16x32_bf16 v[124:127], v[140:143], v[214:217], v[124:127]
	v_mfma_f32_16x16x32_bf16 v[120:123], v[166:169], v[214:217], v[120:123]
	v_mfma_f32_16x16x32_bf16 v[112:115], v[140:143], v[222:225], v[112:115]
	v_mfma_f32_16x16x32_bf16 v[104:107], v[166:169], v[222:225], v[104:107]
	v_mfma_f32_16x16x32_bf16 v[96:99], v[140:143], v[230:233], v[96:99]
	v_mfma_f32_16x16x32_bf16 v[88:91], v[166:169], v[230:233], v[88:91]
	v_mfma_f32_16x16x32_bf16 v[80:83], v[140:143], v[238:241], v[80:83]
	v_mfma_f32_16x16x32_bf16 v[72:75], v[166:169], v[238:241], v[72:75]
	v_mfma_f32_16x16x32_bf16 v[124:127], v[162:165], v[218:221], v[124:127]
	v_mfma_f32_16x16x32_bf16 v[120:123], v[176:179], v[218:221], v[120:123]
	v_mfma_f32_16x16x32_bf16 v[112:115], v[162:165], v[226:229], v[112:115]
	v_mfma_f32_16x16x32_bf16 v[104:107], v[176:179], v[226:229], v[104:107]
	v_mfma_f32_16x16x32_bf16 v[96:99], v[162:165], v[234:237], v[96:99]
	v_mfma_f32_16x16x32_bf16 v[88:91], v[176:179], v[234:237], v[88:91]
	v_mfma_f32_16x16x32_bf16 v[80:83], v[162:165], v[242:245], v[80:83]
	v_mfma_f32_16x16x32_bf16 v[72:75], v[176:179], v[242:245], v[72:75]
	v_mfma_f32_16x16x32_bf16 v[116:119], v[180:183], v[214:217], v[116:119]
	v_mfma_f32_16x16x32_bf16 v[108:111], v[188:191], v[214:217], v[108:111]
	v_mfma_f32_16x16x32_bf16 v[100:103], v[180:183], v[222:225], v[100:103]
	v_mfma_f32_16x16x32_bf16 v[92:95], v[188:191], v[222:225], v[92:95]
	v_mfma_f32_16x16x32_bf16 v[84:87], v[180:183], v[230:233], v[84:87]
	v_mfma_f32_16x16x32_bf16 v[76:79], v[188:191], v[230:233], v[76:79]
	v_mfma_f32_16x16x32_bf16 v[68:71], v[180:183], v[238:241], v[68:71]
	v_mfma_f32_16x16x32_bf16 v[64:67], v[188:191], v[238:241], v[64:67]
	v_mfma_f32_16x16x32_bf16 v[116:119], v[184:187], v[218:221], v[116:119]
	v_mfma_f32_16x16x32_bf16 v[108:111], v[210:213], v[218:221], v[108:111]
	v_mfma_f32_16x16x32_bf16 v[100:103], v[184:187], v[226:229], v[100:103]
	v_mfma_f32_16x16x32_bf16 v[92:95], v[210:213], v[226:229], v[92:95]
	v_mfma_f32_16x16x32_bf16 v[84:87], v[184:187], v[234:237], v[84:87]
	v_mfma_f32_16x16x32_bf16 v[76:79], v[210:213], v[234:237], v[76:79]
	v_mfma_f32_16x16x32_bf16 v[68:71], v[184:187], v[242:245], v[68:71]
	v_mfma_f32_16x16x32_bf16 v[64:67], v[210:213], v[242:245], v[64:67]
	s_setprio 0
	s_barrier
	s_mov_b32 m0, s27
	s_add_u32 s54, s2, 0x40000
	s_addc_u32 s55, s3, 0
	ds_read_b128 v[214:217], v173 offset:16384
	ds_read_b128 v[218:221], v173 offset:17408
	ds_read_b128 v[222:225], v173 offset:18432
	ds_read_b128 v[226:229], v173 offset:19456
	ds_read_b128 v[230:233], v173 offset:20480
	ds_read_b128 v[234:237], v173 offset:21504
	ds_read_b128 v[238:241], v173 offset:22528
	ds_read_b128 v[242:245], v173 offset:23552
	global_load_lds_dwordx4 v132, s[2:3]
	s_mov_b32 m0, s28
	s_nop 0
	global_load_lds_dwordx4 v128, s[2:3]
	s_mov_b32 m0, s29
	s_nop 0
	global_load_lds_dwordx4 v132, s[54:55]
	s_mov_b32 m0, s30
	s_nop 0
	global_load_lds_dwordx4 v128, s[54:55]
	s_mov_b32 m0, s6
	s_nop 0
	global_load_lds_dwordx4 v134, s[4:5]
	s_mov_b32 m0, s31
	s_nop 0
	global_load_lds_dwordx4 v130, s[4:5]
	s_waitcnt vmcnt(8)
	s_waitcnt lgkmcnt(0)
	s_barrier
	s_setprio 1
	v_mfma_f32_16x16x32_bf16 v[60:63], v[140:143], v[214:217], v[60:63]
	v_mfma_f32_16x16x32_bf16 v[56:59], v[166:169], v[214:217], v[56:59]
	v_mfma_f32_16x16x32_bf16 v[48:51], v[140:143], v[222:225], v[48:51]
	v_mfma_f32_16x16x32_bf16 v[40:43], v[166:169], v[222:225], v[40:43]
	v_mfma_f32_16x16x32_bf16 v[32:35], v[140:143], v[230:233], v[32:35]
	v_mfma_f32_16x16x32_bf16 v[24:27], v[166:169], v[230:233], v[24:27]
	v_mfma_f32_16x16x32_bf16 v[16:19], v[140:143], v[238:241], v[16:19]
	v_mfma_f32_16x16x32_bf16 v[8:11], v[166:169], v[238:241], v[8:11]
	v_mfma_f32_16x16x32_bf16 v[60:63], v[162:165], v[218:221], v[60:63]
	v_mfma_f32_16x16x32_bf16 v[56:59], v[176:179], v[218:221], v[56:59]
	v_mfma_f32_16x16x32_bf16 v[48:51], v[162:165], v[226:229], v[48:51]
	v_mfma_f32_16x16x32_bf16 v[40:43], v[176:179], v[226:229], v[40:43]
	v_mfma_f32_16x16x32_bf16 v[32:35], v[162:165], v[234:237], v[32:35]
	v_mfma_f32_16x16x32_bf16 v[24:27], v[176:179], v[234:237], v[24:27]
	v_mfma_f32_16x16x32_bf16 v[16:19], v[162:165], v[242:245], v[16:19]
	v_mfma_f32_16x16x32_bf16 v[8:11], v[176:179], v[242:245], v[8:11]
	v_mfma_f32_16x16x32_bf16 v[52:55], v[180:183], v[214:217], v[52:55]
	v_mfma_f32_16x16x32_bf16 v[44:47], v[188:191], v[214:217], v[44:47]
	v_mfma_f32_16x16x32_bf16 v[36:39], v[180:183], v[222:225], v[36:39]
	v_mfma_f32_16x16x32_bf16 v[28:31], v[188:191], v[222:225], v[28:31]
	v_mfma_f32_16x16x32_bf16 v[20:23], v[180:183], v[230:233], v[20:23]
	v_mfma_f32_16x16x32_bf16 v[12:15], v[188:191], v[230:233], v[12:15]
	v_mfma_f32_16x16x32_bf16 v[4:7], v[180:183], v[238:241], v[4:7]
	v_mfma_f32_16x16x32_bf16 v[0:3], v[188:191], v[238:241], v[0:3]
	v_mfma_f32_16x16x32_bf16 v[52:55], v[184:187], v[218:221], v[52:55]
	v_mfma_f32_16x16x32_bf16 v[44:47], v[210:213], v[218:221], v[44:47]
	v_mfma_f32_16x16x32_bf16 v[36:39], v[184:187], v[226:229], v[36:39]
	v_mfma_f32_16x16x32_bf16 v[28:31], v[210:213], v[226:229], v[28:31]
	v_mfma_f32_16x16x32_bf16 v[20:23], v[184:187], v[234:237], v[20:23]
	v_mfma_f32_16x16x32_bf16 v[12:15], v[210:213], v[234:237], v[12:15]
	v_mfma_f32_16x16x32_bf16 v[4:7], v[184:187], v[242:245], v[4:7]
	v_mfma_f32_16x16x32_bf16 v[0:3], v[210:213], v[242:245], v[0:3]
	s_setprio 0
	s_barrier
; #define PG8_STAGE(bufoff, gbase, voff) do { _Pragma("unroll") for (int _i = 0; _i < 2; ++_i) \
;         __builtin_amdgcn_global_load_lds((const unsigned*)((const char*)(gbase) + (voff)[_i]), (PG8_LAS unsigned*)(lds + (bufoff) + ldsw + _i * 8192), 16, 0, 0); } while (0)
; #define PG8_LDA(dst, b, h) do { _Pragma("unroll") for (int m = 0; m < 4; ++m) _Pragma("unroll") for (int k = 0; k < 2; ++k) dst[m][k] = *(const PG8_LAS bf16x8*)(lds + PG8_SA(b, h) + aoff + m * 2048 + k * 1024); } while (0)
; #define PG8_LDB(dst, b, h) do { _Pragma("unroll") for (int n = 0; n < 2; ++n) _Pragma("unroll") for (int k = 0; k < 2; ++k) dst[n][k] = *(const PG8_LAS bf16x8*)(lds + PG8_SB(b, h) + boff + n * 2048 + k * 1024); } while (0)
; #define PG8_MMA(ai, bj, At, Bt) do { __builtin_amdgcn_s_setprio(1); _Pragma("unroll") for (int m = 0; m < 4; ++m) _Pragma("unroll") for (int n = 0; n < 2; ++n) _Pragma("unroll") for (int k = 0; k < 2; ++k) \
;         acc[ai][bj][m][n] = __builtin_amdgcn_mfma_f32_16x16x32_bf16(Bt[n][k], At[m][k], acc[ai][bj][m][n], 0, 0, 0); __builtin_amdgcn_s_setprio(0); } while (0)
; #define PG8_WAIT_V(n) asm volatile("s_waitcnt vmcnt(" #n ")" ::: "memory")
; #define PG8_WAIT_L(n) asm volatile("s_waitcnt lgkmcnt(" #n ")" ::: "memory")
; #define PG8_BAR __builtin_amdgcn_s_barrier()
; #define PG8_SCHED __builtin_amdgcn_sched_barrier(0)
; template <class Epi, class Sched, bool ALIGN_EPI = false, bool SP2 = false>
; __device__ __forceinline__ void gemm_phase(PG8_LAS unsigned char* lds, const Gemm g, const Sched& S, const Epi& E) {
;     ...
;             PG8_LDB(B0, 1, 0); PG8_LDB(B1, 1, 1); PG8_SCHED; PG8_LDA(At, 1, 0); PG8_STAGE(PG8_SA(0, 1), a2 + hstep, voffA);
;             PG8_WAIT_V(8); PG8_WAIT_L(0); PG8_BAR; PG8_MMA(0, 0, At, B0); PG8_MMA(0, 1, At, B1); PG8_BAR; PG8_SCHED;
;             PG8_LDA(At, 1, 1); PG8_STAGE(PG8_SB(1, 0), b3, voffB); PG8_STAGE(PG8_SB(1, 1), b3 + hstep, voffB); PG8_STAGE(PG8_SA(1, 0), a3, voffA);
;             PG8_WAIT_V(8); PG8_WAIT_L(0); PG8_BAR; PG8_MMA(1, 0, At, B0); PG8_MMA(1, 1, At, B1); PG8_BAR; PG8_SCHED;
;     ...
;         if constexpr (ALIGN_EPI) { if (wr == 0) PG8_BAR; }
	ds_read_b128 v[140:143], v254 offset:32768
	ds_read_b128 v[162:165], v254 offset:33792
	ds_read_b128 v[166:169], v254 offset:34816
	ds_read_b128 v[176:179], v254 offset:35840
	ds_read_b128 v[180:183], v254 offset:49152
	ds_read_b128 v[184:187], v254 offset:50176
	ds_read_b128 v[188:191], v254 offset:51200
	ds_read_b128 v[210:213], v254 offset:52224
	s_add_u32 s4, s4, 0x40000
	s_addc_u32 s5, s5, 0
	s_mov_b32 m0, s33
	ds_read_b128 v[214:217], v173 offset:32768
	ds_read_b128 v[218:221], v173 offset:33792
	ds_read_b128 v[222:225], v173 offset:34816
	ds_read_b128 v[226:229], v173 offset:35840
	ds_read_b128 v[230:233], v173 offset:36864
	ds_read_b128 v[234:237], v173 offset:37888
	ds_read_b128 v[238:241], v173 offset:38912
	ds_read_b128 v[242:245], v173 offset:39936
	global_load_lds_dwordx4 v134, s[4:5]
	s_mov_b32 m0, s34
	s_nop 0
	global_load_lds_dwordx4 v130, s[4:5]
	s_waitcnt vmcnt(8)
	s_waitcnt lgkmcnt(0)
	s_barrier
	s_setprio 1
	v_mfma_f32_16x16x32_bf16 v[124:127], v[140:143], v[214:217], v[124:127]
	v_mfma_f32_16x16x32_bf16 v[120:123], v[166:169], v[214:217], v[120:123]
	v_mfma_f32_16x16x32_bf16 v[112:115], v[140:143], v[222:225], v[112:115]
	v_mfma_f32_16x16x32_bf16 v[104:107], v[166:169], v[222:225], v[104:107]
	v_mfma_f32_16x16x32_bf16 v[96:99], v[140:143], v[230:233], v[96:99]
	v_mfma_f32_16x16x32_bf16 v[88:91], v[166:169], v[230:233], v[88:91]
	v_mfma_f32_16x16x32_bf16 v[80:83], v[140:143], v[238:241], v[80:83]
	v_mfma_f32_16x16x32_bf16 v[72:75], v[166:169], v[238:241], v[72:75]
	v_mfma_f32_16x16x32_bf16 v[124:127], v[162:165], v[218:221], v[124:127]
	v_mfma_f32_16x16x32_bf16 v[120:123], v[176:179], v[218:221], v[120:123]
	v_mfma_f32_16x16x32_bf16 v[112:115], v[162:165], v[226:229], v[112:115]
	v_mfma_f32_16x16x32_bf16 v[104:107], v[176:179], v[226:229], v[104:107]
	v_mfma_f32_16x16x32_bf16 v[96:99], v[162:165], v[234:237], v[96:99]
	v_mfma_f32_16x16x32_bf16 v[88:91], v[176:179], v[234:237], v[88:91]
	v_mfma_f32_16x16x32_bf16 v[80:83], v[162:165], v[242:245], v[80:83]
	v_mfma_f32_16x16x32_bf16 v[72:75], v[176:179], v[242:245], v[72:75]
	v_mfma_f32_16x16x32_bf16 v[116:119], v[180:183], v[214:217], v[116:119]
	v_mfma_f32_16x16x32_bf16 v[108:111], v[188:191], v[214:217], v[108:111]
	v_mfma_f32_16x16x32_bf16 v[100:103], v[180:183], v[222:225], v[100:103]
	v_mfma_f32_16x16x32_bf16 v[92:95], v[188:191], v[222:225], v[92:95]
	v_mfma_f32_16x16x32_bf16 v[84:87], v[180:183], v[230:233], v[84:87]
	v_mfma_f32_16x16x32_bf16 v[76:79], v[188:191], v[230:233], v[76:79]
	v_mfma_f32_16x16x32_bf16 v[68:71], v[180:183], v[238:241], v[68:71]
	v_mfma_f32_16x16x32_bf16 v[64:67], v[188:191], v[238:241], v[64:67]
	v_mfma_f32_16x16x32_bf16 v[116:119], v[184:187], v[218:221], v[116:119]
	v_mfma_f32_16x16x32_bf16 v[108:111], v[210:213], v[218:221], v[108:111]
	v_mfma_f32_16x16x32_bf16 v[100:103], v[184:187], v[226:229], v[100:103]
	v_mfma_f32_16x16x32_bf16 v[92:95], v[210:213], v[226:229], v[92:95]
	v_mfma_f32_16x16x32_bf16 v[84:87], v[184:187], v[234:237], v[84:87]
	v_mfma_f32_16x16x32_bf16 v[76:79], v[210:213], v[234:237], v[76:79]
	v_mfma_f32_16x16x32_bf16 v[68:71], v[184:187], v[242:245], v[68:71]
	v_mfma_f32_16x16x32_bf16 v[64:67], v[210:213], v[242:245], v[64:67]
	s_setprio 0
	s_barrier
	s_mov_b32 m0, s37
	s_add_u32 s2, s2, 0x40080
	s_addc_u32 s3, s3, 0
	ds_read_b128 v[214:217], v173 offset:49152
	ds_read_b128 v[218:221], v173 offset:50176
	ds_read_b128 v[222:225], v173 offset:51200
	ds_read_b128 v[226:229], v173 offset:52224
	ds_read_b128 v[230:233], v173 offset:53248
	ds_read_b128 v[234:237], v173 offset:54272
	ds_read_b128 v[238:241], v173 offset:55296
	ds_read_b128 v[242:245], v173 offset:56320
	s_add_u32 s98, s2, 0xfffc0000
	s_addc_u32 s99, s3, -1
	global_load_lds_dwordx4 v132, s[98:99]
	s_mov_b32 m0, s38
	s_nop 0
	global_load_lds_dwordx4 v128, s[98:99]
	s_mov_b32 m0, s41
	s_nop 0
	global_load_lds_dwordx4 v132, s[2:3]
	s_mov_b32 m0, s42
	s_nop 0
	global_load_lds_dwordx4 v128, s[2:3]
	s_mov_b32 m0, s39
	s_nop 0
	s_add_u32 s100, s4, 0xfffc0080
	s_addc_u32 s101, s5, -1
	global_load_lds_dwordx4 v134, s[100:101]
	s_mov_b32 m0, s40
	s_nop 0
	global_load_lds_dwordx4 v130, s[100:101]
	s_waitcnt vmcnt(8)
	s_waitcnt lgkmcnt(0)
	s_barrier
	s_setprio 1
	v_mfma_f32_16x16x32_bf16 v[60:63], v[140:143], v[214:217], v[60:63]
	v_mfma_f32_16x16x32_bf16 v[56:59], v[166:169], v[214:217], v[56:59]
	v_mfma_f32_16x16x32_bf16 v[48:51], v[140:143], v[222:225], v[48:51]
	v_mfma_f32_16x16x32_bf16 v[40:43], v[166:169], v[222:225], v[40:43]
	v_mfma_f32_16x16x32_bf16 v[32:35], v[140:143], v[230:233], v[32:35]
	v_mfma_f32_16x16x32_bf16 v[24:27], v[166:169], v[230:233], v[24:27]
	v_mfma_f32_16x16x32_bf16 v[16:19], v[140:143], v[238:241], v[16:19]
	v_mfma_f32_16x16x32_bf16 v[8:11], v[166:169], v[238:241], v[8:11]
	v_mfma_f32_16x16x32_bf16 v[60:63], v[162:165], v[218:221], v[60:63]
	v_mfma_f32_16x16x32_bf16 v[56:59], v[176:179], v[218:221], v[56:59]
	v_mfma_f32_16x16x32_bf16 v[48:51], v[162:165], v[226:229], v[48:51]
	v_mfma_f32_16x16x32_bf16 v[40:43], v[176:179], v[226:229], v[40:43]
	v_mfma_f32_16x16x32_bf16 v[32:35], v[162:165], v[234:237], v[32:35]
	v_mfma_f32_16x16x32_bf16 v[24:27], v[176:179], v[234:237], v[24:27]
	v_mfma_f32_16x16x32_bf16 v[16:19], v[162:165], v[242:245], v[16:19]
	v_mfma_f32_16x16x32_bf16 v[8:11], v[176:179], v[242:245], v[8:11]
	v_mfma_f32_16x16x32_bf16 v[52:55], v[180:183], v[214:217], v[52:55]
	v_mfma_f32_16x16x32_bf16 v[44:47], v[188:191], v[214:217], v[44:47]
	v_mfma_f32_16x16x32_bf16 v[36:39], v[180:183], v[222:225], v[36:39]
	v_mfma_f32_16x16x32_bf16 v[28:31], v[188:191], v[222:225], v[28:31]
	v_mfma_f32_16x16x32_bf16 v[20:23], v[180:183], v[230:233], v[20:23]
	v_mfma_f32_16x16x32_bf16 v[12:15], v[188:191], v[230:233], v[12:15]
	v_mfma_f32_16x16x32_bf16 v[4:7], v[180:183], v[238:241], v[4:7]
	v_mfma_f32_16x16x32_bf16 v[0:3], v[188:191], v[238:241], v[0:3]
	v_mfma_f32_16x16x32_bf16 v[52:55], v[184:187], v[218:221], v[52:55]
	v_mfma_f32_16x16x32_bf16 v[44:47], v[210:213], v[218:221], v[44:47]
	v_mfma_f32_16x16x32_bf16 v[36:39], v[184:187], v[226:229], v[36:39]
	v_mfma_f32_16x16x32_bf16 v[28:31], v[210:213], v[226:229], v[28:31]
	v_mfma_f32_16x16x32_bf16 v[20:23], v[184:187], v[234:237], v[20:23]
	v_mfma_f32_16x16x32_bf16 v[12:15], v[210:213], v[234:237], v[12:15]
	v_mfma_f32_16x16x32_bf16 v[4:7], v[184:187], v[242:245], v[4:7]
	v_mfma_f32_16x16x32_bf16 v[0:3], v[210:213], v[242:245], v[0:3]
	s_setprio 0
	s_barrier
	s_add_i32 s52, s52, 2
	s_add_u32 s0, s0, 0x100
	s_addc_u32 s1, s1, 0
	s_add_u32 s50, s50, 0x100
	s_addc_u32 s51, s51, 0
	s_cmp_gt_u32 s52, 13
	s_cbranch_scc0 .LBB0_792
	s_and_b64 vcc, exec, s[12:13]
	s_cbranch_vccz .LBB0_795
	s_barrier

; #define PG8_STAGE(bufoff, gbase, voff) do { _Pragma("unroll") for (int _i = 0; _i < 2; ++_i) \
;         __builtin_amdgcn_global_load_lds((const unsigned*)((const char*)(gbase) + (voff)[_i]), (PG8_LAS unsigned*)(lds + (bufoff) + ldsw + _i * 8192), 16, 0, 0); } while (0)
; #define PG8_LDA(dst, b, h) do { _Pragma("unroll") for (int m = 0; m < 4; ++m) _Pragma("unroll") for (int k = 0; k < 2; ++k) dst[m][k] = *(const PG8_LAS bf16x8*)(lds + PG8_SA(b, h) + aoff + m * 2048 + k * 1024); } while (0)
; #define PG8_LDB(dst, b, h) do { _Pragma("unroll") for (int n = 0; n < 2; ++n) _Pragma("unroll") for (int k = 0; k < 2; ++k) dst[n][k] = *(const PG8_LAS bf16x8*)(lds + PG8_SB(b, h) + boff + n * 2048 + k * 1024); } while (0)
; #define PG8_MMA(ai, bj, At, Bt) do { __builtin_amdgcn_s_setprio(1); _Pragma("unroll") for (int m = 0; m < 4; ++m) _Pragma("unroll") for (int n = 0; n < 2; ++n) _Pragma("unroll") for (int k = 0; k < 2; ++k) \
;         acc[ai][bj][m][n] = __builtin_amdgcn_mfma_f32_16x16x32_bf16(Bt[n][k], At[m][k], acc[ai][bj][m][n], 0, 0, 0); __builtin_amdgcn_s_setprio(0); } while (0)
; #define PG8_WAIT_V(n) asm volatile("s_waitcnt vmcnt(" #n ")" ::: "memory")
; #define PG8_WAIT_L(n) asm volatile("s_waitcnt lgkmcnt(" #n ")" ::: "memory")
; #define PG8_BAR __builtin_amdgcn_s_barrier()
; #define PG8_SCHED __builtin_amdgcn_sched_barrier(0)
; template <class Epi, class Sched, bool ALIGN_EPI = false, bool SP2 = false>
; __device__ __forceinline__ void gemm_phase(PG8_LAS unsigned char* lds, const Gemm g, const Sched& S, const Epi& E) {
;     ...
;             PG8_LDB(B0, 0, 0); PG8_LDB(B1, 0, 1); PG8_SCHED; PG8_LDA(At, 0, 0); PG8_STAGE(PG8_SA(1, 1), a1 + hstep, voffA);
;             PG8_WAIT_V(8); PG8_WAIT_L(0); PG8_BAR; PG8_MMA(0, 0, At, B0); PG8_MMA(0, 1, At, B1); PG8_BAR; PG8_SCHED;
;             PG8_LDA(At, 0, 1); PG8_STAGE(PG8_SB(0, 0), b2, voffB); PG8_STAGE(PG8_SB(0, 1), b2 + hstep, voffB); PG8_STAGE(PG8_SA(0, 0), a2, voffA);
;             PG8_WAIT_V(8); PG8_WAIT_L(0); PG8_BAR; PG8_MMA(1, 0, At, B0); PG8_MMA(1, 1, At, B1); PG8_BAR; PG8_SCHED;
.Lsgo_peel:
	ds_read_b128 v[140:143], v254
	ds_read_b128 v[166:169], v254 offset:1024
	ds_read_b128 v[170:173], v254 offset:2048
	ds_read_b128 v[174:177], v254 offset:3072
	ds_read_b128 v[178:181], v254 offset:16384
	ds_read_b128 v[182:185], v254 offset:17408
	ds_read_b128 v[186:189], v254 offset:18432
	ds_read_b128 v[210:213], v254 offset:19456
	s_add_u32 s2, s0, 0xfffc0080
	s_addc_u32 s3, s1, -1
	s_cmp_eq_u32 s55, 12
	s_cselect_b32 s5, s23, s3
	s_cselect_b32 s4, s51, s2
	s_cselect_b32 s3, s21, s54
	s_cselect_b32 s2, s52, s53
	s_add_i32 m0, s31, 0xc000
	ds_read_b128 v[214:217], v163
	ds_read_b128 v[218:221], v163 offset:1024
	ds_read_b128 v[222:225], v163 offset:2048
	ds_read_b128 v[226:229], v163 offset:3072
	ds_read_b128 v[230:233], v163 offset:4096
	ds_read_b128 v[234:237], v163 offset:5120
	ds_read_b128 v[238:241], v163 offset:6144
	ds_read_b128 v[242:245], v163 offset:7168
	global_load_lds_dwordx4 v136, s[0:1]
	s_add_i32 m0, s31, 0xe000
	s_nop 0
	global_load_lds_dwordx4 v138, s[0:1]
	s_waitcnt vmcnt(8)
	s_waitcnt lgkmcnt(0)
	s_barrier
	s_setprio 1
	v_mfma_f32_16x16x32_bf16 v[124:127], v[140:143], v[214:217], 0
	v_mfma_f32_16x16x32_bf16 v[120:123], v[170:173], v[214:217], 0
	v_mfma_f32_16x16x32_bf16 v[108:111], v[140:143], v[222:225], 0
	v_mfma_f32_16x16x32_bf16 v[104:107], v[170:173], v[222:225], 0
	v_mfma_f32_16x16x32_bf16 v[92:95], v[140:143], v[230:233], 0
	v_mfma_f32_16x16x32_bf16 v[88:91], v[170:173], v[230:233], 0
	v_mfma_f32_16x16x32_bf16 v[76:79], v[140:143], v[238:241], 0
	v_mfma_f32_16x16x32_bf16 v[72:75], v[170:173], v[238:241], 0
	v_mfma_f32_16x16x32_bf16 v[124:127], v[166:169], v[218:221], v[124:127]
	v_mfma_f32_16x16x32_bf16 v[120:123], v[174:177], v[218:221], v[120:123]
	v_mfma_f32_16x16x32_bf16 v[108:111], v[166:169], v[226:229], v[108:111]
	v_mfma_f32_16x16x32_bf16 v[104:107], v[174:177], v[226:229], v[104:107]
	v_mfma_f32_16x16x32_bf16 v[92:95], v[166:169], v[234:237], v[92:95]
	v_mfma_f32_16x16x32_bf16 v[88:91], v[174:177], v[234:237], v[88:91]
	v_mfma_f32_16x16x32_bf16 v[76:79], v[166:169], v[242:245], v[76:79]
	v_mfma_f32_16x16x32_bf16 v[72:75], v[174:177], v[242:245], v[72:75]
	v_mfma_f32_16x16x32_bf16 v[116:119], v[178:181], v[214:217], 0
	v_mfma_f32_16x16x32_bf16 v[112:115], v[186:189], v[214:217], 0
	v_mfma_f32_16x16x32_bf16 v[100:103], v[178:181], v[222:225], 0
	v_mfma_f32_16x16x32_bf16 v[96:99], v[186:189], v[222:225], 0
	v_mfma_f32_16x16x32_bf16 v[84:87], v[178:181], v[230:233], 0
	v_mfma_f32_16x16x32_bf16 v[80:83], v[186:189], v[230:233], 0
	v_mfma_f32_16x16x32_bf16 v[68:71], v[178:181], v[238:241], 0
	v_mfma_f32_16x16x32_bf16 v[64:67], v[186:189], v[238:241], 0
	v_mfma_f32_16x16x32_bf16 v[116:119], v[182:185], v[218:221], v[116:119]
	v_mfma_f32_16x16x32_bf16 v[112:115], v[210:213], v[218:221], v[112:115]
	v_mfma_f32_16x16x32_bf16 v[100:103], v[182:185], v[226:229], v[100:103]
	v_mfma_f32_16x16x32_bf16 v[96:99], v[210:213], v[226:229], v[96:99]
	v_mfma_f32_16x16x32_bf16 v[84:87], v[182:185], v[234:237], v[84:87]
	v_mfma_f32_16x16x32_bf16 v[80:83], v[210:213], v[234:237], v[80:83]
	v_mfma_f32_16x16x32_bf16 v[68:71], v[182:185], v[242:245], v[68:71]
	v_mfma_f32_16x16x32_bf16 v[64:67], v[210:213], v[242:245], v[64:67]
	s_setprio 0
	s_barrier
	s_mov_b32 m0, s33
	s_add_u32 s56, s2, 0x40000
	s_addc_u32 s57, s3, 0
	ds_read_b128 v[214:217], v163 offset:16384
	ds_read_b128 v[218:221], v163 offset:17408
	ds_read_b128 v[222:225], v163 offset:18432
	ds_read_b128 v[226:229], v163 offset:19456
	ds_read_b128 v[230:233], v163 offset:20480
	ds_read_b128 v[234:237], v163 offset:21504
	ds_read_b128 v[238:241], v163 offset:22528
	ds_read_b128 v[242:245], v163 offset:23552
	global_load_lds_dwordx4 v132, s[2:3]
	s_mov_b32 m0, s34
	s_nop 0
	global_load_lds_dwordx4 v128, s[2:3]
	s_mov_b32 m0, s35
	s_nop 0
	global_load_lds_dwordx4 v132, s[56:57]
	s_mov_b32 m0, s36
	s_nop 0
	global_load_lds_dwordx4 v128, s[56:57]
	s_mov_b32 m0, s31
	s_nop 0
	global_load_lds_dwordx4 v134, s[4:5]
	s_mov_b32 m0, s37
	s_nop 0
	global_load_lds_dwordx4 v130, s[4:5]
	s_waitcnt vmcnt(8)
	s_waitcnt lgkmcnt(0)
	s_barrier
	s_setprio 1
	v_mfma_f32_16x16x32_bf16 v[60:63], v[140:143], v[214:217], 0
	v_mfma_f32_16x16x32_bf16 v[56:59], v[170:173], v[214:217], 0
	v_mfma_f32_16x16x32_bf16 v[44:47], v[140:143], v[222:225], 0
	v_mfma_f32_16x16x32_bf16 v[40:43], v[170:173], v[222:225], 0
	v_mfma_f32_16x16x32_bf16 v[28:31], v[140:143], v[230:233], 0
	v_mfma_f32_16x16x32_bf16 v[24:27], v[170:173], v[230:233], 0
	v_mfma_f32_16x16x32_bf16 v[12:15], v[140:143], v[238:241], 0
	v_mfma_f32_16x16x32_bf16 v[8:11], v[170:173], v[238:241], 0
	v_mfma_f32_16x16x32_bf16 v[60:63], v[166:169], v[218:221], v[60:63]
	v_mfma_f32_16x16x32_bf16 v[56:59], v[174:177], v[218:221], v[56:59]
	v_mfma_f32_16x16x32_bf16 v[44:47], v[166:169], v[226:229], v[44:47]
	v_mfma_f32_16x16x32_bf16 v[40:43], v[174:177], v[226:229], v[40:43]
	v_mfma_f32_16x16x32_bf16 v[28:31], v[166:169], v[234:237], v[28:31]
	v_mfma_f32_16x16x32_bf16 v[24:27], v[174:177], v[234:237], v[24:27]
	v_mfma_f32_16x16x32_bf16 v[12:15], v[166:169], v[242:245], v[12:15]
	v_mfma_f32_16x16x32_bf16 v[8:11], v[174:177], v[242:245], v[8:11]
	v_mfma_f32_16x16x32_bf16 v[52:55], v[178:181], v[214:217], 0
	v_mfma_f32_16x16x32_bf16 v[48:51], v[186:189], v[214:217], 0
	v_mfma_f32_16x16x32_bf16 v[36:39], v[178:181], v[222:225], 0
	v_mfma_f32_16x16x32_bf16 v[32:35], v[186:189], v[222:225], 0
	v_mfma_f32_16x16x32_bf16 v[20:23], v[178:181], v[230:233], 0
	v_mfma_f32_16x16x32_bf16 v[16:19], v[186:189], v[230:233], 0
	v_mfma_f32_16x16x32_bf16 v[4:7], v[178:181], v[238:241], 0
	v_mfma_f32_16x16x32_bf16 v[0:3], v[186:189], v[238:241], 0
	v_mfma_f32_16x16x32_bf16 v[52:55], v[182:185], v[218:221], v[52:55]
	v_mfma_f32_16x16x32_bf16 v[48:51], v[210:213], v[218:221], v[48:51]
	v_mfma_f32_16x16x32_bf16 v[36:39], v[182:185], v[226:229], v[36:39]
	v_mfma_f32_16x16x32_bf16 v[32:35], v[210:213], v[226:229], v[32:35]
	v_mfma_f32_16x16x32_bf16 v[20:23], v[182:185], v[234:237], v[20:23]
	v_mfma_f32_16x16x32_bf16 v[16:19], v[210:213], v[234:237], v[16:19]
	v_mfma_f32_16x16x32_bf16 v[4:7], v[182:185], v[242:245], v[4:7]
	v_mfma_f32_16x16x32_bf16 v[0:3], v[210:213], v[242:245], v[0:3]
	s_setprio 0
	s_barrier
; #define PG8_STAGE(bufoff, gbase, voff) do { _Pragma("unroll") for (int _i = 0; _i < 2; ++_i) \
;         __builtin_amdgcn_global_load_lds((const unsigned*)((const char*)(gbase) + (voff)[_i]), (PG8_LAS unsigned*)(lds + (bufoff) + ldsw + _i * 8192), 16, 0, 0); } while (0)
; #define PG8_LDA(dst, b, h) do { _Pragma("unroll") for (int m = 0; m < 4; ++m) _Pragma("unroll") for (int k = 0; k < 2; ++k) dst[m][k] = *(const PG8_LAS bf16x8*)(lds + PG8_SA(b, h) + aoff + m * 2048 + k * 1024); } while (0)
; #define PG8_LDB(dst, b, h) do { _Pragma("unroll") for (int n = 0; n < 2; ++n) _Pragma("unroll") for (int k = 0; k < 2; ++k) dst[n][k] = *(const PG8_LAS bf16x8*)(lds + PG8_SB(b, h) + boff + n * 2048 + k * 1024); } while (0)
; #define PG8_MMA(ai, bj, At, Bt) do { __builtin_amdgcn_s_setprio(1); _Pragma("unroll") for (int m = 0; m < 4; ++m) _Pragma("unroll") for (int n = 0; n < 2; ++n) _Pragma("unroll") for (int k = 0; k < 2; ++k) \
;         acc[ai][bj][m][n] = __builtin_amdgcn_mfma_f32_16x16x32_bf16(Bt[n][k], At[m][k], acc[ai][bj][m][n], 0, 0, 0); __builtin_amdgcn_s_setprio(0); } while (0)
; #define PG8_WAIT_V(n) asm volatile("s_waitcnt vmcnt(" #n ")" ::: "memory")
; #define PG8_WAIT_L(n) asm volatile("s_waitcnt lgkmcnt(" #n ")" ::: "memory")
; #define PG8_BAR __builtin_amdgcn_s_barrier()
; #define PG8_SCHED __builtin_amdgcn_sched_barrier(0)
; template <class Epi, class Sched, bool ALIGN_EPI = false, bool SP2 = false>
; __device__ __forceinline__ void gemm_phase(PG8_LAS unsigned char* lds, const Gemm g, const Sched& S, const Epi& E) {
;     ...
;             PG8_LDB(B0, 1, 0); PG8_LDB(B1, 1, 1); PG8_SCHED; PG8_LDA(At, 1, 0); PG8_STAGE(PG8_SA(0, 1), a2 + hstep, voffA);
;             PG8_WAIT_V(8); PG8_WAIT_L(0); PG8_BAR; PG8_MMA(0, 0, At, B0); PG8_MMA(0, 1, At, B1); PG8_BAR; PG8_SCHED;
;             PG8_LDA(At, 1, 1); PG8_STAGE(PG8_SB(1, 0), b3, voffB); PG8_STAGE(PG8_SB(1, 1), b3 + hstep, voffB); PG8_STAGE(PG8_SA(1, 0), a3, voffA);
;             PG8_WAIT_V(8); PG8_WAIT_L(0); PG8_BAR; PG8_MMA(1, 0, At, B0); PG8_MMA(1, 1, At, B1); PG8_BAR; PG8_SCHED;
	ds_read_b128 v[140:143], v254 offset:32768
	ds_read_b128 v[166:169], v254 offset:33792
	ds_read_b128 v[170:173], v254 offset:34816
	ds_read_b128 v[174:177], v254 offset:35840
	ds_read_b128 v[178:181], v254 offset:49152
	ds_read_b128 v[182:185], v254 offset:50176
	ds_read_b128 v[186:189], v254 offset:51200
	ds_read_b128 v[210:213], v254 offset:52224
	s_add_u32 s4, s4, 0x40000
	s_addc_u32 s5, s5, 0
	s_mov_b32 m0, s38
	ds_read_b128 v[214:217], v163 offset:32768
	ds_read_b128 v[218:221], v163 offset:33792
	ds_read_b128 v[222:225], v163 offset:34816
	ds_read_b128 v[226:229], v163 offset:35840
	ds_read_b128 v[230:233], v163 offset:36864
	ds_read_b128 v[234:237], v163 offset:37888
	ds_read_b128 v[238:241], v163 offset:38912
	ds_read_b128 v[242:245], v163 offset:39936
	global_load_lds_dwordx4 v134, s[4:5]
	s_mov_b32 m0, s39
	s_nop 0
	global_load_lds_dwordx4 v130, s[4:5]
	s_waitcnt vmcnt(8)
	s_waitcnt lgkmcnt(0)
	s_barrier
	s_setprio 1
	v_mfma_f32_16x16x32_bf16 v[124:127], v[140:143], v[214:217], v[124:127]
	v_mfma_f32_16x16x32_bf16 v[120:123], v[170:173], v[214:217], v[120:123]
	v_mfma_f32_16x16x32_bf16 v[108:111], v[140:143], v[222:225], v[108:111]
	v_mfma_f32_16x16x32_bf16 v[104:107], v[170:173], v[222:225], v[104:107]
	v_mfma_f32_16x16x32_bf16 v[92:95], v[140:143], v[230:233], v[92:95]
	v_mfma_f32_16x16x32_bf16 v[88:91], v[170:173], v[230:233], v[88:91]
	v_mfma_f32_16x16x32_bf16 v[76:79], v[140:143], v[238:241], v[76:79]
	v_mfma_f32_16x16x32_bf16 v[72:75], v[170:173], v[238:241], v[72:75]
	v_mfma_f32_16x16x32_bf16 v[124:127], v[166:169], v[218:221], v[124:127]
	v_mfma_f32_16x16x32_bf16 v[120:123], v[174:177], v[218:221], v[120:123]
	v_mfma_f32_16x16x32_bf16 v[108:111], v[166:169], v[226:229], v[108:111]
	v_mfma_f32_16x16x32_bf16 v[104:107], v[174:177], v[226:229], v[104:107]
	v_mfma_f32_16x16x32_bf16 v[92:95], v[166:169], v[234:237], v[92:95]
	v_mfma_f32_16x16x32_bf16 v[88:91], v[174:177], v[234:237], v[88:91]
	v_mfma_f32_16x16x32_bf16 v[76:79], v[166:169], v[242:245], v[76:79]
	v_mfma_f32_16x16x32_bf16 v[72:75], v[174:177], v[242:245], v[72:75]
	v_mfma_f32_16x16x32_bf16 v[116:119], v[178:181], v[214:217], v[116:119]
	v_mfma_f32_16x16x32_bf16 v[112:115], v[186:189], v[214:217], v[112:115]
	v_mfma_f32_16x16x32_bf16 v[100:103], v[178:181], v[222:225], v[100:103]
	v_mfma_f32_16x16x32_bf16 v[96:99], v[186:189], v[222:225], v[96:99]
	v_mfma_f32_16x16x32_bf16 v[84:87], v[178:181], v[230:233], v[84:87]
	v_mfma_f32_16x16x32_bf16 v[80:83], v[186:189], v[230:233], v[80:83]
	v_mfma_f32_16x16x32_bf16 v[68:71], v[178:181], v[238:241], v[68:71]
	v_mfma_f32_16x16x32_bf16 v[64:67], v[186:189], v[238:241], v[64:67]
	v_mfma_f32_16x16x32_bf16 v[116:119], v[182:185], v[218:221], v[116:119]
	v_mfma_f32_16x16x32_bf16 v[112:115], v[210:213], v[218:221], v[112:115]
	v_mfma_f32_16x16x32_bf16 v[100:103], v[182:185], v[226:229], v[100:103]
	v_mfma_f32_16x16x32_bf16 v[96:99], v[210:213], v[226:229], v[96:99]
	v_mfma_f32_16x16x32_bf16 v[84:87], v[182:185], v[234:237], v[84:87]
	v_mfma_f32_16x16x32_bf16 v[80:83], v[210:213], v[234:237], v[80:83]
	v_mfma_f32_16x16x32_bf16 v[68:71], v[182:185], v[242:245], v[68:71]
	v_mfma_f32_16x16x32_bf16 v[64:67], v[210:213], v[242:245], v[64:67]
	s_setprio 0
	s_barrier
	s_mov_b32 m0, s43
	s_add_u32 s2, s2, 0x40080
	s_addc_u32 s3, s3, 0
	ds_read_b128 v[214:217], v163 offset:49152
	ds_read_b128 v[218:221], v163 offset:50176
	ds_read_b128 v[222:225], v163 offset:51200
	ds_read_b128 v[226:229], v163 offset:52224
	ds_read_b128 v[230:233], v163 offset:53248
	ds_read_b128 v[234:237], v163 offset:54272
	ds_read_b128 v[238:241], v163 offset:55296
	ds_read_b128 v[242:245], v163 offset:56320
	s_add_u32 s98, s2, 0xfffc0000
	s_addc_u32 s99, s3, -1
	global_load_lds_dwordx4 v132, s[98:99]
	s_mov_b32 m0, s44
	s_nop 0
	global_load_lds_dwordx4 v128, s[98:99]
	s_mov_b32 m0, s48
	s_nop 0
	global_load_lds_dwordx4 v132, s[2:3]
	s_mov_b32 m0, s49
	s_nop 0
	global_load_lds_dwordx4 v128, s[2:3]
	s_mov_b32 m0, s45
	s_nop 0
	s_add_u32 s100, s4, 0xfffc0080
	s_addc_u32 s101, s5, -1
	global_load_lds_dwordx4 v134, s[100:101]
	s_mov_b32 m0, s47
	s_nop 0
	global_load_lds_dwordx4 v130, s[100:101]
	s_waitcnt vmcnt(8)
	s_waitcnt lgkmcnt(0)
	s_barrier
	s_setprio 1
	v_mfma_f32_16x16x32_bf16 v[60:63], v[140:143], v[214:217], v[60:63]
	v_mfma_f32_16x16x32_bf16 v[56:59], v[170:173], v[214:217], v[56:59]
	v_mfma_f32_16x16x32_bf16 v[44:47], v[140:143], v[222:225], v[44:47]
	v_mfma_f32_16x16x32_bf16 v[40:43], v[170:173], v[222:225], v[40:43]
	v_mfma_f32_16x16x32_bf16 v[28:31], v[140:143], v[230:233], v[28:31]
	v_mfma_f32_16x16x32_bf16 v[24:27], v[170:173], v[230:233], v[24:27]
	v_mfma_f32_16x16x32_bf16 v[12:15], v[140:143], v[238:241], v[12:15]
	v_mfma_f32_16x16x32_bf16 v[8:11], v[170:173], v[238:241], v[8:11]
	v_mfma_f32_16x16x32_bf16 v[60:63], v[166:169], v[218:221], v[60:63]
	v_mfma_f32_16x16x32_bf16 v[56:59], v[174:177], v[218:221], v[56:59]
	v_mfma_f32_16x16x32_bf16 v[44:47], v[166:169], v[226:229], v[44:47]
	v_mfma_f32_16x16x32_bf16 v[40:43], v[174:177], v[226:229], v[40:43]
	v_mfma_f32_16x16x32_bf16 v[28:31], v[166:169], v[234:237], v[28:31]
	v_mfma_f32_16x16x32_bf16 v[24:27], v[174:177], v[234:237], v[24:27]
	v_mfma_f32_16x16x32_bf16 v[12:15], v[166:169], v[242:245], v[12:15]
	v_mfma_f32_16x16x32_bf16 v[8:11], v[174:177], v[242:245], v[8:11]
	v_mfma_f32_16x16x32_bf16 v[52:55], v[178:181], v[214:217], v[52:55]
	v_mfma_f32_16x16x32_bf16 v[48:51], v[186:189], v[214:217], v[48:51]
	v_mfma_f32_16x16x32_bf16 v[36:39], v[178:181], v[222:225], v[36:39]
	v_mfma_f32_16x16x32_bf16 v[32:35], v[186:189], v[222:225], v[32:35]
	v_mfma_f32_16x16x32_bf16 v[20:23], v[178:181], v[230:233], v[20:23]
	v_mfma_f32_16x16x32_bf16 v[16:19], v[186:189], v[230:233], v[16:19]
	v_mfma_f32_16x16x32_bf16 v[4:7], v[178:181], v[238:241], v[4:7]
	v_mfma_f32_16x16x32_bf16 v[0:3], v[186:189], v[238:241], v[0:3]
	v_mfma_f32_16x16x32_bf16 v[52:55], v[182:185], v[218:221], v[52:55]
	v_mfma_f32_16x16x32_bf16 v[48:51], v[210:213], v[218:221], v[48:51]
	v_mfma_f32_16x16x32_bf16 v[36:39], v[182:185], v[226:229], v[36:39]
	v_mfma_f32_16x16x32_bf16 v[32:35], v[210:213], v[226:229], v[32:35]
	v_mfma_f32_16x16x32_bf16 v[20:23], v[182:185], v[234:237], v[20:23]
	v_mfma_f32_16x16x32_bf16 v[16:19], v[210:213], v[234:237], v[16:19]
	v_mfma_f32_16x16x32_bf16 v[4:7], v[182:185], v[242:245], v[4:7]
	v_mfma_f32_16x16x32_bf16 v[0:3], v[210:213], v[242:245], v[0:3]
	s_setprio 0
	s_barrier
	s_add_i32 s55, s55, 2
	s_add_u32 s0, s0, 0x100
	s_addc_u32 s1, s1, 0
	s_add_u32 s53, s53, 0x100
	s_addc_u32 s54, s54, 0
	s_cmp_gt_u32 s55, 13
; #define PG8_STAGE(bufoff, gbase, voff) do { _Pragma("unroll") for (int _i = 0; _i < 2; ++_i) \
;         __builtin_amdgcn_global_load_lds((const unsigned*)((const char*)(gbase) + (voff)[_i]), (PG8_LAS unsigned*)(lds + (bufoff) + ldsw + _i * 8192), 16, 0, 0); } while (0)
; #define PG8_LDA(dst, b, h) do { _Pragma("unroll") for (int m = 0; m < 4; ++m) _Pragma("unroll") for (int k = 0; k < 2; ++k) dst[m][k] = *(const PG8_LAS bf16x8*)(lds + PG8_SA(b, h) + aoff + m * 2048 + k * 1024); } while (0)
; #define PG8_LDB(dst, b, h) do { _Pragma("unroll") for (int n = 0; n < 2; ++n) _Pragma("unroll") for (int k = 0; k < 2; ++k) dst[n][k] = *(const PG8_LAS bf16x8*)(lds + PG8_SB(b, h) + boff + n * 2048 + k * 1024); } while (0)
; #define PG8_MMA(ai, bj, At, Bt) do { __builtin_amdgcn_s_setprio(1); _Pragma("unroll") for (int m = 0; m < 4; ++m) _Pragma("unroll") for (int n = 0; n < 2; ++n) _Pragma("unroll") for (int k = 0; k < 2; ++k) \
;         acc[ai][bj][m][n] = __builtin_amdgcn_mfma_f32_16x16x32_bf16(Bt[n][k], At[m][k], acc[ai][bj][m][n], 0, 0, 0); __builtin_amdgcn_s_setprio(0); } while (0)
; #define PG8_WAIT_V(n) asm volatile("s_waitcnt vmcnt(" #n ")" ::: "memory")
; #define PG8_WAIT_L(n) asm volatile("s_waitcnt lgkmcnt(" #n ")" ::: "memory")
; #define PG8_BAR __builtin_amdgcn_s_barrier()
; #define PG8_SCHED __builtin_amdgcn_sched_barrier(0)
; template <class Epi, class Sched, bool ALIGN_EPI = false, bool SP2 = false>
; __device__ __forceinline__ void gemm_phase(PG8_LAS unsigned char* lds, const Gemm g, const Sched& S, const Epi& E) {
;     ...
;             PG8_LDB(B0, 0, 0); PG8_LDB(B1, 0, 1); PG8_SCHED; PG8_LDA(At, 0, 0); PG8_STAGE(PG8_SA(1, 1), a1 + hstep, voffA);
;             PG8_WAIT_V(8); PG8_WAIT_L(0); PG8_BAR; PG8_MMA(0, 0, At, B0); PG8_MMA(0, 1, At, B1); PG8_BAR; PG8_SCHED;
;             PG8_LDA(At, 0, 1); PG8_STAGE(PG8_SB(0, 0), b2, voffB); PG8_STAGE(PG8_SB(0, 1), b2 + hstep, voffB); PG8_STAGE(PG8_SA(0, 0), a2, voffA);
;             PG8_WAIT_V(8); PG8_WAIT_L(0); PG8_BAR; PG8_MMA(1, 0, At, B0); PG8_MMA(1, 1, At, B1); PG8_BAR; PG8_SCHED;
.LBB0_1042:
	ds_read_b128 v[140:143], v254
	ds_read_b128 v[166:169], v254 offset:1024
	ds_read_b128 v[170:173], v254 offset:2048
	ds_read_b128 v[174:177], v254 offset:3072
	ds_read_b128 v[178:181], v254 offset:16384
	ds_read_b128 v[182:185], v254 offset:17408
	ds_read_b128 v[186:189], v254 offset:18432
	ds_read_b128 v[210:213], v254 offset:19456
	s_add_u32 s2, s0, 0xfffc0080
	s_addc_u32 s3, s1, -1
	s_cmp_eq_u32 s55, 12
	s_cselect_b32 s5, s23, s3
	s_cselect_b32 s4, s51, s2
	s_cselect_b32 s3, s21, s54
	s_cselect_b32 s2, s52, s53
	s_add_i32 m0, s31, 0xc000
	ds_read_b128 v[214:217], v163
	ds_read_b128 v[218:221], v163 offset:1024
	ds_read_b128 v[222:225], v163 offset:2048
	ds_read_b128 v[226:229], v163 offset:3072
	ds_read_b128 v[230:233], v163 offset:4096
	ds_read_b128 v[234:237], v163 offset:5120
	ds_read_b128 v[238:241], v163 offset:6144
	ds_read_b128 v[242:245], v163 offset:7168
	global_load_lds_dwordx4 v136, s[0:1]
	s_add_i32 m0, s31, 0xe000
	s_nop 0
	global_load_lds_dwordx4 v138, s[0:1]
	s_waitcnt vmcnt(8)
	s_waitcnt lgkmcnt(0)
	s_barrier
	s_setprio 1
	v_mfma_f32_16x16x32_bf16 v[124:127], v[140:143], v[214:217], v[124:127]
	v_mfma_f32_16x16x32_bf16 v[120:123], v[170:173], v[214:217], v[120:123]
	v_mfma_f32_16x16x32_bf16 v[108:111], v[140:143], v[222:225], v[108:111]
	v_mfma_f32_16x16x32_bf16 v[104:107], v[170:173], v[222:225], v[104:107]
	v_mfma_f32_16x16x32_bf16 v[92:95], v[140:143], v[230:233], v[92:95]
	v_mfma_f32_16x16x32_bf16 v[88:91], v[170:173], v[230:233], v[88:91]
	v_mfma_f32_16x16x32_bf16 v[76:79], v[140:143], v[238:241], v[76:79]
	v_mfma_f32_16x16x32_bf16 v[72:75], v[170:173], v[238:241], v[72:75]
	v_mfma_f32_16x16x32_bf16 v[124:127], v[166:169], v[218:221], v[124:127]
	v_mfma_f32_16x16x32_bf16 v[120:123], v[174:177], v[218:221], v[120:123]
	v_mfma_f32_16x16x32_bf16 v[108:111], v[166:169], v[226:229], v[108:111]
	v_mfma_f32_16x16x32_bf16 v[104:107], v[174:177], v[226:229], v[104:107]
	v_mfma_f32_16x16x32_bf16 v[92:95], v[166:169], v[234:237], v[92:95]
	v_mfma_f32_16x16x32_bf16 v[88:91], v[174:177], v[234:237], v[88:91]
	v_mfma_f32_16x16x32_bf16 v[76:79], v[166:169], v[242:245], v[76:79]
	v_mfma_f32_16x16x32_bf16 v[72:75], v[174:177], v[242:245], v[72:75]
	v_mfma_f32_16x16x32_bf16 v[116:119], v[178:181], v[214:217], v[116:119]
	v_mfma_f32_16x16x32_bf16 v[112:115], v[186:189], v[214:217], v[112:115]
	v_mfma_f32_16x16x32_bf16 v[100:103], v[178:181], v[222:225], v[100:103]
	v_mfma_f32_16x16x32_bf16 v[96:99], v[186:189], v[222:225], v[96:99]
	v_mfma_f32_16x16x32_bf16 v[84:87], v[178:181], v[230:233], v[84:87]
	v_mfma_f32_16x16x32_bf16 v[80:83], v[186:189], v[230:233], v[80:83]
	v_mfma_f32_16x16x32_bf16 v[68:71], v[178:181], v[238:241], v[68:71]
	v_mfma_f32_16x16x32_bf16 v[64:67], v[186:189], v[238:241], v[64:67]
	v_mfma_f32_16x16x32_bf16 v[116:119], v[182:185], v[218:221], v[116:119]
	v_mfma_f32_16x16x32_bf16 v[112:115], v[210:213], v[218:221], v[112:115]
	v_mfma_f32_16x16x32_bf16 v[100:103], v[182:185], v[226:229], v[100:103]
	v_mfma_f32_16x16x32_bf16 v[96:99], v[210:213], v[226:229], v[96:99]
	v_mfma_f32_16x16x32_bf16 v[84:87], v[182:185], v[234:237], v[84:87]
	v_mfma_f32_16x16x32_bf16 v[80:83], v[210:213], v[234:237], v[80:83]
	v_mfma_f32_16x16x32_bf16 v[68:71], v[182:185], v[242:245], v[68:71]
	v_mfma_f32_16x16x32_bf16 v[64:67], v[210:213], v[242:245], v[64:67]
	s_setprio 0
	s_barrier
	s_mov_b32 m0, s33
	s_add_u32 s56, s2, 0x40000
	s_addc_u32 s57, s3, 0
	ds_read_b128 v[214:217], v163 offset:16384
	ds_read_b128 v[218:221], v163 offset:17408
	ds_read_b128 v[222:225], v163 offset:18432
	ds_read_b128 v[226:229], v163 offset:19456
	ds_read_b128 v[230:233], v163 offset:20480
	ds_read_b128 v[234:237], v163 offset:21504
	ds_read_b128 v[238:241], v163 offset:22528
	ds_read_b128 v[242:245], v163 offset:23552
	global_load_lds_dwordx4 v132, s[2:3]
	s_mov_b32 m0, s34
	s_nop 0
	global_load_lds_dwordx4 v128, s[2:3]
	s_mov_b32 m0, s35
	s_nop 0
	global_load_lds_dwordx4 v132, s[56:57]
	s_mov_b32 m0, s36
	s_nop 0
	global_load_lds_dwordx4 v128, s[56:57]
	s_mov_b32 m0, s31
	s_nop 0
	global_load_lds_dwordx4 v134, s[4:5]
	s_mov_b32 m0, s37
	s_nop 0
	global_load_lds_dwordx4 v130, s[4:5]
	s_waitcnt vmcnt(8)
	s_waitcnt lgkmcnt(0)
	s_barrier
	s_setprio 1
	v_mfma_f32_16x16x32_bf16 v[60:63], v[140:143], v[214:217], v[60:63]
	v_mfma_f32_16x16x32_bf16 v[56:59], v[170:173], v[214:217], v[56:59]
	v_mfma_f32_16x16x32_bf16 v[44:47], v[140:143], v[222:225], v[44:47]
	v_mfma_f32_16x16x32_bf16 v[40:43], v[170:173], v[222:225], v[40:43]
	v_mfma_f32_16x16x32_bf16 v[28:31], v[140:143], v[230:233], v[28:31]
	v_mfma_f32_16x16x32_bf16 v[24:27], v[170:173], v[230:233], v[24:27]
	v_mfma_f32_16x16x32_bf16 v[12:15], v[140:143], v[238:241], v[12:15]
	v_mfma_f32_16x16x32_bf16 v[8:11], v[170:173], v[238:241], v[8:11]
	v_mfma_f32_16x16x32_bf16 v[60:63], v[166:169], v[218:221], v[60:63]
	v_mfma_f32_16x16x32_bf16 v[56:59], v[174:177], v[218:221], v[56:59]
	v_mfma_f32_16x16x32_bf16 v[44:47], v[166:169], v[226:229], v[44:47]
	v_mfma_f32_16x16x32_bf16 v[40:43], v[174:177], v[226:229], v[40:43]
	v_mfma_f32_16x16x32_bf16 v[28:31], v[166:169], v[234:237], v[28:31]
	v_mfma_f32_16x16x32_bf16 v[24:27], v[174:177], v[234:237], v[24:27]
	v_mfma_f32_16x16x32_bf16 v[12:15], v[166:169], v[242:245], v[12:15]
	v_mfma_f32_16x16x32_bf16 v[8:11], v[174:177], v[242:245], v[8:11]
	v_mfma_f32_16x16x32_bf16 v[52:55], v[178:181], v[214:217], v[52:55]
	v_mfma_f32_16x16x32_bf16 v[48:51], v[186:189], v[214:217], v[48:51]
	v_mfma_f32_16x16x32_bf16 v[36:39], v[178:181], v[222:225], v[36:39]
	v_mfma_f32_16x16x32_bf16 v[32:35], v[186:189], v[222:225], v[32:35]
	v_mfma_f32_16x16x32_bf16 v[20:23], v[178:181], v[230:233], v[20:23]
	v_mfma_f32_16x16x32_bf16 v[16:19], v[186:189], v[230:233], v[16:19]
	v_mfma_f32_16x16x32_bf16 v[4:7], v[178:181], v[238:241], v[4:7]
	v_mfma_f32_16x16x32_bf16 v[0:3], v[186:189], v[238:241], v[0:3]
	v_mfma_f32_16x16x32_bf16 v[52:55], v[182:185], v[218:221], v[52:55]
	v_mfma_f32_16x16x32_bf16 v[48:51], v[210:213], v[218:221], v[48:51]
	v_mfma_f32_16x16x32_bf16 v[36:39], v[182:185], v[226:229], v[36:39]
	v_mfma_f32_16x16x32_bf16 v[32:35], v[210:213], v[226:229], v[32:35]
	v_mfma_f32_16x16x32_bf16 v[20:23], v[182:185], v[234:237], v[20:23]
	v_mfma_f32_16x16x32_bf16 v[16:19], v[210:213], v[234:237], v[16:19]
	v_mfma_f32_16x16x32_bf16 v[4:7], v[182:185], v[242:245], v[4:7]
	v_mfma_f32_16x16x32_bf16 v[0:3], v[210:213], v[242:245], v[0:3]
	s_setprio 0
	s_barrier
; #define PG8_STAGE(bufoff, gbase, voff) do { _Pragma("unroll") for (int _i = 0; _i < 2; ++_i) \
;         __builtin_amdgcn_global_load_lds((const unsigned*)((const char*)(gbase) + (voff)[_i]), (PG8_LAS unsigned*)(lds + (bufoff) + ldsw + _i * 8192), 16, 0, 0); } while (0)
; #define PG8_LDA(dst, b, h) do { _Pragma("unroll") for (int m = 0; m < 4; ++m) _Pragma("unroll") for (int k = 0; k < 2; ++k) dst[m][k] = *(const PG8_LAS bf16x8*)(lds + PG8_SA(b, h) + aoff + m * 2048 + k * 1024); } while (0)
; #define PG8_LDB(dst, b, h) do { _Pragma("unroll") for (int n = 0; n < 2; ++n) _Pragma("unroll") for (int k = 0; k < 2; ++k) dst[n][k] = *(const PG8_LAS bf16x8*)(lds + PG8_SB(b, h) + boff + n * 2048 + k * 1024); } while (0)
; #define PG8_MMA(ai, bj, At, Bt) do { __builtin_amdgcn_s_setprio(1); _Pragma("unroll") for (int m = 0; m < 4; ++m) _Pragma("unroll") for (int n = 0; n < 2; ++n) _Pragma("unroll") for (int k = 0; k < 2; ++k) \
;         acc[ai][bj][m][n] = __builtin_amdgcn_mfma_f32_16x16x32_bf16(Bt[n][k], At[m][k], acc[ai][bj][m][n], 0, 0, 0); __builtin_amdgcn_s_setprio(0); } while (0)
; #define PG8_WAIT_V(n) asm volatile("s_waitcnt vmcnt(" #n ")" ::: "memory")
; #define PG8_WAIT_L(n) asm volatile("s_waitcnt lgkmcnt(" #n ")" ::: "memory")
; #define PG8_BAR __builtin_amdgcn_s_barrier()
; #define PG8_SCHED __builtin_amdgcn_sched_barrier(0)
; template <class Epi, class Sched, bool ALIGN_EPI = false, bool SP2 = false>
; __device__ __forceinline__ void gemm_phase(PG8_LAS unsigned char* lds, const Gemm g, const Sched& S, const Epi& E) {
;     ...
;             PG8_LDB(B0, 1, 0); PG8_LDB(B1, 1, 1); PG8_SCHED; PG8_LDA(At, 1, 0); PG8_STAGE(PG8_SA(0, 1), a2 + hstep, voffA);
;             PG8_WAIT_V(8); PG8_WAIT_L(0); PG8_BAR; PG8_MMA(0, 0, At, B0); PG8_MMA(0, 1, At, B1); PG8_BAR; PG8_SCHED;
;             PG8_LDA(At, 1, 1); PG8_STAGE(PG8_SB(1, 0), b3, voffB); PG8_STAGE(PG8_SB(1, 1), b3 + hstep, voffB); PG8_STAGE(PG8_SA(1, 0), a3, voffA);
;             PG8_WAIT_V(8); PG8_WAIT_L(0); PG8_BAR; PG8_MMA(1, 0, At, B0); PG8_MMA(1, 1, At, B1); PG8_BAR; PG8_SCHED;
;     ...
;         if constexpr (ALIGN_EPI) { if (wr == 0) PG8_BAR; }
	ds_read_b128 v[140:143], v254 offset:32768
	ds_read_b128 v[166:169], v254 offset:33792
	ds_read_b128 v[170:173], v254 offset:34816
	ds_read_b128 v[174:177], v254 offset:35840
	ds_read_b128 v[178:181], v254 offset:49152
	ds_read_b128 v[182:185], v254 offset:50176
	ds_read_b128 v[186:189], v254 offset:51200
	ds_read_b128 v[210:213], v254 offset:52224
	s_add_u32 s4, s4, 0x40000
	s_addc_u32 s5, s5, 0
	s_mov_b32 m0, s38
	ds_read_b128 v[214:217], v163 offset:32768
	ds_read_b128 v[218:221], v163 offset:33792
	ds_read_b128 v[222:225], v163 offset:34816
	ds_read_b128 v[226:229], v163 offset:35840
	ds_read_b128 v[230:233], v163 offset:36864
	ds_read_b128 v[234:237], v163 offset:37888
	ds_read_b128 v[238:241], v163 offset:38912
	ds_read_b128 v[242:245], v163 offset:39936
	global_load_lds_dwordx4 v134, s[4:5]
	s_mov_b32 m0, s39
	s_nop 0
	global_load_lds_dwordx4 v130, s[4:5]
	s_waitcnt vmcnt(8)
	s_waitcnt lgkmcnt(0)
	s_barrier
	s_setprio 1
	v_mfma_f32_16x16x32_bf16 v[124:127], v[140:143], v[214:217], v[124:127]
	v_mfma_f32_16x16x32_bf16 v[120:123], v[170:173], v[214:217], v[120:123]
	v_mfma_f32_16x16x32_bf16 v[108:111], v[140:143], v[222:225], v[108:111]
	v_mfma_f32_16x16x32_bf16 v[104:107], v[170:173], v[222:225], v[104:107]
	v_mfma_f32_16x16x32_bf16 v[92:95], v[140:143], v[230:233], v[92:95]
	v_mfma_f32_16x16x32_bf16 v[88:91], v[170:173], v[230:233], v[88:91]
	v_mfma_f32_16x16x32_bf16 v[76:79], v[140:143], v[238:241], v[76:79]
	v_mfma_f32_16x16x32_bf16 v[72:75], v[170:173], v[238:241], v[72:75]
	v_mfma_f32_16x16x32_bf16 v[124:127], v[166:169], v[218:221], v[124:127]
	v_mfma_f32_16x16x32_bf16 v[120:123], v[174:177], v[218:221], v[120:123]
	v_mfma_f32_16x16x32_bf16 v[108:111], v[166:169], v[226:229], v[108:111]
	v_mfma_f32_16x16x32_bf16 v[104:107], v[174:177], v[226:229], v[104:107]
	v_mfma_f32_16x16x32_bf16 v[92:95], v[166:169], v[234:237], v[92:95]
	v_mfma_f32_16x16x32_bf16 v[88:91], v[174:177], v[234:237], v[88:91]
	v_mfma_f32_16x16x32_bf16 v[76:79], v[166:169], v[242:245], v[76:79]
	v_mfma_f32_16x16x32_bf16 v[72:75], v[174:177], v[242:245], v[72:75]
	v_mfma_f32_16x16x32_bf16 v[116:119], v[178:181], v[214:217], v[116:119]
	v_mfma_f32_16x16x32_bf16 v[112:115], v[186:189], v[214:217], v[112:115]
	v_mfma_f32_16x16x32_bf16 v[100:103], v[178:181], v[222:225], v[100:103]
	v_mfma_f32_16x16x32_bf16 v[96:99], v[186:189], v[222:225], v[96:99]
	v_mfma_f32_16x16x32_bf16 v[84:87], v[178:181], v[230:233], v[84:87]
	v_mfma_f32_16x16x32_bf16 v[80:83], v[186:189], v[230:233], v[80:83]
	v_mfma_f32_16x16x32_bf16 v[68:71], v[178:181], v[238:241], v[68:71]
	v_mfma_f32_16x16x32_bf16 v[64:67], v[186:189], v[238:241], v[64:67]
	v_mfma_f32_16x16x32_bf16 v[116:119], v[182:185], v[218:221], v[116:119]
	v_mfma_f32_16x16x32_bf16 v[112:115], v[210:213], v[218:221], v[112:115]
	v_mfma_f32_16x16x32_bf16 v[100:103], v[182:185], v[226:229], v[100:103]
	v_mfma_f32_16x16x32_bf16 v[96:99], v[210:213], v[226:229], v[96:99]
	v_mfma_f32_16x16x32_bf16 v[84:87], v[182:185], v[234:237], v[84:87]
	v_mfma_f32_16x16x32_bf16 v[80:83], v[210:213], v[234:237], v[80:83]
	v_mfma_f32_16x16x32_bf16 v[68:71], v[182:185], v[242:245], v[68:71]
	v_mfma_f32_16x16x32_bf16 v[64:67], v[210:213], v[242:245], v[64:67]
	s_setprio 0
	s_barrier
	s_mov_b32 m0, s43
	s_add_u32 s2, s2, 0x40080
	s_addc_u32 s3, s3, 0
	ds_read_b128 v[214:217], v163 offset:49152
	ds_read_b128 v[218:221], v163 offset:50176
	ds_read_b128 v[222:225], v163 offset:51200
	ds_read_b128 v[226:229], v163 offset:52224
	ds_read_b128 v[230:233], v163 offset:53248
	ds_read_b128 v[234:237], v163 offset:54272
	ds_read_b128 v[238:241], v163 offset:55296
	ds_read_b128 v[242:245], v163 offset:56320
	s_add_u32 s98, s2, 0xfffc0000
	s_addc_u32 s99, s3, -1
	global_load_lds_dwordx4 v132, s[98:99]
	s_mov_b32 m0, s44
	s_nop 0
	global_load_lds_dwordx4 v128, s[98:99]
	s_mov_b32 m0, s48
	s_nop 0
	global_load_lds_dwordx4 v132, s[2:3]
	s_mov_b32 m0, s49
	s_nop 0
	global_load_lds_dwordx4 v128, s[2:3]
	s_mov_b32 m0, s45
	s_nop 0
	s_add_u32 s100, s4, 0xfffc0080
	s_addc_u32 s101, s5, -1
	global_load_lds_dwordx4 v134, s[100:101]
	s_mov_b32 m0, s47
	s_nop 0
	global_load_lds_dwordx4 v130, s[100:101]
	s_waitcnt vmcnt(8)
	s_waitcnt lgkmcnt(0)
	s_barrier
	s_setprio 1
	v_mfma_f32_16x16x32_bf16 v[60:63], v[140:143], v[214:217], v[60:63]
	v_mfma_f32_16x16x32_bf16 v[56:59], v[170:173], v[214:217], v[56:59]
	v_mfma_f32_16x16x32_bf16 v[44:47], v[140:143], v[222:225], v[44:47]
	v_mfma_f32_16x16x32_bf16 v[40:43], v[170:173], v[222:225], v[40:43]
	v_mfma_f32_16x16x32_bf16 v[28:31], v[140:143], v[230:233], v[28:31]
	v_mfma_f32_16x16x32_bf16 v[24:27], v[170:173], v[230:233], v[24:27]
	v_mfma_f32_16x16x32_bf16 v[12:15], v[140:143], v[238:241], v[12:15]
	v_mfma_f32_16x16x32_bf16 v[8:11], v[170:173], v[238:241], v[8:11]
	v_mfma_f32_16x16x32_bf16 v[60:63], v[166:169], v[218:221], v[60:63]
	v_mfma_f32_16x16x32_bf16 v[56:59], v[174:177], v[218:221], v[56:59]
	v_mfma_f32_16x16x32_bf16 v[44:47], v[166:169], v[226:229], v[44:47]
	v_mfma_f32_16x16x32_bf16 v[40:43], v[174:177], v[226:229], v[40:43]
	v_mfma_f32_16x16x32_bf16 v[28:31], v[166:169], v[234:237], v[28:31]
	v_mfma_f32_16x16x32_bf16 v[24:27], v[174:177], v[234:237], v[24:27]
	v_mfma_f32_16x16x32_bf16 v[12:15], v[166:169], v[242:245], v[12:15]
	v_mfma_f32_16x16x32_bf16 v[8:11], v[174:177], v[242:245], v[8:11]
	v_mfma_f32_16x16x32_bf16 v[52:55], v[178:181], v[214:217], v[52:55]
	v_mfma_f32_16x16x32_bf16 v[48:51], v[186:189], v[214:217], v[48:51]
	v_mfma_f32_16x16x32_bf16 v[36:39], v[178:181], v[222:225], v[36:39]
	v_mfma_f32_16x16x32_bf16 v[32:35], v[186:189], v[222:225], v[32:35]
	v_mfma_f32_16x16x32_bf16 v[20:23], v[178:181], v[230:233], v[20:23]
	v_mfma_f32_16x16x32_bf16 v[16:19], v[186:189], v[230:233], v[16:19]
	v_mfma_f32_16x16x32_bf16 v[4:7], v[178:181], v[238:241], v[4:7]
	v_mfma_f32_16x16x32_bf16 v[0:3], v[186:189], v[238:241], v[0:3]
	v_mfma_f32_16x16x32_bf16 v[52:55], v[182:185], v[218:221], v[52:55]
	v_mfma_f32_16x16x32_bf16 v[48:51], v[210:213], v[218:221], v[48:51]
	v_mfma_f32_16x16x32_bf16 v[36:39], v[182:185], v[226:229], v[36:39]
	v_mfma_f32_16x16x32_bf16 v[32:35], v[210:213], v[226:229], v[32:35]
	v_mfma_f32_16x16x32_bf16 v[20:23], v[182:185], v[234:237], v[20:23]
	v_mfma_f32_16x16x32_bf16 v[16:19], v[210:213], v[234:237], v[16:19]
	v_mfma_f32_16x16x32_bf16 v[4:7], v[182:185], v[242:245], v[4:7]
	v_mfma_f32_16x16x32_bf16 v[0:3], v[210:213], v[242:245], v[0:3]
	s_setprio 0
	s_barrier
	s_add_i32 s55, s55, 2
	s_add_u32 s0, s0, 0x100
	s_addc_u32 s1, s1, 0
	s_add_u32 s53, s53, 0x100
	s_addc_u32 s54, s54, 0
	s_cmp_gt_u32 s55, 13
	s_cbranch_scc0 .LBB0_1042
	s_and_b64 vcc, exec, s[18:19]
	s_cbranch_vccz .LBB0_1045
	s_barrier
